# mixer3 output epilogue: RMSNorm gain quads preloaded once per t-block (was: 8x reload + vmcnt(0) incl. previous store); natten table fill de-serialized
# baseline (speedup 1.0000x reference)
; __device__ __forceinline__ void natten_unit(const bf16* __restrict__ P, bf16* __restrict__ Y, const float* __restrict__ rpbh, long qrow0, long crow0, long wrow0, int h, int NT, bool win, int r0, int ws0, char* lds, int tid) {
;     ...
;   __syncthreads();
;   if (win) { for (int i = tid; i < 15 * NAT_TABW; i += 512) { const int dr = i >> 7, dc = (i & 127) - 48; tab[i] = (dc >= 0 && dc <= 30) ? rpbh[dr * 31 + dc] * 1.4426950408889634f : 0.f; } }
.LBB0_963:
	s_and_b32 s12, s10, 7
	v_readfirstlane_b32 s9, v209
	s_waitcnt vmcnt(63) expcnt(7) lgkmcnt(15)
	s_barrier
	s_mov_b64 s[0:1], exec
	v_readlane_b32 s2, v245, 58
	v_readlane_b32 s3, v245, 59
	s_and_b64 s[2:3], s[0:1], s[2:3]
	s_mov_b64 exec, s[2:3]
	s_cbranch_execz .LBB0_968
	s_mul_i32 s2, s12, 0x744
	s_add_u32 s2, s42, s2
	v_readlane_b32 s3, v245, 56
	s_addc_u32 s3, s3, 0
	v_mov_b32_e32 v0, v227
	v_mov_b32_e32 v1, v209
	v_mov_b32_e32 v4, 0
	v_mov_b32_e32 v5, 0
	v_mov_b32_e32 v6, 0
	v_mov_b32_e32 v7, 0
	s_movk_i32 s6, 0x180
	v_cmp_gt_i32_e32 vcc, s6, v1
	s_nop 1
	s_mov_b64 s[4:5], vcc
	s_and_saveexec_b64 s[6:7], s[44:45]
	s_cbranch_execz .Lnat_tab_w
	v_ashrrev_i32_e32 v2, 7, v1
	v_mul_lo_u32 v2, v2, 31
	v_ashrrev_i32_e32 v3, 31, v2
	v_lshl_add_u64 v[2:3], v[2:3], 0, v[150:151]
	v_lshl_add_u64 v[8:9], v[2:3], 2, s[2:3]
	global_load_dword v4, v[8:9], off offset:-192
	global_load_dword v5, v[8:9], off offset:304
	global_load_dword v6, v[8:9], off offset:800
	s_and_b64 exec, exec, s[4:5]
	global_load_dword v7, v[8:9], off offset:1296
.Lnat_tab_w:
	s_or_b64 exec, exec, s[6:7]
	s_waitcnt vmcnt(0)
	v_mul_f32_e32 v4, 0x3fb8aa3b, v4
	v_mul_f32_e32 v5, 0x3fb8aa3b, v5
	v_mul_f32_e32 v6, 0x3fb8aa3b, v6
	v_mul_f32_e32 v7, 0x3fb8aa3b, v7
	ds_write_b32 v0, v4
	ds_write_b32 v0, v5 offset:2048
	ds_write_b32 v0, v6 offset:4096
	s_and_b64 exec, exec, s[4:5]
	ds_write_b32 v0, v7 offset:6144

; #define P3_STEP2(st) do { P3_SLOAD(A1, (st) + 1); P3_SCOMP(A0, (st)); P3_SLOAD(A0, (st) + 2); P3_SCOMP(A1, (st) + 1); } while (0)
; template <int DK> __device__ __forceinline__ void scan_out_wave(const ScanBufs<DK>& S, int g, int h, const bf16* P, int gcol, const float* gain, bf16* Y, LAS unsigned char* W, int lane) {
;     ...
;         struct Raw8 { v4u x[8]; }; Raw8 A0, A1;
;         constexpr int NST = 2 * (2 + NK);
;     ...
;         P3_SLOAD(A0, 0);
;         P3_STEP2(0); P3_STEP2(2); P3_STEP2(4); P3_STEP2(6); P3_STEP2(8); P3_STEP2(10);
.LBB0_1094:
	s_mov_b64 s[0:1], s[4:5]
	s_mov_b32 s15, s59
	v_lshl_add_u64 v[12:13], s[0:1], 0, v[100:101]
	s_mov_b64 s[0:1], s[6:7]
	global_load_dwordx4 v[0:3], v[12:13], off
	global_load_dwordx4 v[4:7], v[12:13], off offset:512
	global_load_dwordx4 v[8:11], v[12:13], off offset:1024
	s_nop 0
	global_load_dwordx4 v[12:15], v[12:13], off offset:1536
	s_nop 0
	v_lshl_add_u64 v[16:17], s[0:1], 0, v[100:101]
	global_load_dwordx4 v[66:69], v[16:17], off
	global_load_dwordx4 v[70:73], v[16:17], off offset:512
	global_load_dwordx4 v[74:77], v[16:17], off offset:1024
	global_load_dwordx4 v[78:81], v[16:17], off offset:1536
	s_lshl_b32 s1, s60, 5
	s_or_b32 s14, s58, s1
	s_mul_i32 s1, s59, 0x8a00
	s_mul_hi_u32 s2, s14, 0x8a00
	s_add_i32 s1, s2, s1
	s_mul_i32 s2, s14, 0x8a00
	s_mul_i32 s0, s60, 0x2400
	s_add_u32 s2, s84, s2
	s_addc_u32 s3, s85, s1
	s_add_i32 s19, s78, s0
	s_mov_b64 s[0:1], s[8:9]
	s_nop 0
	v_lshl_add_u64 v[16:17], s[0:1], 0, v[100:101]
	s_mov_b64 s[0:1], s[10:11]
	global_load_dwordx4 v[82:85], v[16:17], off
	global_load_dwordx4 v[86:89], v[16:17], off offset:512
	global_load_dwordx4 v[90:93], v[16:17], off offset:1024
	global_load_dwordx4 v[94:97], v[16:17], off offset:1536
	s_nop 0
	v_lshl_add_u64 v[16:17], s[0:1], 0, v[100:101]
	global_load_dwordx4 v[120:123], v[16:17], off
	global_load_dwordx4 v[124:127], v[16:17], off offset:512
	global_load_dwordx4 v[128:131], v[16:17], off offset:1024
	global_load_dwordx4 v[132:135], v[16:17], off offset:1536
	v_add3_u32 v156, s19, v110, v108
	ds_read_b128 v[136:139], v156
	s_waitcnt vmcnt(15) lgkmcnt(0)
	v_mfma_f32_32x32x16_bf16 v[48:63], v[0:3], v[136:139], 0
	s_waitcnt vmcnt(14)
	v_mfma_f32_32x32x16_bf16 v[32:47], v[4:7], v[136:139], 0
	s_waitcnt vmcnt(13)
	v_mfma_f32_32x32x16_bf16 v[16:31], v[8:11], v[136:139], 0
	s_waitcnt vmcnt(12)
	v_mfma_f32_32x32x16_bf16 v[0:15], v[12:15], v[136:139], 0
	ds_read_b128 v[136:139], v156 offset:32
	s_waitcnt vmcnt(11) lgkmcnt(0)
	v_mfma_f32_32x32x16_bf16 v[48:63], v[66:69], v[136:139], v[48:63]
	s_waitcnt vmcnt(10)
	v_mfma_f32_32x32x16_bf16 v[32:47], v[70:73], v[136:139], v[32:47]
	s_waitcnt vmcnt(9)
	v_mfma_f32_32x32x16_bf16 v[16:31], v[74:77], v[136:139], v[16:31]
	s_waitcnt vmcnt(8)
	v_mfma_f32_32x32x16_bf16 v[0:15], v[78:81], v[136:139], v[0:15]
	s_lshl_b64 s[0:1], s[14:15], 10
	s_add_u32 s0, s28, s0
	s_addc_u32 s1, s29, s1
	s_add_u32 s0, s0, s16
	s_mov_b64 s[20:21], s[12:13]
	s_addc_u32 s1, s1, 0
	s_mov_b64 s[22:23], s[0:1]
	s_mov_b64 s[24:25], s[38:39]
	v_lshl_add_u64 v[78:79], s[20:21], 0, v[100:101]
	global_load_dwordx4 v[66:69], v[78:79], off
	global_load_dwordx4 v[70:73], v[78:79], off offset:512
	global_load_dwordx4 v[74:77], v[78:79], off offset:1024
	s_nop 0
	global_load_dwordx4 v[78:81], v[78:79], off offset:1536
	v_lshl_add_u64 v[136:137], s[22:23], 0, v[64:65]
	v_lshl_add_u64 v[144:145], s[24:25], 0, v[98:99]
	global_load_dwordx4 v[136:139], v[136:137], off
	s_nop 0
	global_load_dwordx4 v[140:143], v[144:145], off offset:16
	s_nop 0
	global_load_dwordx4 v[144:147], v[144:145], off
	s_mov_b32 s60, 1
	ds_read_b128 v[148:151], v156 offset:64
	s_waitcnt vmcnt(14) lgkmcnt(0)
	v_mfma_f32_32x32x16_bf16 v[48:63], v[82:85], v[148:151], v[48:63]
	ds_read_b128 v[82:85], v156 offset:96
	s_waitcnt vmcnt(13)
	v_mfma_f32_32x32x16_bf16 v[32:47], v[86:89], v[148:151], v[32:47]
	s_waitcnt vmcnt(12)
	v_mfma_f32_32x32x16_bf16 v[16:31], v[90:93], v[148:151], v[16:31]
	s_waitcnt vmcnt(11)
	v_mfma_f32_32x32x16_bf16 v[0:15], v[94:97], v[148:151], v[0:15]
	s_waitcnt vmcnt(10) lgkmcnt(0)
	v_mfma_f32_32x32x16_bf16 v[48:63], v[120:123], v[82:85], v[48:63]
	s_waitcnt vmcnt(9)
	v_mfma_f32_32x32x16_bf16 v[32:47], v[124:127], v[82:85], v[32:47]
	s_waitcnt vmcnt(8)
	v_mfma_f32_32x32x16_bf16 v[16:31], v[128:131], v[82:85], v[16:31]
	s_waitcnt vmcnt(7)
	v_mfma_f32_32x32x16_bf16 v[0:15], v[132:135], v[82:85], v[0:15]
	s_mov_b64 s[20:21], s[40:41]
	s_add_u32 s22, s0, 32
	s_addc_u32 s23, s1, 0
	s_mov_b64 s[24:25], s[42:43]
	v_lshl_add_u64 v[94:95], s[20:21], 0, v[100:101]
	global_load_dwordx4 v[82:85], v[94:95], off
	global_load_dwordx4 v[86:89], v[94:95], off offset:512
	global_load_dwordx4 v[90:93], v[94:95], off offset:1024
	s_nop 0
	global_load_dwordx4 v[94:97], v[94:95], off offset:1536
	v_lshl_add_u64 v[120:121], s[22:23], 0, v[64:65]
	v_lshl_add_u64 v[128:129], s[24:25], 0, v[98:99]
	global_load_dwordx4 v[120:123], v[120:121], off
	s_nop 0
	global_load_dwordx4 v[124:127], v[128:129], off offset:16
	s_nop 0
	global_load_dwordx4 v[128:131], v[128:129], off
	s_waitcnt vmcnt(9)
	v_lshlrev_b32_e32 v132, 16, v136
	v_and_b32_e32 v133, 0xffff0000, v136
	v_lshlrev_b32_e32 v134, 16, v137
	v_and_b32_e32 v135, 0xffff0000, v137
	s_waitcnt vmcnt(7)
	v_pk_mul_f32 v[132:133], v[144:145], v[132:133]
	v_pk_mul_f32 v[134:135], v[146:147], v[134:135]
	v_cvt_pk_bf16_f32 v132, v132, v133
	v_cvt_pk_bf16_f32 v133, v134, v135
	v_lshlrev_b32_e32 v134, 16, v138
	v_and_b32_e32 v135, 0xffff0000, v138
	v_lshlrev_b32_e32 v136, 16, v139
	v_and_b32_e32 v137, 0xffff0000, v139
	v_pk_mul_f32 v[134:135], v[140:141], v[134:135]
	v_pk_mul_f32 v[136:137], v[142:143], v[136:137]
	v_cvt_pk_bf16_f32 v134, v134, v135
	v_cvt_pk_bf16_f32 v135, v136, v137
	s_nop 1
	v_mfma_f32_32x32x16_bf16 v[48:63], v[66:69], v[132:135], v[48:63]
	v_mfma_f32_32x32x16_bf16 v[32:47], v[70:73], v[132:135], v[32:47]
	v_mfma_f32_32x32x16_bf16 v[16:31], v[74:77], v[132:135], v[16:31]
	v_mfma_f32_32x32x16_bf16 v[0:15], v[78:81], v[132:135], v[0:15]
	s_mov_b64 s[20:21], s[44:45]
	s_add_u32 s22, s0, 64
	s_addc_u32 s23, s1, 0
	s_mov_b64 s[24:25], s[46:47]
	v_lshl_add_u64 v[78:79], s[20:21], 0, v[100:101]
	global_load_dwordx4 v[66:69], v[78:79], off
	global_load_dwordx4 v[70:73], v[78:79], off offset:512
	global_load_dwordx4 v[74:77], v[78:79], off offset:1024
	s_nop 0
	global_load_dwordx4 v[78:81], v[78:79], off offset:1536
	v_lshl_add_u64 v[132:133], s[22:23], 0, v[64:65]
	v_lshl_add_u64 v[140:141], s[24:25], 0, v[98:99]
	global_load_dwordx4 v[132:135], v[132:133], off
	s_nop 0
	global_load_dwordx4 v[136:139], v[140:141], off offset:16
	s_nop 0
	global_load_dwordx4 v[140:143], v[140:141], off
	s_waitcnt vmcnt(9)
; #define P3_STEP2(st) do { P3_SLOAD(A1, (st) + 1); P3_SCOMP(A0, (st)); P3_SLOAD(A0, (st) + 2); P3_SCOMP(A1, (st) + 1); } while (0)
; template <int DK> __device__ __forceinline__ void scan_out_wave(const ScanBufs<DK>& S, int g, int h, const bf16* P, int gcol, const float* gain, bf16* Y, LAS unsigned char* W, int lane) {
;     ...
;         P3_SLOAD(A0, 0);
;         P3_STEP2(0); P3_STEP2(2); P3_STEP2(4); P3_STEP2(6); P3_STEP2(8); P3_STEP2(10);
	v_lshlrev_b32_e32 v144, 16, v120
	v_and_b32_e32 v145, 0xffff0000, v120
	s_waitcnt vmcnt(7)
	v_pk_mul_f32 v[128:129], v[128:129], v[144:145]
	s_nop 0
	v_cvt_pk_bf16_f32 v120, v128, v129
	v_lshlrev_b32_e32 v128, 16, v121
	v_and_b32_e32 v129, 0xffff0000, v121
	v_pk_mul_f32 v[128:129], v[130:131], v[128:129]
	s_nop 0
	v_cvt_pk_bf16_f32 v121, v128, v129
	v_lshlrev_b32_e32 v128, 16, v122
	v_and_b32_e32 v129, 0xffff0000, v122
	v_pk_mul_f32 v[124:125], v[124:125], v[128:129]
	s_nop 0
	v_cvt_pk_bf16_f32 v122, v124, v125
	v_lshlrev_b32_e32 v124, 16, v123
	v_and_b32_e32 v125, 0xffff0000, v123
	v_pk_mul_f32 v[124:125], v[126:127], v[124:125]
	s_nop 0
	v_cvt_pk_bf16_f32 v123, v124, v125
	s_nop 1
	v_mfma_f32_32x32x16_bf16 v[48:63], v[82:85], v[120:123], v[48:63]
	v_mfma_f32_32x32x16_bf16 v[32:47], v[86:89], v[120:123], v[32:47]
	v_mfma_f32_32x32x16_bf16 v[16:31], v[90:93], v[120:123], v[16:31]
	v_mfma_f32_32x32x16_bf16 v[0:15], v[94:97], v[120:123], v[0:15]
	s_mov_b64 s[20:21], s[48:49]
	s_add_u32 s22, s0, 0x60
	s_addc_u32 s23, s1, 0
	s_mov_b64 s[24:25], s[50:51]
	v_lshl_add_u64 v[94:95], s[20:21], 0, v[100:101]
	global_load_dwordx4 v[82:85], v[94:95], off
	global_load_dwordx4 v[86:89], v[94:95], off offset:512
	global_load_dwordx4 v[90:93], v[94:95], off offset:1024
	s_nop 0
	global_load_dwordx4 v[94:97], v[94:95], off offset:1536
	v_lshl_add_u64 v[120:121], s[22:23], 0, v[64:65]
	v_lshl_add_u64 v[128:129], s[24:25], 0, v[98:99]
	global_load_dwordx4 v[120:123], v[120:121], off
	s_nop 0
	global_load_dwordx4 v[124:127], v[128:129], off offset:16
	s_nop 0
	global_load_dwordx4 v[128:131], v[128:129], off
	s_waitcnt vmcnt(9)
	v_lshlrev_b32_e32 v144, 16, v132
	v_and_b32_e32 v145, 0xffff0000, v132
	s_waitcnt vmcnt(7)
	v_pk_mul_f32 v[140:141], v[140:141], v[144:145]
	s_nop 0
	v_cvt_pk_bf16_f32 v132, v140, v141
	v_lshlrev_b32_e32 v140, 16, v133
	v_and_b32_e32 v141, 0xffff0000, v133
	v_pk_mul_f32 v[140:141], v[142:143], v[140:141]
	s_nop 0
	v_cvt_pk_bf16_f32 v133, v140, v141
	v_lshlrev_b32_e32 v140, 16, v134
	v_and_b32_e32 v141, 0xffff0000, v134
	v_pk_mul_f32 v[136:137], v[136:137], v[140:141]
	s_nop 0
	v_cvt_pk_bf16_f32 v134, v136, v137
	v_lshlrev_b32_e32 v136, 16, v135
	v_and_b32_e32 v137, 0xffff0000, v135
	v_pk_mul_f32 v[136:137], v[138:139], v[136:137]
	s_nop 0
	v_cvt_pk_bf16_f32 v135, v136, v137
	s_nop 1
	v_mfma_f32_32x32x16_bf16 v[48:63], v[66:69], v[132:135], v[48:63]
	v_mfma_f32_32x32x16_bf16 v[32:47], v[70:73], v[132:135], v[32:47]
	v_mfma_f32_32x32x16_bf16 v[16:31], v[74:77], v[132:135], v[16:31]
	v_mfma_f32_32x32x16_bf16 v[0:15], v[78:81], v[132:135], v[0:15]
	s_mov_b64 s[20:21], s[4:5]
	s_nop 0
	v_lshl_add_u64 v[78:79], s[20:21], 0, v[100:101]
	s_mov_b64 s[20:21], s[6:7]
	global_load_dwordx4 v[66:69], v[78:79], off
	global_load_dwordx4 v[70:73], v[78:79], off offset:512
	global_load_dwordx4 v[74:77], v[78:79], off offset:1024
	s_nop 0
	global_load_dwordx4 v[78:81], v[78:79], off offset:1536
	s_nop 0
	v_lshl_add_u64 v[144:145], s[20:21], 0, v[100:101]
	global_load_dwordx4 v[132:135], v[144:145], off
	global_load_dwordx4 v[136:139], v[144:145], off offset:512
	global_load_dwordx4 v[140:143], v[144:145], off offset:1024
	s_nop 0
	global_load_dwordx4 v[144:147], v[144:145], off offset:1536
	s_waitcnt vmcnt(10)
	v_lshlrev_b32_e32 v148, 16, v120
	v_and_b32_e32 v149, 0xffff0000, v120
	s_waitcnt vmcnt(8)
	v_pk_mul_f32 v[128:129], v[128:129], v[148:149]
	s_nop 0
	v_cvt_pk_bf16_f32 v120, v128, v129
	v_lshlrev_b32_e32 v128, 16, v121
	v_and_b32_e32 v129, 0xffff0000, v121
	v_pk_mul_f32 v[128:129], v[130:131], v[128:129]
	s_nop 0
	v_cvt_pk_bf16_f32 v121, v128, v129
	v_lshlrev_b32_e32 v128, 16, v122
	v_and_b32_e32 v129, 0xffff0000, v122
	v_pk_mul_f32 v[124:125], v[124:125], v[128:129]
	s_nop 0
	v_cvt_pk_bf16_f32 v122, v124, v125
	v_lshlrev_b32_e32 v124, 16, v123
	v_and_b32_e32 v125, 0xffff0000, v123
	v_pk_mul_f32 v[124:125], v[126:127], v[124:125]
	s_nop 0
	v_cvt_pk_bf16_f32 v123, v124, v125
	s_nop 1
	v_mfma_f32_32x32x16_bf16 v[48:63], v[82:85], v[120:123], v[48:63]
	v_mfma_f32_32x32x16_bf16 v[32:47], v[86:89], v[120:123], v[32:47]
	v_mfma_f32_32x32x16_bf16 v[16:31], v[90:93], v[120:123], v[16:31]
	v_mfma_f32_32x32x16_bf16 v[0:15], v[94:97], v[120:123], v[0:15]
	s_mov_b64 s[20:21], s[8:9]
	s_nop 0
	v_lshl_add_u64 v[94:95], s[20:21], 0, v[100:101]
	s_mov_b64 s[20:21], s[10:11]
	global_load_dwordx4 v[82:85], v[94:95], off
	global_load_dwordx4 v[86:89], v[94:95], off offset:512
	global_load_dwordx4 v[90:93], v[94:95], off offset:1024
	s_nop 0
	global_load_dwordx4 v[94:97], v[94:95], off offset:1536
	s_nop 0
	v_lshl_add_u64 v[148:149], s[20:21], 0, v[100:101]
	global_load_dwordx4 v[120:123], v[148:149], off
	global_load_dwordx4 v[124:127], v[148:149], off offset:512
	global_load_dwordx4 v[128:131], v[148:149], off offset:1024
	s_nop 0
	global_load_dwordx4 v[148:151], v[148:149], off offset:1536
	ds_read_b128 v[152:155], v156 offset:4608
	s_waitcnt vmcnt(15) lgkmcnt(0)
	v_mfma_f32_32x32x16_bf16 v[48:63], v[66:69], v[152:155], v[48:63]
	ds_read_b128 v[66:69], v156 offset:4640
	s_waitcnt vmcnt(14)
	v_mfma_f32_32x32x16_bf16 v[32:47], v[70:73], v[152:155], v[32:47]
	s_waitcnt vmcnt(13)
	v_mfma_f32_32x32x16_bf16 v[16:31], v[74:77], v[152:155], v[16:31]
	s_waitcnt vmcnt(12)
	v_mfma_f32_32x32x16_bf16 v[0:15], v[78:81], v[152:155], v[0:15]
	s_waitcnt vmcnt(11) lgkmcnt(0)
	v_mfma_f32_32x32x16_bf16 v[48:63], v[132:135], v[66:69], v[48:63]
	s_waitcnt vmcnt(10)
	v_mfma_f32_32x32x16_bf16 v[32:47], v[136:139], v[66:69], v[32:47]
	s_waitcnt vmcnt(9)
	v_mfma_f32_32x32x16_bf16 v[16:31], v[140:143], v[66:69], v[16:31]
	s_waitcnt vmcnt(8)
; #define P3_STEP2(st) do { P3_SLOAD(A1, (st) + 1); P3_SCOMP(A0, (st)); P3_SLOAD(A0, (st) + 2); P3_SCOMP(A1, (st) + 1); } while (0)
; template <int DK> __device__ __forceinline__ void scan_out_wave(const ScanBufs<DK>& S, int g, int h, const bf16* P, int gcol, const float* gain, bf16* Y, LAS unsigned char* W, int lane) {
;     ...
;         P3_SLOAD(A0, 0);
;         P3_STEP2(0); P3_STEP2(2); P3_STEP2(4); P3_STEP2(6); P3_STEP2(8); P3_STEP2(10);
	v_mfma_f32_32x32x16_bf16 v[0:15], v[144:147], v[66:69], v[0:15]
	s_mov_b64 s[20:21], s[52:53]
	s_add_u32 s22, s0, 0x900000
	s_addc_u32 s23, s1, 0
	s_mov_b64 s[24:25], s[54:55]
	v_lshl_add_u64 v[78:79], s[20:21], 0, v[100:101]
	global_load_dwordx4 v[66:69], v[78:79], off
	global_load_dwordx4 v[70:73], v[78:79], off offset:512
	global_load_dwordx4 v[74:77], v[78:79], off offset:1024
	s_nop 0
	global_load_dwordx4 v[78:81], v[78:79], off offset:1536
	v_lshl_add_u64 v[132:133], s[22:23], 0, v[64:65]
	v_lshl_add_u64 v[140:141], s[24:25], 0, v[98:99]
	global_load_dwordx4 v[132:135], v[132:133], off
	s_nop 0
	global_load_dwordx4 v[136:139], v[140:141], off offset:16
	s_nop 0
	global_load_dwordx4 v[140:143], v[140:141], off
	ds_read_b128 v[144:147], v156 offset:4672
	s_waitcnt vmcnt(14) lgkmcnt(0)
	v_mfma_f32_32x32x16_bf16 v[48:63], v[82:85], v[144:147], v[48:63]
	ds_read_b128 v[82:85], v156 offset:4704
	s_waitcnt vmcnt(13)
	v_mfma_f32_32x32x16_bf16 v[32:47], v[86:89], v[144:147], v[32:47]
	s_waitcnt vmcnt(12)
	v_mfma_f32_32x32x16_bf16 v[16:31], v[90:93], v[144:147], v[16:31]
	s_waitcnt vmcnt(11)
	v_mfma_f32_32x32x16_bf16 v[0:15], v[94:97], v[144:147], v[0:15]
	s_waitcnt vmcnt(10) lgkmcnt(0)
	v_mfma_f32_32x32x16_bf16 v[48:63], v[120:123], v[82:85], v[48:63]
	s_waitcnt vmcnt(9)
	v_mfma_f32_32x32x16_bf16 v[32:47], v[124:127], v[82:85], v[32:47]
	s_waitcnt vmcnt(8)
	v_mfma_f32_32x32x16_bf16 v[16:31], v[128:131], v[82:85], v[16:31]
	s_waitcnt vmcnt(7)
	v_mfma_f32_32x32x16_bf16 v[0:15], v[148:151], v[82:85], v[0:15]
	s_mov_b64 s[20:21], s[62:63]
	s_add_u32 s22, s0, 0x900020
	s_addc_u32 s23, s1, 0
	s_mov_b64 s[24:25], s[64:65]
	v_lshl_add_u64 v[94:95], s[20:21], 0, v[100:101]
	global_load_dwordx4 v[82:85], v[94:95], off
	global_load_dwordx4 v[86:89], v[94:95], off offset:512
	global_load_dwordx4 v[90:93], v[94:95], off offset:1024
	s_nop 0
	global_load_dwordx4 v[94:97], v[94:95], off offset:1536
	v_lshl_add_u64 v[120:121], s[22:23], 0, v[64:65]
	v_lshl_add_u64 v[128:129], s[24:25], 0, v[98:99]
	global_load_dwordx4 v[120:123], v[120:121], off
	s_nop 0
	global_load_dwordx4 v[124:127], v[128:129], off offset:16
	s_nop 0
	global_load_dwordx4 v[128:131], v[128:129], off
	s_waitcnt vmcnt(9)
	v_lshlrev_b32_e32 v144, 16, v132
	v_and_b32_e32 v145, 0xffff0000, v132
	s_waitcnt vmcnt(7)
	v_pk_mul_f32 v[140:141], v[140:141], v[144:145]
	s_nop 0
	v_cvt_pk_bf16_f32 v132, v140, v141
	v_lshlrev_b32_e32 v140, 16, v133
	v_and_b32_e32 v141, 0xffff0000, v133
	v_pk_mul_f32 v[140:141], v[142:143], v[140:141]
	s_nop 0
	v_cvt_pk_bf16_f32 v133, v140, v141
	v_lshlrev_b32_e32 v140, 16, v134
	v_and_b32_e32 v141, 0xffff0000, v134
	v_pk_mul_f32 v[136:137], v[136:137], v[140:141]
	s_nop 0
	v_cvt_pk_bf16_f32 v134, v136, v137
	v_lshlrev_b32_e32 v136, 16, v135
	v_and_b32_e32 v137, 0xffff0000, v135
	v_pk_mul_f32 v[136:137], v[138:139], v[136:137]
	s_nop 0
	v_cvt_pk_bf16_f32 v135, v136, v137
	s_nop 1
	v_mfma_f32_32x32x16_bf16 v[48:63], v[66:69], v[132:135], v[48:63]
	v_mfma_f32_32x32x16_bf16 v[32:47], v[70:73], v[132:135], v[32:47]
	v_mfma_f32_32x32x16_bf16 v[16:31], v[74:77], v[132:135], v[16:31]
	v_mfma_f32_32x32x16_bf16 v[0:15], v[78:81], v[132:135], v[0:15]
	s_mov_b64 s[20:21], s[66:67]
	s_add_u32 s22, s0, 0x900040
	s_addc_u32 s23, s1, 0
	s_mov_b64 s[24:25], s[68:69]
	v_lshl_add_u64 v[78:79], s[20:21], 0, v[100:101]
	global_load_dwordx4 v[66:69], v[78:79], off
	global_load_dwordx4 v[70:73], v[78:79], off offset:512
	global_load_dwordx4 v[74:77], v[78:79], off offset:1024
	s_nop 0
	global_load_dwordx4 v[78:81], v[78:79], off offset:1536
	v_lshl_add_u64 v[132:133], s[22:23], 0, v[64:65]
	v_lshl_add_u64 v[140:141], s[24:25], 0, v[98:99]
	global_load_dwordx4 v[132:135], v[132:133], off
	s_nop 0
	global_load_dwordx4 v[136:139], v[140:141], off offset:16
	s_nop 0
	global_load_dwordx4 v[140:143], v[140:141], off
	s_waitcnt vmcnt(9)
	v_lshlrev_b32_e32 v144, 16, v120
	v_and_b32_e32 v145, 0xffff0000, v120
	s_waitcnt vmcnt(7)
	v_pk_mul_f32 v[128:129], v[128:129], v[144:145]
	s_nop 0
	v_cvt_pk_bf16_f32 v120, v128, v129
	v_lshlrev_b32_e32 v128, 16, v121
	v_and_b32_e32 v129, 0xffff0000, v121
	v_pk_mul_f32 v[128:129], v[130:131], v[128:129]
	s_nop 0
	v_cvt_pk_bf16_f32 v121, v128, v129
	v_lshlrev_b32_e32 v128, 16, v122
	v_and_b32_e32 v129, 0xffff0000, v122
	v_pk_mul_f32 v[124:125], v[124:125], v[128:129]
	s_nop 0
	v_cvt_pk_bf16_f32 v122, v124, v125
	v_lshlrev_b32_e32 v124, 16, v123
	v_and_b32_e32 v125, 0xffff0000, v123
	v_pk_mul_f32 v[124:125], v[126:127], v[124:125]
	s_nop 0
	v_cvt_pk_bf16_f32 v123, v124, v125
	s_nop 1
	v_mfma_f32_32x32x16_bf16 v[48:63], v[82:85], v[120:123], v[48:63]
	v_mfma_f32_32x32x16_bf16 v[32:47], v[86:89], v[120:123], v[32:47]
	v_mfma_f32_32x32x16_bf16 v[16:31], v[90:93], v[120:123], v[16:31]
	v_mfma_f32_32x32x16_bf16 v[0:15], v[94:97], v[120:123], v[0:15]
	s_mov_b64 s[20:21], s[70:71]
	s_add_u32 s0, s0, 0x900060
	s_addc_u32 s1, s1, 0
	s_mov_b64 s[22:23], s[72:73]
	v_lshl_add_u64 v[82:83], s[20:21], 0, v[100:101]
	global_load_dwordx4 v[120:123], v[82:83], off
	global_load_dwordx4 v[124:127], v[82:83], off offset:512
	global_load_dwordx4 v[128:131], v[82:83], off offset:1024
	global_load_dwordx4 v[144:147], v[82:83], off offset:1536
	v_lshl_add_u64 v[82:83], s[0:1], 0, v[64:65]
	global_load_dwordx4 v[148:151], v[82:83], off
	v_lshl_add_u64 v[82:83], s[22:23], 0, v[98:99]
	global_load_dwordx4 v[152:155], v[82:83], off offset:16
	global_load_dwordx4 v[156:159], v[82:83], off
	s_waitcnt vmcnt(9)
	v_lshlrev_b32_e32 v82, 16, v132
	v_and_b32_e32 v83, 0xffff0000, v132
	v_lshlrev_b32_e32 v84, 16, v133
	v_and_b32_e32 v85, 0xffff0000, v133
	s_waitcnt vmcnt(7)
; #define P3_STEP2(st) do { P3_SLOAD(A1, (st) + 1); P3_SCOMP(A0, (st)); P3_SLOAD(A0, (st) + 2); P3_SCOMP(A1, (st) + 1); } while (0)
; template <int DK> __device__ __forceinline__ void scan_out_wave(const ScanBufs<DK>& S, int g, int h, const bf16* P, int gcol, const float* gain, bf16* Y, LAS unsigned char* W, int lane) {
;     ...
;         P3_SLOAD(A0, 0);
;         P3_STEP2(0); P3_STEP2(2); P3_STEP2(4); P3_STEP2(6); P3_STEP2(8); P3_STEP2(10);
;         if (NK == 8) { P3_STEP2(12); P3_STEP2(14); P3_STEP2(16); P3_STEP2(18); }
;     ...
;         float ss = 0.f;
; #pragma unroll
;         for (int dvt = 0; dvt < 4; ++dvt)
; #pragma unroll
;             for (int e = 0; e < 16; ++e) ss += acc[dvt][e] * acc[dvt][e];
;         ss += __shfl_xor(ss, 32);
	v_pk_mul_f32 v[82:83], v[140:141], v[82:83]
	v_pk_mul_f32 v[84:85], v[142:143], v[84:85]
	v_cvt_pk_bf16_f32 v82, v82, v83
	v_cvt_pk_bf16_f32 v83, v84, v85
	v_lshlrev_b32_e32 v84, 16, v134
	v_and_b32_e32 v85, 0xffff0000, v134
	v_lshlrev_b32_e32 v86, 16, v135
	v_and_b32_e32 v87, 0xffff0000, v135
	s_add_u32 s2, s2, s17
	v_pk_mul_f32 v[84:85], v[136:137], v[84:85]
	v_pk_mul_f32 v[86:87], v[138:139], v[86:87]
	s_addc_u32 s3, s3, 0
	v_cvt_pk_bf16_f32 v84, v84, v85
	v_cvt_pk_bf16_f32 v85, v86, v87
	s_add_u32 s0, s2, 0x3800
	s_addc_u32 s1, s3, 0
	v_mfma_f32_32x32x16_bf16 v[48:63], v[66:69], v[82:85], v[48:63]
	v_mfma_f32_32x32x16_bf16 v[32:47], v[70:73], v[82:85], v[32:47]
	v_mfma_f32_32x32x16_bf16 v[16:31], v[74:77], v[82:85], v[16:31]
	v_mfma_f32_32x32x16_bf16 v[0:15], v[78:81], v[82:85], v[0:15]
	s_nop 0
	v_lshl_add_u64 v[66:67], s[0:1], 0, v[102:103]
	s_add_u32 s0, s2, 0x3880
	s_addc_u32 s1, s3, 0
	global_load_dwordx4 v[94:97], v[66:67], off
	s_nop 0
	v_lshl_add_u64 v[66:67], s[0:1], 0, v[102:103]
	s_add_u32 s0, s2, 0x48800
	s_addc_u32 s1, s3, 0
	global_load_dwordx4 v[90:93], v[66:67], off
	s_nop 0
	v_lshl_add_u64 v[66:67], s[0:1], 0, v[102:103]
	s_add_u32 s0, s2, 0x48880
	s_addc_u32 s1, s3, 0
	global_load_dwordx4 v[86:89], v[66:67], off
	s_nop 0
	v_lshl_add_u64 v[66:67], s[0:1], 0, v[102:103]
	s_add_u32 s0, s2, 0x8d800
	s_addc_u32 s1, s3, 0
	global_load_dwordx4 v[82:85], v[66:67], off
	s_nop 0
	v_lshl_add_u64 v[66:67], s[0:1], 0, v[102:103]
	s_add_u32 s0, s2, 0x8d880
	s_addc_u32 s1, s3, 0
	global_load_dwordx4 v[78:81], v[66:67], off
	s_nop 0
	v_lshl_add_u64 v[66:67], s[0:1], 0, v[102:103]
	s_add_u32 s0, s2, 0xd2800
	s_addc_u32 s1, s3, 0
	global_load_dwordx4 v[74:77], v[66:67], off
	s_nop 0
	v_lshl_add_u64 v[66:67], s[0:1], 0, v[102:103]
	s_add_u32 s0, s2, 0xd2880
	s_addc_u32 s1, s3, 0
	global_load_dwordx4 v[70:73], v[66:67], off
	s_nop 0
	v_lshl_add_u64 v[66:67], s[0:1], 0, v[102:103]
	global_load_dwordx4 v[66:69], v[66:67], off
	s_waitcnt vmcnt(10)
	v_lshlrev_b32_e32 v132, 16, v148
	v_and_b32_e32 v133, 0xffff0000, v148
	v_lshlrev_b32_e32 v134, 16, v149
	v_and_b32_e32 v135, 0xffff0000, v149
	s_waitcnt vmcnt(8)
	v_pk_mul_f32 v[132:133], v[156:157], v[132:133]
	v_pk_mul_f32 v[134:135], v[158:159], v[134:135]
	v_cvt_pk_bf16_f32 v132, v132, v133
	v_cvt_pk_bf16_f32 v133, v134, v135
	v_lshlrev_b32_e32 v134, 16, v150
	v_and_b32_e32 v135, 0xffff0000, v150
	v_lshlrev_b32_e32 v136, 16, v151
	v_and_b32_e32 v137, 0xffff0000, v151
	v_pk_mul_f32 v[134:135], v[152:153], v[134:135]
	v_pk_mul_f32 v[136:137], v[154:155], v[136:137]
	v_cvt_pk_bf16_f32 v134, v134, v135
	v_cvt_pk_bf16_f32 v135, v136, v137
	s_nop 1
	v_mfma_f32_32x32x16_bf16 v[48:63], v[120:123], v[132:135], v[48:63]
	v_mfma_f32_32x32x16_bf16 v[32:47], v[124:127], v[132:135], v[32:47]
	v_mfma_f32_32x32x16_bf16 v[16:31], v[128:131], v[132:135], v[16:31]
	v_mfma_f32_32x32x16_bf16 v[0:15], v[144:147], v[132:135], v[0:15]
	s_nop 8
	v_mul_f32_e32 v126, v49, v49
	v_fmac_f32_e32 v126, v48, v48
	v_fmac_f32_e32 v126, v50, v50
	v_fmac_f32_e32 v126, v51, v51
	v_fmac_f32_e32 v126, v52, v52
	v_fmac_f32_e32 v126, v53, v53
	v_fmac_f32_e32 v126, v54, v54
	v_fmac_f32_e32 v126, v55, v55
	v_fmac_f32_e32 v126, v56, v56
	v_fmac_f32_e32 v126, v57, v57
	v_fmac_f32_e32 v126, v58, v58
	v_fmac_f32_e32 v126, v59, v59
	v_fmac_f32_e32 v126, v60, v60
	v_fmac_f32_e32 v126, v61, v61
	v_fmac_f32_e32 v126, v62, v62
	v_fmac_f32_e32 v126, v63, v63
	v_fmac_f32_e32 v126, v32, v32
	v_fmac_f32_e32 v126, v33, v33
	v_fmac_f32_e32 v126, v34, v34
	v_fmac_f32_e32 v126, v35, v35
	v_fmac_f32_e32 v126, v36, v36
	v_fmac_f32_e32 v126, v37, v37
	v_fmac_f32_e32 v126, v38, v38
	v_fmac_f32_e32 v126, v39, v39
	v_fmac_f32_e32 v126, v40, v40
	v_fmac_f32_e32 v126, v41, v41
	v_fmac_f32_e32 v126, v42, v42
	v_fmac_f32_e32 v126, v43, v43
	v_fmac_f32_e32 v126, v44, v44
	v_fmac_f32_e32 v126, v45, v45
	v_fmac_f32_e32 v126, v46, v46
	v_fmac_f32_e32 v126, v47, v47
	v_fmac_f32_e32 v126, v16, v16
	v_fmac_f32_e32 v126, v17, v17
	v_fmac_f32_e32 v126, v18, v18
	v_fmac_f32_e32 v126, v19, v19
	v_fmac_f32_e32 v126, v20, v20
	v_fmac_f32_e32 v126, v21, v21
	v_fmac_f32_e32 v126, v22, v22
	v_fmac_f32_e32 v126, v23, v23
	v_fmac_f32_e32 v126, v24, v24
	v_fmac_f32_e32 v126, v25, v25
	v_fmac_f32_e32 v126, v26, v26
	v_fmac_f32_e32 v126, v27, v27
	v_fmac_f32_e32 v126, v28, v28
	v_fmac_f32_e32 v126, v29, v29
	v_fmac_f32_e32 v126, v30, v30
	v_fmac_f32_e32 v126, v31, v31
	v_fmac_f32_e32 v126, v0, v0
	v_fmac_f32_e32 v126, v1, v1
	v_fmac_f32_e32 v126, v2, v2
	v_fmac_f32_e32 v126, v3, v3
	v_fmac_f32_e32 v126, v4, v4
	v_fmac_f32_e32 v126, v5, v5
	v_fmac_f32_e32 v126, v6, v6
	v_fmac_f32_e32 v126, v7, v7
	v_fmac_f32_e32 v126, v8, v8
	v_fmac_f32_e32 v126, v9, v9
	v_pk_mul_f32 v[124:125], v[10:11], v[10:11]
	v_pk_mul_f32 v[122:123], v[12:13], v[12:13]
	v_add_f32_e32 v124, v124, v126
	v_add_f32_e32 v124, v125, v124
	v_add_f32_e32 v122, v122, v124
	v_pk_mul_f32 v[120:121], v[14:15], v[14:15]
	v_add_f32_e32 v122, v123, v122
	v_add_f32_e32 v120, v120, v122
	v_and_b32_e32 v122, 64, v201
	v_add_f32_e32 v120, v121, v120
	v_xor_b32_e32 v121, 32, v201
	v_add_u32_e32 v122, 64, v122
	v_cmp_lt_i32_e32 vcc, v121, v122
	s_nop 1
	v_cndmask_b32_e32 v121, v201, v121, vcc
	v_lshlrev_b32_e32 v121, 2, v121
	ds_bpermute_b32 v121, v121, v120
	s_waitcnt lgkmcnt(0)
; #define GAS __attribute__((address_space(1)))
; #define LAS __attribute__((address_space(3)))
; #define LDS_WAIT() asm volatile("s_waitcnt lgkmcnt(0)" ::: "memory")
; __device__ __forceinline__ unsigned pk2(float lo, float hi) { const f32x2_t v = {lo, hi}; const bf16x2_t b = __builtin_convertvector(v, bf16x2_t); return __builtin_bit_cast(unsigned, b); }
; __device__ __forceinline__ float bflo(unsigned w) { return __uint_as_float(w << 16); }
; __device__ __forceinline__ float bfhi(unsigned w) { return __uint_as_float(w & 0xffff0000u); }
; __device__ __forceinline__ float sigmoidf_(float x) { return __builtin_amdgcn_rcpf(1.f + __expf(-x)); }
; template <int DK> __device__ __forceinline__ void scan_out_wave(const ScanBufs<DK>& S, int g, int h, const bf16* P, int gcol, const float* gain, bf16* Y, LAS unsigned char* W, int lane) {
;     ...
;         const float rstd = 1.0f / sqrtf(ss * (1.f / 128.f) + RMS_EPS);
;         LAS unsigned char* st = W + (size_t)tt * 2 * 32 * P3_ALP;
; #pragma unroll
;         for (int dvt = 0; dvt < 4; ++dvt)
; #pragma unroll
;             for (int q = 0; q < 4; ++q) { v2u o; o.x = pk2(acc[dvt][4 * q] * rstd, acc[dvt][4 * q + 1] * rstd); o.y = pk2(acc[dvt][4 * q + 2] * rstd, acc[dvt][4 * q + 3] * rstd); *(LAS v2u*)(st + r * P3_STP + (32 * dvt + 8 * q + 4 * hi) * 2) = o; }
;         LDS_WAIT();
;         { char* Yu = (char*)(Y + rowt * 1024 + h * 128); const unsigned oy = (unsigned)((tl * 1024 + seg * 8) * 2);
; #pragma unroll
;           for (int j = 0; j < 8; ++j) { const int rr = 8 * (j >> 1), hf = j & 1; const v4u ow = *(const LAS v4u*)(st + (tl + rr) * P3_STP + hf * 128 + seg * 16); const v4u gw = A0.x[j];
;               const float* gn = gain + hf * 64 + seg * 8; const f32x4 n0 = *(const GAS f32x4*)gn, n1 = *(const GAS f32x4*)(gn + 4); v4u y;
; #pragma unroll
;               for (int c = 0; c < 4; ++c) { const float z0 = bflo(gw[c]), z1 = bfhi(gw[c]); const float na = c < 2 ? n0[2 * c] : n1[2 * c - 4], nb = c < 2 ? n0[2 * c + 1] : n1[2 * c - 3];
;                   y[c] = pk2(bflo(ow[c]) * na * z0 * sigmoidf_(z0), bfhi(ow[c]) * nb * z1 * sigmoidf_(z1)); }
;               *(GAS v4u*)(Yu + oy + ((size_t)rr * 1024 + hf * 64) * 2) = y; } }
	v_add_f32_e32 v120, v120, v121
	v_fmamk_f32 v120, v120, 0x3c000000, v202
	v_cmp_gt_f32_e32 vcc, s93, v120
	v_mul_f32_e32 v121, 0x4f800000, v120
	s_nop 0
	v_cndmask_b32_e32 v120, v120, v121, vcc
	v_sqrt_f32_e32 v121, v120
	s_nop 0
	v_add_u32_e32 v122, -1, v121
	v_fma_f32 v123, -v122, v121, v120
	v_cmp_ge_f32_e64 s[2:3], 0, v123
	v_add_u32_e32 v123, 1, v121
	s_nop 0
	v_cndmask_b32_e64 v122, v121, v122, s[2:3]
	v_fma_f32 v121, -v123, v121, v120
	v_cmp_lt_f32_e64 s[2:3], 0, v121
	s_nop 1
	v_cndmask_b32_e64 v121, v122, v123, s[2:3]
	v_mul_f32_e32 v122, 0x37800000, v121
	v_cndmask_b32_e32 v121, v121, v122, vcc
	v_cmp_class_f32_e32 vcc, v120, v203
	s_nop 1
	v_cndmask_b32_e32 v120, v121, v120, vcc
	v_div_scale_f32 v121, s[0:1], v120, v120, 1.0
	v_rcp_f32_e32 v122, v121
	s_lshl_b64 s[0:1], s[14:15], 11
	v_fma_f32 v123, -v121, v122, 1.0
	v_fmac_f32_e32 v122, v123, v122
	v_div_scale_f32 v123, vcc, 1.0, v120, 1.0
	v_mul_f32_e32 v124, v123, v122
	v_fma_f32 v125, -v121, v124, v123
	v_fmac_f32_e32 v124, v125, v122
	v_fma_f32 v121, -v121, v124, v123
	v_div_fmas_f32 v121, v121, v122, v124
	v_div_fixup_f32 v120, v121, v120, 1.0
	v_add3_u32 v121, s19, v111, v109
	v_pk_mul_f32 v[48:49], v[48:49], v[120:121] op_sel_hi:[1,0]
	v_pk_mul_f32 v[50:51], v[50:51], v[120:121] op_sel_hi:[1,0]
	v_pk_mul_f32 v[32:33], v[32:33], v[120:121] op_sel_hi:[1,0]
	v_pk_mul_f32 v[34:35], v[34:35], v[120:121] op_sel_hi:[1,0]
	v_pk_mul_f32 v[16:17], v[16:17], v[120:121] op_sel_hi:[1,0]
	v_pk_mul_f32 v[18:19], v[18:19], v[120:121] op_sel_hi:[1,0]
	v_pk_mul_f32 v[0:1], v[0:1], v[120:121] op_sel_hi:[1,0]
	v_pk_mul_f32 v[2:3], v[2:3], v[120:121] op_sel_hi:[1,0]
	v_cvt_pk_bf16_f32 v48, v48, v49
	v_cvt_pk_bf16_f32 v49, v50, v51
	v_pk_mul_f32 v[50:51], v[52:53], v[120:121] op_sel_hi:[1,0]
	v_pk_mul_f32 v[52:53], v[54:55], v[120:121] op_sel_hi:[1,0]
	v_cvt_pk_bf16_f32 v32, v32, v33
	v_cvt_pk_bf16_f32 v33, v34, v35
	v_pk_mul_f32 v[34:35], v[36:37], v[120:121] op_sel_hi:[1,0]
	v_pk_mul_f32 v[36:37], v[38:39], v[120:121] op_sel_hi:[1,0]
	v_cvt_pk_bf16_f32 v16, v16, v17
	v_cvt_pk_bf16_f32 v17, v18, v19
	v_pk_mul_f32 v[18:19], v[20:21], v[120:121] op_sel_hi:[1,0]
	v_pk_mul_f32 v[20:21], v[22:23], v[120:121] op_sel_hi:[1,0]
	v_cvt_pk_bf16_f32 v0, v0, v1
	v_cvt_pk_bf16_f32 v1, v2, v3
	v_pk_mul_f32 v[2:3], v[4:5], v[120:121] op_sel_hi:[1,0]
	v_pk_mul_f32 v[4:5], v[6:7], v[120:121] op_sel_hi:[1,0]
	v_cvt_pk_bf16_f32 v50, v50, v51
	v_cvt_pk_bf16_f32 v51, v52, v53
	v_cvt_pk_bf16_f32 v34, v34, v35
	v_cvt_pk_bf16_f32 v35, v36, v37
	v_cvt_pk_bf16_f32 v18, v18, v19
	v_cvt_pk_bf16_f32 v19, v20, v21
	v_cvt_pk_bf16_f32 v2, v2, v3
	v_cvt_pk_bf16_f32 v3, v4, v5
	ds_write2_b64 v121, v[48:49], v[50:51] offset1:2
	v_pk_mul_f32 v[48:49], v[56:57], v[120:121] op_sel_hi:[1,0]
	v_pk_mul_f32 v[50:51], v[58:59], v[120:121] op_sel_hi:[1,0]
	ds_write2_b64 v121, v[32:33], v[34:35] offset0:8 offset1:10
	v_pk_mul_f32 v[32:33], v[40:41], v[120:121] op_sel_hi:[1,0]
	v_pk_mul_f32 v[34:35], v[42:43], v[120:121] op_sel_hi:[1,0]
	ds_write2_b64 v121, v[16:17], v[18:19] offset0:16 offset1:18
	v_pk_mul_f32 v[16:17], v[24:25], v[120:121] op_sel_hi:[1,0]
	v_pk_mul_f32 v[18:19], v[26:27], v[120:121] op_sel_hi:[1,0]
	ds_write2_b64 v121, v[0:1], v[2:3] offset0:24 offset1:26
	v_pk_mul_f32 v[0:1], v[8:9], v[120:121] op_sel_hi:[1,0]
	v_pk_mul_f32 v[2:3], v[10:11], v[120:121] op_sel_hi:[1,0]
	v_cvt_pk_bf16_f32 v48, v48, v49
	v_cvt_pk_bf16_f32 v49, v50, v51
	v_pk_mul_f32 v[50:51], v[60:61], v[120:121] op_sel_hi:[1,0]
	v_pk_mul_f32 v[52:53], v[62:63], v[120:121] op_sel_hi:[1,0]
	v_cvt_pk_bf16_f32 v32, v32, v33
	v_cvt_pk_bf16_f32 v33, v34, v35
	v_pk_mul_f32 v[34:35], v[44:45], v[120:121] op_sel_hi:[1,0]
	v_pk_mul_f32 v[36:37], v[46:47], v[120:121] op_sel_hi:[1,0]
	v_cvt_pk_bf16_f32 v16, v16, v17
	v_cvt_pk_bf16_f32 v17, v18, v19
	v_pk_mul_f32 v[18:19], v[28:29], v[120:121] op_sel_hi:[1,0]
	v_pk_mul_f32 v[20:21], v[30:31], v[120:121] op_sel_hi:[1,0]
	v_cvt_pk_bf16_f32 v0, v0, v1
	v_cvt_pk_bf16_f32 v1, v2, v3
	v_pk_mul_f32 v[2:3], v[12:13], v[120:121] op_sel_hi:[1,0]
	v_pk_mul_f32 v[4:5], v[14:15], v[120:121] op_sel_hi:[1,0]
	v_cvt_pk_bf16_f32 v50, v50, v51
	v_cvt_pk_bf16_f32 v51, v52, v53
	v_cvt_pk_bf16_f32 v34, v34, v35
	v_cvt_pk_bf16_f32 v35, v36, v37
	v_cvt_pk_bf16_f32 v18, v18, v19
	v_cvt_pk_bf16_f32 v19, v20, v21
	v_cvt_pk_bf16_f32 v2, v2, v3
	v_cvt_pk_bf16_f32 v3, v4, v5
	ds_write2_b64 v121, v[48:49], v[50:51] offset0:4 offset1:6
	ds_write2_b64 v121, v[32:33], v[34:35] offset0:12 offset1:14
	ds_write2_b64 v121, v[16:17], v[18:19] offset0:20 offset1:22
	ds_write2_b64 v121, v[0:1], v[2:3] offset0:28 offset1:30
	s_waitcnt lgkmcnt(0)
	global_load_dwordx4 v[48:51], v[104:105], off
	global_load_dwordx4 v[52:55], v[104:105], off offset:16
	global_load_dwordx4 v[56:59], v[104:105], off offset:256
	global_load_dwordx4 v[60:63], v[104:105], off offset:272
	s_waitcnt vmcnt(0)
	v_add3_u32 v14, s19, v119, v118
	ds_read_b128 v[0:3], v14
	v_lshlrev_b32_e32 v16, 16, v94
	v_and_b32_e32 v17, 0xffff0000, v94
	v_mul_f32_e32 v15, 0xbfb8aa3b, v16
	s_waitcnt lgkmcnt(0)
; #define GAS __attribute__((address_space(1)))
; #define LAS __attribute__((address_space(3)))
; __device__ __forceinline__ unsigned pk2(float lo, float hi) { const f32x2_t v = {lo, hi}; const bf16x2_t b = __builtin_convertvector(v, bf16x2_t); return __builtin_bit_cast(unsigned, b); }
; __device__ __forceinline__ float bflo(unsigned w) { return __uint_as_float(w << 16); }
; __device__ __forceinline__ float bfhi(unsigned w) { return __uint_as_float(w & 0xffff0000u); }
; __device__ __forceinline__ float sigmoidf_(float x) { return __builtin_amdgcn_rcpf(1.f + __expf(-x)); }
; template <int DK> __device__ __forceinline__ void scan_out_wave(const ScanBufs<DK>& S, int g, int h, const bf16* P, int gcol, const float* gain, bf16* Y, LAS unsigned char* W, int lane) {
;     ...
;         { char* Yu = (char*)(Y + rowt * 1024 + h * 128); const unsigned oy = (unsigned)((tl * 1024 + seg * 8) * 2);
; #pragma unroll
;           for (int j = 0; j < 8; ++j) { const int rr = 8 * (j >> 1), hf = j & 1; const v4u ow = *(const LAS v4u*)(st + (tl + rr) * P3_STP + hf * 128 + seg * 16); const v4u gw = A0.x[j];
;               const float* gn = gain + hf * 64 + seg * 8; const f32x4 n0 = *(const GAS f32x4*)gn, n1 = *(const GAS f32x4*)(gn + 4); v4u y;
; #pragma unroll
;               for (int c = 0; c < 4; ++c) { const float z0 = bflo(gw[c]), z1 = bfhi(gw[c]); const float na = c < 2 ? n0[2 * c] : n1[2 * c - 4], nb = c < 2 ? n0[2 * c + 1] : n1[2 * c - 3];
;                   y[c] = pk2(bflo(ow[c]) * na * z0 * sigmoidf_(z0), bfhi(ow[c]) * nb * z1 * sigmoidf_(z1)); }
;               *(GAS v4u*)(Yu + oy + ((size_t)rr * 1024 + hf * 64) * 2) = y; } }
	v_lshlrev_b32_e32 v20, 16, v0
	v_and_b32_e32 v21, 0xffff0000, v0
	v_mul_f32_e32 v0, 0xbfb8aa3b, v17
	v_exp_f32_e32 v15, v15
	v_exp_f32_e32 v0, v0
	v_lshl_add_u64 v[12:13], v[106:107], 0, s[0:1]
	v_add_f32_e32 v15, 1.0, v15
	v_add_f32_e32 v0, 1.0, v0
	v_rcp_f32_e32 v18, v15
	v_rcp_f32_e32 v19, v0
	v_pk_mul_f32 v[8:9], v[48:49], v[20:21]
	s_nop 0
	v_pk_mul_f32 v[8:9], v[8:9], v[16:17]
	s_nop 0
	v_pk_mul_f32 v[8:9], v[18:19], v[8:9]
	v_lshlrev_b32_e32 v18, 16, v1
	v_cvt_pk_bf16_f32 v0, v8, v9
	v_lshlrev_b32_e32 v8, 16, v95
	v_and_b32_e32 v9, 0xffff0000, v95
	v_mul_f32_e32 v15, 0xbfb8aa3b, v8
	v_and_b32_e32 v19, 0xffff0000, v1
	v_mul_f32_e32 v1, 0xbfb8aa3b, v9
	v_exp_f32_e32 v15, v15
	v_exp_f32_e32 v1, v1
	v_pk_mul_f32 v[10:11], v[50:51], v[18:19]
	v_add_f32_e32 v15, 1.0, v15
	v_add_f32_e32 v1, 1.0, v1
	v_rcp_f32_e32 v16, v15
	v_rcp_f32_e32 v17, v1
	v_pk_mul_f32 v[10:11], v[10:11], v[8:9]
	s_nop 0
	v_pk_mul_f32 v[8:9], v[16:17], v[10:11]
	s_nop 0
	v_cvt_pk_bf16_f32 v1, v8, v9
	v_lshlrev_b32_e32 v8, 16, v96
	v_and_b32_e32 v9, 0xffff0000, v96
	v_mul_f32_e32 v10, 0xbfb8aa3b, v8
	v_lshlrev_b32_e32 v16, 16, v2
	v_and_b32_e32 v17, 0xffff0000, v2
	v_mul_f32_e32 v2, 0xbfb8aa3b, v9
	v_exp_f32_e32 v10, v10
	v_exp_f32_e32 v2, v2
	v_pk_mul_f32 v[4:5], v[52:53], v[16:17]
	v_lshlrev_b32_e32 v16, 16, v90
	v_add_f32_e32 v10, 1.0, v10
	v_add_f32_e32 v2, 1.0, v2
	v_rcp_f32_e32 v10, v10
	v_rcp_f32_e32 v11, v2
	v_pk_mul_f32 v[4:5], v[4:5], v[8:9]
	v_and_b32_e32 v17, 0xffff0000, v90
	v_mul_f32_e32 v15, 0xbfb8aa3b, v16
	v_pk_mul_f32 v[4:5], v[10:11], v[4:5]
	v_lshlrev_b32_e32 v10, 16, v3
	v_cvt_pk_bf16_f32 v2, v4, v5
	v_lshlrev_b32_e32 v4, 16, v97
	v_and_b32_e32 v5, 0xffff0000, v97
	v_mul_f32_e32 v8, 0xbfb8aa3b, v4
	v_and_b32_e32 v11, 0xffff0000, v3
	v_mul_f32_e32 v3, 0xbfb8aa3b, v5
	v_exp_f32_e32 v8, v8
	v_exp_f32_e32 v3, v3
	v_pk_mul_f32 v[6:7], v[54:55], v[10:11]
	v_exp_f32_e32 v15, v15
	v_add_f32_e32 v8, 1.0, v8
	v_add_f32_e32 v3, 1.0, v3
	v_rcp_f32_e32 v8, v8
	v_rcp_f32_e32 v9, v3
	v_pk_mul_f32 v[6:7], v[6:7], v[4:5]
	v_add_f32_e32 v15, 1.0, v15
	v_rcp_f32_e32 v18, v15
	v_pk_mul_f32 v[4:5], v[8:9], v[6:7]
	s_nop 0
	v_cvt_pk_bf16_f32 v3, v4, v5
	global_store_dwordx4 v[12:13], v[0:3], off
	s_nop 1
	ds_read_b128 v[0:3], v14 offset:128
	s_waitcnt lgkmcnt(0)
	v_lshlrev_b32_e32 v20, 16, v0
	v_and_b32_e32 v21, 0xffff0000, v0
	v_mul_f32_e32 v0, 0xbfb8aa3b, v17
	v_exp_f32_e32 v0, v0
	v_pk_mul_f32 v[8:9], v[56:57], v[20:21]
	v_add_f32_e32 v0, 1.0, v0
	v_rcp_f32_e32 v19, v0
	v_pk_mul_f32 v[8:9], v[8:9], v[16:17]
	s_nop 0
	v_pk_mul_f32 v[8:9], v[18:19], v[8:9]
	s_nop 0
	v_cvt_pk_bf16_f32 v0, v8, v9
	v_lshlrev_b32_e32 v8, 16, v91
	v_and_b32_e32 v9, 0xffff0000, v91
	v_mul_f32_e32 v15, 0xbfb8aa3b, v8
	v_lshlrev_b32_e32 v18, 16, v1
	v_and_b32_e32 v19, 0xffff0000, v1
	v_mul_f32_e32 v1, 0xbfb8aa3b, v9
	v_exp_f32_e32 v15, v15
	v_exp_f32_e32 v1, v1
	v_pk_mul_f32 v[10:11], v[58:59], v[18:19]
	v_add_f32_e32 v15, 1.0, v15
	v_add_f32_e32 v1, 1.0, v1
	v_rcp_f32_e32 v16, v15
	v_rcp_f32_e32 v17, v1
	v_pk_mul_f32 v[10:11], v[10:11], v[8:9]
	s_nop 0
	v_pk_mul_f32 v[8:9], v[16:17], v[10:11]
	s_nop 0
	v_cvt_pk_bf16_f32 v1, v8, v9
	v_lshlrev_b32_e32 v8, 16, v92
	v_and_b32_e32 v9, 0xffff0000, v92
	v_mul_f32_e32 v10, 0xbfb8aa3b, v8
	v_lshlrev_b32_e32 v16, 16, v2
	v_and_b32_e32 v17, 0xffff0000, v2
	v_mul_f32_e32 v2, 0xbfb8aa3b, v9
	v_exp_f32_e32 v10, v10
	v_exp_f32_e32 v2, v2
	v_pk_mul_f32 v[4:5], v[60:61], v[16:17]
	v_lshlrev_b32_e32 v16, 16, v86
	v_add_f32_e32 v10, 1.0, v10
	v_add_f32_e32 v2, 1.0, v2
	v_rcp_f32_e32 v10, v10
	v_rcp_f32_e32 v11, v2
	v_pk_mul_f32 v[4:5], v[4:5], v[8:9]
	v_and_b32_e32 v17, 0xffff0000, v86
	v_mul_f32_e32 v15, 0xbfb8aa3b, v16
	v_pk_mul_f32 v[4:5], v[10:11], v[4:5]
	v_lshlrev_b32_e32 v10, 16, v3
	v_cvt_pk_bf16_f32 v2, v4, v5
	v_lshlrev_b32_e32 v4, 16, v93
	v_and_b32_e32 v5, 0xffff0000, v93
	v_mul_f32_e32 v8, 0xbfb8aa3b, v4
	v_and_b32_e32 v11, 0xffff0000, v3
	v_mul_f32_e32 v3, 0xbfb8aa3b, v5
	v_exp_f32_e32 v8, v8
	v_exp_f32_e32 v3, v3
	v_pk_mul_f32 v[6:7], v[62:63], v[10:11]
	v_exp_f32_e32 v15, v15
	v_add_f32_e32 v8, 1.0, v8
	v_add_f32_e32 v3, 1.0, v3
	v_rcp_f32_e32 v8, v8
	v_rcp_f32_e32 v9, v3
	v_pk_mul_f32 v[6:7], v[6:7], v[4:5]
	v_add_f32_e32 v15, 1.0, v15
	v_rcp_f32_e32 v18, v15
	v_pk_mul_f32 v[4:5], v[8:9], v[6:7]
	s_nop 0
	v_cvt_pk_bf16_f32 v3, v4, v5
	global_store_dwordx4 v[12:13], v[0:3], off offset:128
	s_nop 1
	ds_read_b128 v[0:3], v14 offset:2176
	s_waitcnt lgkmcnt(0)
	v_lshlrev_b32_e32 v20, 16, v0
	v_and_b32_e32 v21, 0xffff0000, v0
	v_mul_f32_e32 v0, 0xbfb8aa3b, v17
	v_exp_f32_e32 v0, v0
	v_pk_mul_f32 v[8:9], v[48:49], v[20:21]
	v_add_f32_e32 v0, 1.0, v0
	v_rcp_f32_e32 v19, v0
	v_pk_mul_f32 v[8:9], v[8:9], v[16:17]
	s_nop 0
	v_pk_mul_f32 v[8:9], v[18:19], v[8:9]
	s_nop 0
	v_cvt_pk_bf16_f32 v0, v8, v9
	v_lshlrev_b32_e32 v8, 16, v87
	v_and_b32_e32 v9, 0xffff0000, v87
	v_mul_f32_e32 v15, 0xbfb8aa3b, v8
	v_lshlrev_b32_e32 v18, 16, v1
	v_and_b32_e32 v19, 0xffff0000, v1
	v_mul_f32_e32 v1, 0xbfb8aa3b, v9
	v_exp_f32_e32 v15, v15
	v_exp_f32_e32 v1, v1
	v_pk_mul_f32 v[10:11], v[50:51], v[18:19]
	v_add_f32_e32 v15, 1.0, v15
	v_add_f32_e32 v1, 1.0, v1
	v_rcp_f32_e32 v16, v15
	v_rcp_f32_e32 v17, v1
	v_pk_mul_f32 v[10:11], v[10:11], v[8:9]
	s_nop 0
	v_pk_mul_f32 v[8:9], v[16:17], v[10:11]
	s_nop 0
	v_cvt_pk_bf16_f32 v1, v8, v9
	v_lshlrev_b32_e32 v8, 16, v88
	v_and_b32_e32 v9, 0xffff0000, v88
	v_mul_f32_e32 v10, 0xbfb8aa3b, v8
	v_lshlrev_b32_e32 v16, 16, v2
	v_and_b32_e32 v17, 0xffff0000, v2
	v_mul_f32_e32 v2, 0xbfb8aa3b, v9
	v_exp_f32_e32 v10, v10
	v_exp_f32_e32 v2, v2
	v_pk_mul_f32 v[4:5], v[52:53], v[16:17]
	v_add_f32_e32 v10, 1.0, v10
	v_add_f32_e32 v2, 1.0, v2
	v_rcp_f32_e32 v10, v10
	v_rcp_f32_e32 v11, v2
	v_pk_mul_f32 v[4:5], v[4:5], v[8:9]
	s_nop 0
	v_pk_mul_f32 v[4:5], v[10:11], v[4:5]
	s_nop 0
	v_cvt_pk_bf16_f32 v2, v4, v5
	v_lshlrev_b32_e32 v4, 16, v89
	v_and_b32_e32 v5, 0xffff0000, v89
	v_mul_f32_e32 v8, 0xbfb8aa3b, v4
	v_lshlrev_b32_e32 v10, 16, v3
	v_and_b32_e32 v11, 0xffff0000, v3
	v_mul_f32_e32 v3, 0xbfb8aa3b, v5
	v_exp_f32_e32 v8, v8
	v_exp_f32_e32 v3, v3
	v_pk_mul_f32 v[6:7], v[54:55], v[10:11]
	v_lshlrev_b32_e32 v10, 16, v82
	v_add_f32_e32 v8, 1.0, v8
	v_add_f32_e32 v3, 1.0, v3
	v_rcp_f32_e32 v8, v8
	v_rcp_f32_e32 v9, v3
	v_pk_mul_f32 v[6:7], v[6:7], v[4:5]
	v_and_b32_e32 v11, 0xffff0000, v82
	v_mul_f32_e32 v15, 0xbfb8aa3b, v10
	v_pk_mul_f32 v[4:5], v[8:9], v[6:7]
	v_add_co_u32_e32 v8, vcc, s88, v12
	v_cvt_pk_bf16_f32 v3, v4, v5
	s_nop 0
	v_addc_co_u32_e32 v9, vcc, 0, v13, vcc
	global_store_dwordx4 v[8:9], v[0:3], off
	s_nop 1
	ds_read_b128 v[0:3], v14 offset:2304
	v_exp_f32_e32 v15, v15
	s_waitcnt lgkmcnt(0)
; #define GAS __attribute__((address_space(1)))
; #define LAS __attribute__((address_space(3)))
; __device__ __forceinline__ unsigned pk2(float lo, float hi) { const f32x2_t v = {lo, hi}; const bf16x2_t b = __builtin_convertvector(v, bf16x2_t); return __builtin_bit_cast(unsigned, b); }
; __device__ __forceinline__ float bflo(unsigned w) { return __uint_as_float(w << 16); }
; __device__ __forceinline__ float bfhi(unsigned w) { return __uint_as_float(w & 0xffff0000u); }
; __device__ __forceinline__ float sigmoidf_(float x) { return __builtin_amdgcn_rcpf(1.f + __expf(-x)); }
; template <int DK> __device__ __forceinline__ void scan_out_wave(const ScanBufs<DK>& S, int g, int h, const bf16* P, int gcol, const float* gain, bf16* Y, LAS unsigned char* W, int lane) {
;     ...
;         { char* Yu = (char*)(Y + rowt * 1024 + h * 128); const unsigned oy = (unsigned)((tl * 1024 + seg * 8) * 2);
; #pragma unroll
;           for (int j = 0; j < 8; ++j) { const int rr = 8 * (j >> 1), hf = j & 1; const v4u ow = *(const LAS v4u*)(st + (tl + rr) * P3_STP + hf * 128 + seg * 16); const v4u gw = A0.x[j];
;               const float* gn = gain + hf * 64 + seg * 8; const f32x4 n0 = *(const GAS f32x4*)gn, n1 = *(const GAS f32x4*)(gn + 4); v4u y;
; #pragma unroll
;               for (int c = 0; c < 4; ++c) { const float z0 = bflo(gw[c]), z1 = bfhi(gw[c]); const float na = c < 2 ? n0[2 * c] : n1[2 * c - 4], nb = c < 2 ? n0[2 * c + 1] : n1[2 * c - 3];
;                   y[c] = pk2(bflo(ow[c]) * na * z0 * sigmoidf_(z0), bfhi(ow[c]) * nb * z1 * sigmoidf_(z1)); }
;               *(GAS v4u*)(Yu + oy + ((size_t)rr * 1024 + hf * 64) * 2) = y; } }
	v_lshlrev_b32_e32 v22, 16, v0
	v_and_b32_e32 v23, 0xffff0000, v0
	v_mul_f32_e32 v0, 0xbfb8aa3b, v11
	v_exp_f32_e32 v0, v0
	v_add_f32_e32 v15, 1.0, v15
	v_rcp_f32_e32 v20, v15
	v_add_f32_e32 v0, 1.0, v0
	v_rcp_f32_e32 v21, v0
	v_pk_mul_f32 v[16:17], v[56:57], v[22:23]
	s_nop 0
	v_pk_mul_f32 v[16:17], v[16:17], v[10:11]
	s_nop 0
	v_pk_mul_f32 v[10:11], v[20:21], v[16:17]
	v_lshlrev_b32_e32 v20, 16, v1
	v_cvt_pk_bf16_f32 v0, v10, v11
	v_lshlrev_b32_e32 v10, 16, v83
	v_and_b32_e32 v11, 0xffff0000, v83
	v_mul_f32_e32 v15, 0xbfb8aa3b, v10
	v_and_b32_e32 v21, 0xffff0000, v1
	v_mul_f32_e32 v1, 0xbfb8aa3b, v11
	v_exp_f32_e32 v15, v15
	v_exp_f32_e32 v1, v1
	v_pk_mul_f32 v[18:19], v[58:59], v[20:21]
	v_add_f32_e32 v15, 1.0, v15
	v_add_f32_e32 v1, 1.0, v1
	v_rcp_f32_e32 v16, v15
	v_rcp_f32_e32 v17, v1
	v_pk_mul_f32 v[18:19], v[18:19], v[10:11]
	s_nop 0
	v_pk_mul_f32 v[10:11], v[16:17], v[18:19]
	s_nop 0
	v_cvt_pk_bf16_f32 v1, v10, v11
	v_lshlrev_b32_e32 v10, 16, v84
	v_and_b32_e32 v11, 0xffff0000, v84
	v_mul_f32_e32 v15, 0xbfb8aa3b, v10
	v_lshlrev_b32_e32 v18, 16, v2
	v_and_b32_e32 v19, 0xffff0000, v2
	v_mul_f32_e32 v2, 0xbfb8aa3b, v11
	v_exp_f32_e32 v15, v15
	v_exp_f32_e32 v2, v2
	v_pk_mul_f32 v[4:5], v[60:61], v[18:19]
	v_add_f32_e32 v15, 1.0, v15
	v_add_f32_e32 v2, 1.0, v2
	v_rcp_f32_e32 v16, v15
	v_rcp_f32_e32 v17, v2
	v_pk_mul_f32 v[4:5], v[4:5], v[10:11]
	s_nop 0
	v_pk_mul_f32 v[4:5], v[16:17], v[4:5]
	s_nop 0
	v_cvt_pk_bf16_f32 v2, v4, v5
	v_lshlrev_b32_e32 v4, 16, v85
	v_and_b32_e32 v5, 0xffff0000, v85
	v_mul_f32_e32 v10, 0xbfb8aa3b, v4
	v_lshlrev_b32_e32 v16, 16, v3
	v_and_b32_e32 v17, 0xffff0000, v3
	v_mul_f32_e32 v3, 0xbfb8aa3b, v5
	v_exp_f32_e32 v10, v10
	v_exp_f32_e32 v3, v3
	v_pk_mul_f32 v[6:7], v[62:63], v[16:17]
	v_lshlrev_b32_e32 v16, 16, v78
	v_add_f32_e32 v10, 1.0, v10
	v_add_f32_e32 v3, 1.0, v3
	v_rcp_f32_e32 v10, v10
	v_rcp_f32_e32 v11, v3
	v_pk_mul_f32 v[6:7], v[6:7], v[4:5]
	v_and_b32_e32 v17, 0xffff0000, v78
	v_mul_f32_e32 v15, 0xbfb8aa3b, v16
	v_pk_mul_f32 v[4:5], v[10:11], v[6:7]
	v_exp_f32_e32 v15, v15
	v_cvt_pk_bf16_f32 v3, v4, v5
	global_store_dwordx4 v[8:9], v[0:3], off offset:128
	s_nop 1
	ds_read_b128 v[0:3], v14 offset:4352
	v_add_f32_e32 v15, 1.0, v15
	v_rcp_f32_e32 v18, v15
	s_waitcnt lgkmcnt(0)
	v_lshlrev_b32_e32 v20, 16, v0
	v_and_b32_e32 v21, 0xffff0000, v0
	v_mul_f32_e32 v0, 0xbfb8aa3b, v17
	v_exp_f32_e32 v0, v0
	v_pk_mul_f32 v[8:9], v[48:49], v[20:21]
	v_add_f32_e32 v0, 1.0, v0
	v_rcp_f32_e32 v19, v0
	v_pk_mul_f32 v[8:9], v[8:9], v[16:17]
	s_nop 0
	v_pk_mul_f32 v[8:9], v[18:19], v[8:9]
	s_nop 0
	v_cvt_pk_bf16_f32 v0, v8, v9
	v_lshlrev_b32_e32 v8, 16, v79
	v_and_b32_e32 v9, 0xffff0000, v79
	v_mul_f32_e32 v15, 0xbfb8aa3b, v8
	v_lshlrev_b32_e32 v18, 16, v1
	v_and_b32_e32 v19, 0xffff0000, v1
	v_mul_f32_e32 v1, 0xbfb8aa3b, v9
	v_exp_f32_e32 v15, v15
	v_exp_f32_e32 v1, v1
	v_pk_mul_f32 v[10:11], v[50:51], v[18:19]
	v_add_f32_e32 v15, 1.0, v15
	v_add_f32_e32 v1, 1.0, v1
	v_rcp_f32_e32 v16, v15
	v_rcp_f32_e32 v17, v1
	v_pk_mul_f32 v[10:11], v[10:11], v[8:9]
	s_nop 0
	v_pk_mul_f32 v[8:9], v[16:17], v[10:11]
	s_nop 0
	v_cvt_pk_bf16_f32 v1, v8, v9
	v_lshlrev_b32_e32 v8, 16, v80
	v_and_b32_e32 v9, 0xffff0000, v80
	v_mul_f32_e32 v10, 0xbfb8aa3b, v8
	v_lshlrev_b32_e32 v16, 16, v2
	v_and_b32_e32 v17, 0xffff0000, v2
	v_mul_f32_e32 v2, 0xbfb8aa3b, v9
	v_exp_f32_e32 v10, v10
	v_exp_f32_e32 v2, v2
	v_pk_mul_f32 v[4:5], v[52:53], v[16:17]
	v_add_f32_e32 v10, 1.0, v10
	v_add_f32_e32 v2, 1.0, v2
	v_rcp_f32_e32 v10, v10
	v_rcp_f32_e32 v11, v2
	v_pk_mul_f32 v[4:5], v[4:5], v[8:9]
	s_nop 0
	v_pk_mul_f32 v[4:5], v[10:11], v[4:5]
	s_nop 0
	v_cvt_pk_bf16_f32 v2, v4, v5
	v_lshlrev_b32_e32 v4, 16, v81
	v_and_b32_e32 v5, 0xffff0000, v81
	v_mul_f32_e32 v8, 0xbfb8aa3b, v4
	v_lshlrev_b32_e32 v10, 16, v3
	v_and_b32_e32 v11, 0xffff0000, v3
	v_mul_f32_e32 v3, 0xbfb8aa3b, v5
	v_exp_f32_e32 v8, v8
	v_exp_f32_e32 v3, v3
	v_pk_mul_f32 v[6:7], v[54:55], v[10:11]
	v_lshlrev_b32_e32 v10, 16, v74
	v_add_f32_e32 v8, 1.0, v8
	v_add_f32_e32 v3, 1.0, v3
	v_rcp_f32_e32 v8, v8
	v_rcp_f32_e32 v9, v3
	v_pk_mul_f32 v[6:7], v[6:7], v[4:5]
	v_and_b32_e32 v11, 0xffff0000, v74
	v_mul_f32_e32 v15, 0xbfb8aa3b, v10
	v_pk_mul_f32 v[4:5], v[8:9], v[6:7]
	v_add_co_u32_e32 v8, vcc, s89, v12
	v_cvt_pk_bf16_f32 v3, v4, v5
	s_nop 0
	v_addc_co_u32_e32 v9, vcc, 0, v13, vcc
	global_store_dwordx4 v[8:9], v[0:3], off
	s_nop 1
	ds_read_b128 v[0:3], v14 offset:4480
	v_exp_f32_e32 v15, v15
	s_waitcnt lgkmcnt(0)
; #define GAS __attribute__((address_space(1)))
; #define LAS __attribute__((address_space(3)))
; #define LDS_WAIT() asm volatile("s_waitcnt lgkmcnt(0)" ::: "memory")
; __device__ __forceinline__ unsigned pk2(float lo, float hi) { const f32x2_t v = {lo, hi}; const bf16x2_t b = __builtin_convertvector(v, bf16x2_t); return __builtin_bit_cast(unsigned, b); }
; __device__ __forceinline__ float bflo(unsigned w) { return __uint_as_float(w << 16); }
; __device__ __forceinline__ float bfhi(unsigned w) { return __uint_as_float(w & 0xffff0000u); }
; __device__ __forceinline__ float sigmoidf_(float x) { return __builtin_amdgcn_rcpf(1.f + __expf(-x)); }
; template <int DK> __device__ __forceinline__ void scan_out_wave(const ScanBufs<DK>& S, int g, int h, const bf16* P, int gcol, const float* gain, bf16* Y, LAS unsigned char* W, int lane) {
;     ...
;         { char* Yu = (char*)(Y + rowt * 1024 + h * 128); const unsigned oy = (unsigned)((tl * 1024 + seg * 8) * 2);
; #pragma unroll
;           for (int j = 0; j < 8; ++j) { const int rr = 8 * (j >> 1), hf = j & 1; const v4u ow = *(const LAS v4u*)(st + (tl + rr) * P3_STP + hf * 128 + seg * 16); const v4u gw = A0.x[j];
;               const float* gn = gain + hf * 64 + seg * 8; const f32x4 n0 = *(const GAS f32x4*)gn, n1 = *(const GAS f32x4*)(gn + 4); v4u y;
; #pragma unroll
;               for (int c = 0; c < 4; ++c) { const float z0 = bflo(gw[c]), z1 = bfhi(gw[c]); const float na = c < 2 ? n0[2 * c] : n1[2 * c - 4], nb = c < 2 ? n0[2 * c + 1] : n1[2 * c - 3];
;                   y[c] = pk2(bflo(ow[c]) * na * z0 * sigmoidf_(z0), bfhi(ow[c]) * nb * z1 * sigmoidf_(z1)); }
;               *(GAS v4u*)(Yu + oy + ((size_t)rr * 1024 + hf * 64) * 2) = y; } }
;         LDS_WAIT();
;     }
	v_lshlrev_b32_e32 v22, 16, v0
	v_and_b32_e32 v23, 0xffff0000, v0
	v_mul_f32_e32 v0, 0xbfb8aa3b, v11
	v_exp_f32_e32 v0, v0
	v_add_f32_e32 v15, 1.0, v15
	v_rcp_f32_e32 v20, v15
	v_add_f32_e32 v0, 1.0, v0
	v_rcp_f32_e32 v21, v0
	v_pk_mul_f32 v[16:17], v[56:57], v[22:23]
	s_nop 0
	v_pk_mul_f32 v[16:17], v[16:17], v[10:11]
	s_nop 0
	v_pk_mul_f32 v[10:11], v[20:21], v[16:17]
	v_lshlrev_b32_e32 v20, 16, v1
	v_cvt_pk_bf16_f32 v0, v10, v11
	v_lshlrev_b32_e32 v10, 16, v75
	v_and_b32_e32 v11, 0xffff0000, v75
	v_mul_f32_e32 v15, 0xbfb8aa3b, v10
	v_and_b32_e32 v21, 0xffff0000, v1
	v_mul_f32_e32 v1, 0xbfb8aa3b, v11
	v_exp_f32_e32 v15, v15
	v_exp_f32_e32 v1, v1
	v_pk_mul_f32 v[18:19], v[58:59], v[20:21]
	v_add_f32_e32 v15, 1.0, v15
	v_add_f32_e32 v1, 1.0, v1
	v_rcp_f32_e32 v16, v15
	v_rcp_f32_e32 v17, v1
	v_pk_mul_f32 v[18:19], v[18:19], v[10:11]
	s_nop 0
	v_pk_mul_f32 v[10:11], v[16:17], v[18:19]
	s_nop 0
	v_cvt_pk_bf16_f32 v1, v10, v11
	v_lshlrev_b32_e32 v10, 16, v76
	v_and_b32_e32 v11, 0xffff0000, v76
	v_mul_f32_e32 v15, 0xbfb8aa3b, v10
	v_lshlrev_b32_e32 v18, 16, v2
	v_and_b32_e32 v19, 0xffff0000, v2
	v_mul_f32_e32 v2, 0xbfb8aa3b, v11
	v_exp_f32_e32 v15, v15
	v_exp_f32_e32 v2, v2
	v_pk_mul_f32 v[4:5], v[60:61], v[18:19]
	v_add_f32_e32 v15, 1.0, v15
	v_add_f32_e32 v2, 1.0, v2
	v_rcp_f32_e32 v16, v15
	v_rcp_f32_e32 v17, v2
	v_pk_mul_f32 v[4:5], v[4:5], v[10:11]
	s_nop 0
	v_pk_mul_f32 v[4:5], v[16:17], v[4:5]
	s_nop 0
	v_cvt_pk_bf16_f32 v2, v4, v5
	v_lshlrev_b32_e32 v4, 16, v77
	v_and_b32_e32 v5, 0xffff0000, v77
	v_mul_f32_e32 v10, 0xbfb8aa3b, v4
	v_lshlrev_b32_e32 v16, 16, v3
	v_and_b32_e32 v17, 0xffff0000, v3
	v_mul_f32_e32 v3, 0xbfb8aa3b, v5
	v_exp_f32_e32 v10, v10
	v_exp_f32_e32 v3, v3
	v_pk_mul_f32 v[6:7], v[62:63], v[16:17]
	v_lshlrev_b32_e32 v16, 16, v70
	v_add_f32_e32 v10, 1.0, v10
	v_add_f32_e32 v3, 1.0, v3
	v_rcp_f32_e32 v10, v10
	v_rcp_f32_e32 v11, v3
	v_pk_mul_f32 v[6:7], v[6:7], v[4:5]
	v_and_b32_e32 v17, 0xffff0000, v70
	v_mul_f32_e32 v15, 0xbfb8aa3b, v16
	v_pk_mul_f32 v[4:5], v[10:11], v[6:7]
	v_exp_f32_e32 v15, v15
	v_cvt_pk_bf16_f32 v3, v4, v5
	global_store_dwordx4 v[8:9], v[0:3], off offset:128
	s_nop 1
	ds_read_b128 v[0:3], v14 offset:6528
	v_add_f32_e32 v15, 1.0, v15
	v_rcp_f32_e32 v18, v15
	s_waitcnt lgkmcnt(0)
	v_lshlrev_b32_e32 v20, 16, v0
	v_and_b32_e32 v21, 0xffff0000, v0
	v_mul_f32_e32 v0, 0xbfb8aa3b, v17
	v_exp_f32_e32 v0, v0
	v_pk_mul_f32 v[8:9], v[48:49], v[20:21]
	v_add_f32_e32 v0, 1.0, v0
	v_rcp_f32_e32 v19, v0
	v_pk_mul_f32 v[8:9], v[8:9], v[16:17]
	s_nop 0
	v_pk_mul_f32 v[8:9], v[18:19], v[8:9]
	s_nop 0
	v_cvt_pk_bf16_f32 v0, v8, v9
	v_lshlrev_b32_e32 v8, 16, v71
	v_and_b32_e32 v9, 0xffff0000, v71
	v_mul_f32_e32 v15, 0xbfb8aa3b, v8
	v_lshlrev_b32_e32 v18, 16, v1
	v_and_b32_e32 v19, 0xffff0000, v1
	v_mul_f32_e32 v1, 0xbfb8aa3b, v9
	v_exp_f32_e32 v15, v15
	v_exp_f32_e32 v1, v1
	v_pk_mul_f32 v[10:11], v[50:51], v[18:19]
	v_add_f32_e32 v15, 1.0, v15
	v_add_f32_e32 v1, 1.0, v1
	v_rcp_f32_e32 v16, v15
	v_rcp_f32_e32 v17, v1
	v_pk_mul_f32 v[10:11], v[10:11], v[8:9]
	v_and_b32_e32 v15, 0xffff0000, v66
	v_pk_mul_f32 v[8:9], v[16:17], v[10:11]
	s_nop 0
	v_cvt_pk_bf16_f32 v1, v8, v9
	v_lshlrev_b32_e32 v8, 16, v72
	v_and_b32_e32 v9, 0xffff0000, v72
	v_mul_f32_e32 v10, 0xbfb8aa3b, v8
	v_lshlrev_b32_e32 v16, 16, v2
	v_and_b32_e32 v17, 0xffff0000, v2
	v_mul_f32_e32 v2, 0xbfb8aa3b, v9
	v_exp_f32_e32 v10, v10
	v_exp_f32_e32 v2, v2
	v_pk_mul_f32 v[4:5], v[52:53], v[16:17]
	v_add_f32_e32 v10, 1.0, v10
	v_add_f32_e32 v2, 1.0, v2
	v_rcp_f32_e32 v10, v10
	v_rcp_f32_e32 v11, v2
	v_pk_mul_f32 v[4:5], v[4:5], v[8:9]
	s_nop 0
	v_pk_mul_f32 v[4:5], v[10:11], v[4:5]
	s_nop 0
	v_cvt_pk_bf16_f32 v2, v4, v5
	v_lshlrev_b32_e32 v4, 16, v73
	v_and_b32_e32 v5, 0xffff0000, v73
	v_mul_f32_e32 v8, 0xbfb8aa3b, v4
	v_lshlrev_b32_e32 v10, 16, v3
	v_and_b32_e32 v11, 0xffff0000, v3
	v_mul_f32_e32 v3, 0xbfb8aa3b, v5
	v_exp_f32_e32 v8, v8
	v_exp_f32_e32 v3, v3
	v_pk_mul_f32 v[6:7], v[54:55], v[10:11]
	v_add_f32_e32 v8, 1.0, v8
	v_add_f32_e32 v3, 1.0, v3
	v_rcp_f32_e32 v8, v8
	v_rcp_f32_e32 v9, v3
	v_pk_mul_f32 v[6:7], v[6:7], v[4:5]
	s_nop 0
	v_pk_mul_f32 v[4:5], v[8:9], v[6:7]
	v_add_co_u32_e32 v8, vcc, s90, v12
	v_cvt_pk_bf16_f32 v3, v4, v5
	s_nop 0
	v_addc_co_u32_e32 v9, vcc, 0, v13, vcc
	global_store_dwordx4 v[8:9], v[0:3], off
	s_nop 1
	ds_read_b128 v[0:3], v14 offset:6656
	v_lshlrev_b32_e32 v14, 16, v66
	v_mul_f32_e32 v16, 0xbfb8aa3b, v14
	v_exp_f32_e32 v16, v16
	s_waitcnt lgkmcnt(0)
	v_lshlrev_b32_e32 v18, 16, v0
	v_and_b32_e32 v19, 0xffff0000, v0
	v_mul_f32_e32 v0, 0xbfb8aa3b, v15
	v_exp_f32_e32 v0, v0
	v_add_f32_e32 v16, 1.0, v16
	v_rcp_f32_e32 v16, v16
	s_and_b64 vcc, exec, s[74:75]
	v_add_f32_e32 v0, 1.0, v0
	v_rcp_f32_e32 v17, v0
	s_mov_b64 s[74:75], 0
	v_pk_mul_f32 v[10:11], v[56:57], v[18:19]
	s_nop 0
	v_pk_mul_f32 v[10:11], v[10:11], v[14:15]
	s_nop 0
	v_pk_mul_f32 v[10:11], v[16:17], v[10:11]
	v_lshlrev_b32_e32 v16, 16, v1
	v_cvt_pk_bf16_f32 v0, v10, v11
	v_lshlrev_b32_e32 v10, 16, v67
	v_and_b32_e32 v11, 0xffff0000, v67
	v_mul_f32_e32 v14, 0xbfb8aa3b, v10
	v_and_b32_e32 v17, 0xffff0000, v1
	v_mul_f32_e32 v1, 0xbfb8aa3b, v11
	v_exp_f32_e32 v14, v14
	v_exp_f32_e32 v1, v1
	v_pk_mul_f32 v[12:13], v[58:59], v[16:17]
	v_add_f32_e32 v14, 1.0, v14
	v_add_f32_e32 v1, 1.0, v1
	v_rcp_f32_e32 v14, v14
	v_rcp_f32_e32 v15, v1
	v_pk_mul_f32 v[12:13], v[12:13], v[10:11]
	s_nop 0
	v_pk_mul_f32 v[10:11], v[14:15], v[12:13]
	s_nop 0
	v_cvt_pk_bf16_f32 v1, v10, v11
	v_lshlrev_b32_e32 v10, 16, v68
	v_and_b32_e32 v11, 0xffff0000, v68
	v_mul_f32_e32 v12, 0xbfb8aa3b, v10
	v_lshlrev_b32_e32 v14, 16, v2
	v_and_b32_e32 v15, 0xffff0000, v2
	v_mul_f32_e32 v2, 0xbfb8aa3b, v11
	v_exp_f32_e32 v12, v12
	v_exp_f32_e32 v2, v2
	v_pk_mul_f32 v[4:5], v[60:61], v[14:15]
	v_add_f32_e32 v12, 1.0, v12
	v_add_f32_e32 v2, 1.0, v2
	v_rcp_f32_e32 v12, v12
	v_rcp_f32_e32 v13, v2
	v_pk_mul_f32 v[4:5], v[4:5], v[10:11]
	s_nop 0
	v_pk_mul_f32 v[4:5], v[12:13], v[4:5]
	s_nop 0
	v_cvt_pk_bf16_f32 v2, v4, v5
	v_lshlrev_b32_e32 v4, 16, v69
	v_and_b32_e32 v5, 0xffff0000, v69
	v_mul_f32_e32 v10, 0xbfb8aa3b, v4
	v_lshlrev_b32_e32 v12, 16, v3
	v_and_b32_e32 v13, 0xffff0000, v3
	v_mul_f32_e32 v3, 0xbfb8aa3b, v5
	v_exp_f32_e32 v10, v10
	v_exp_f32_e32 v3, v3
	v_pk_mul_f32 v[6:7], v[62:63], v[12:13]
	v_add_f32_e32 v10, 1.0, v10
	v_add_f32_e32 v3, 1.0, v3
	v_rcp_f32_e32 v10, v10
	v_rcp_f32_e32 v11, v3
	v_pk_mul_f32 v[6:7], v[6:7], v[4:5]
	s_nop 0
	v_pk_mul_f32 v[4:5], v[10:11], v[6:7]
	s_nop 0
	v_cvt_pk_bf16_f32 v3, v4, v5
	global_store_dwordx4 v[8:9], v[0:3], off offset:128
	s_nop 1
	s_waitcnt lgkmcnt(0)
	s_cbranch_vccnz .LBB0_1094
	s_mov_b64 s[0:1], 0

; #define P3_STEP2(st) do { P3_SLOAD(A1, (st) + 1); P3_SCOMP(A0, (st)); P3_SLOAD(A0, (st) + 2); P3_SCOMP(A1, (st) + 1); } while (0)
; template <int DK> __device__ __forceinline__ void scan_out_wave(const ScanBufs<DK>& S, int g, int h, const bf16* P, int gcol, const float* gain, bf16* Y, LAS unsigned char* W, int lane) {
;     ...
;         const int tl = lane >> 3, seg = lane & 7; const size_t rowt = row0 + 32 * tt;
;         const char* Gu = (const char*)(P + rowt * NINP + gcol + h * 128); const unsigned og = (unsigned)((tl * NINP + seg * 8) * 2);
;         struct Raw8 { v4u x[8]; }; Raw8 A0, A1;
;         constexpr int NST = 2 * (2 + NK);
;     ...
;         P3_SLOAD(A0, 0);
;         P3_STEP2(0); P3_STEP2(2); P3_STEP2(4); P3_STEP2(6); P3_STEP2(8); P3_STEP2(10);
.LBB0_1098:
	s_mov_b64 s[0:1], s[4:5]
	s_mov_b64 s[2:3], s[6:7]
	s_nop 0
	v_lshl_add_u64 v[12:13], s[0:1], 0, v[100:101]
	global_load_dwordx4 v[0:3], v[12:13], off
	global_load_dwordx4 v[4:7], v[12:13], off offset:512
	global_load_dwordx4 v[8:11], v[12:13], off offset:1024
	s_nop 0
	global_load_dwordx4 v[12:15], v[12:13], off offset:1536
	s_lshl_b32 s0, s60, 5
	v_lshl_add_u64 v[16:17], s[2:3], 0, v[100:101]
	global_load_dwordx4 v[68:71], v[16:17], off
	global_load_dwordx4 v[72:75], v[16:17], off offset:512
	global_load_dwordx4 v[76:79], v[16:17], off offset:1024
	global_load_dwordx4 v[80:83], v[16:17], off offset:1536
	s_or_b32 s0, s58, s0
	s_mul_i32 s3, s59, 0x8a00
	s_mul_hi_u32 s8, s0, 0x8a00
	s_mul_i32 s9, s0, 0x8a00
	s_add_i32 s8, s8, s3
	s_mul_i32 s2, s60, 0x2400
	s_mov_b32 s1, s59
	s_add_u32 s3, s84, s9
	s_addc_u32 s8, s85, s8
	s_add_i32 s33, s78, s2
	s_lshl_b64 s[34:35], s[0:1], 11
	s_add_u32 s0, s26, s34
	s_addc_u32 s1, s27, s35
	s_add_u32 s78, s0, s61
	s_addc_u32 s79, s1, 0
	s_add_u32 s76, s78, 32
	s_addc_u32 s77, s79, 0
	s_add_u32 s70, s78, 64
	s_addc_u32 s71, s79, 0
	s_add_u32 s68, s78, 0x60
	s_addc_u32 s69, s79, 0
	s_add_u32 s66, s78, 0x80
	s_addc_u32 s67, s79, 0
	s_add_u32 s64, s78, 0xa0
	s_addc_u32 s65, s79, 0
	s_add_u32 s62, s78, 0xc0
	s_addc_u32 s63, s79, 0
	s_add_u32 s54, s78, 0xe0
	s_addc_u32 s55, s79, 0
	s_add_u32 s52, s78, 0x1200000
	s_addc_u32 s53, s79, 0
	s_add_u32 s50, s78, 0x1200020
	s_addc_u32 s51, s79, 0
	s_add_u32 s48, s78, 0x1200040
	s_addc_u32 s49, s79, 0
	s_add_u32 s46, s78, 0x1200060
	s_addc_u32 s47, s79, 0
	s_add_u32 s44, s78, 0x1200080
	s_addc_u32 s45, s79, 0
	s_add_u32 s42, s78, 0x12000a0
	s_addc_u32 s43, s79, 0
	s_add_u32 s40, s78, 0x12000c0
	s_addc_u32 s41, s79, 0
	s_add_u32 s38, s78, 0x12000e0
	s_addc_u32 s39, s79, 0
	s_add_u32 s2, s3, s61
	s_addc_u32 s3, s8, 0
	s_add_u32 s36, s2, 0x1000
	s_addc_u32 s37, s3, 0
	s_add_u32 s18, s2, 0x1080
	s_addc_u32 s19, s3, 0
	s_add_u32 s24, s2, 0x46000
	s_addc_u32 s25, s3, 0
	s_add_u32 s0, s2, 0x46080
	s_addc_u32 s1, s3, 0
	s_add_u32 s22, s2, 0x8b000
	s_addc_u32 s23, s3, 0
	s_add_u32 s20, s2, 0x8b080
	s_addc_u32 s21, s3, 0
	s_add_u32 s16, s2, 0xd0000
	s_addc_u32 s17, s3, 0
	s_mov_b32 s60, 1
	s_add_u32 s2, s2, 0xd0080
	s_addc_u32 s3, s3, 0
	s_mov_b64 s[8:9], s[80:81]
	s_nop 0
	v_lshl_add_u64 v[16:17], s[8:9], 0, v[100:101]
	s_mov_b64 s[8:9], s[10:11]
	global_load_dwordx4 v[84:87], v[16:17], off
	global_load_dwordx4 v[88:91], v[16:17], off offset:512
	global_load_dwordx4 v[92:95], v[16:17], off offset:1024
	global_load_dwordx4 v[116:119], v[16:17], off offset:1536
	s_nop 0
	v_lshl_add_u64 v[16:17], s[8:9], 0, v[100:101]
	global_load_dwordx4 v[120:123], v[16:17], off
	global_load_dwordx4 v[124:127], v[16:17], off offset:512
	global_load_dwordx4 v[128:131], v[16:17], off offset:1024
	global_load_dwordx4 v[132:135], v[16:17], off offset:1536
	v_add3_u32 v66, s33, v110, v108
	ds_read_b128 v[136:139], v66
	s_waitcnt vmcnt(15) lgkmcnt(0)
	v_mfma_f32_32x32x16_bf16 v[48:63], v[0:3], v[136:139], 0
	s_waitcnt vmcnt(14)
	v_mfma_f32_32x32x16_bf16 v[32:47], v[4:7], v[136:139], 0
	s_waitcnt vmcnt(13)
	v_mfma_f32_32x32x16_bf16 v[16:31], v[8:11], v[136:139], 0
	s_waitcnt vmcnt(12)
	v_mfma_f32_32x32x16_bf16 v[0:15], v[12:15], v[136:139], 0
	ds_read_b128 v[136:139], v66 offset:32
	s_waitcnt vmcnt(11) lgkmcnt(0)
	v_mfma_f32_32x32x16_bf16 v[48:63], v[68:71], v[136:139], v[48:63]
	s_waitcnt vmcnt(10)
	v_mfma_f32_32x32x16_bf16 v[32:47], v[72:75], v[136:139], v[32:47]
	s_waitcnt vmcnt(9)
	v_mfma_f32_32x32x16_bf16 v[16:31], v[76:79], v[136:139], v[16:31]
	s_waitcnt vmcnt(8)
	v_mfma_f32_32x32x16_bf16 v[0:15], v[80:83], v[136:139], v[0:15]
	s_mov_b64 s[8:9], s[12:13]
	s_mov_b64 s[26:27], s[82:83]
	v_lshl_add_u64 v[80:81], s[8:9], 0, v[100:101]
	global_load_dwordx4 v[68:71], v[80:81], off
	global_load_dwordx4 v[72:75], v[80:81], off offset:512
	global_load_dwordx4 v[76:79], v[80:81], off offset:1024
	s_nop 0
	global_load_dwordx4 v[80:83], v[80:81], off offset:1536
	v_lshl_add_u64 v[96:97], s[78:79], 0, v[64:65]
	global_load_dwordx4 v[136:139], v[96:97], off
	v_lshl_add_u64 v[96:97], s[26:27], 0, v[98:99]
	global_load_dwordx4 v[140:143], v[96:97], off offset:16
	global_load_dwordx4 v[144:147], v[96:97], off
	v_readlane_b32 s78, v251, 39
	ds_read_b128 v[148:151], v66 offset:64
	s_waitcnt vmcnt(14) lgkmcnt(0)
	v_mfma_f32_32x32x16_bf16 v[48:63], v[84:87], v[148:151], v[48:63]
	ds_read_b128 v[84:87], v66 offset:96
	s_waitcnt vmcnt(13)
	v_mfma_f32_32x32x16_bf16 v[32:47], v[88:91], v[148:151], v[32:47]
	s_waitcnt vmcnt(12)
	v_mfma_f32_32x32x16_bf16 v[16:31], v[92:95], v[148:151], v[16:31]
	s_waitcnt vmcnt(11)
	v_mfma_f32_32x32x16_bf16 v[0:15], v[116:119], v[148:151], v[0:15]
	s_waitcnt vmcnt(10) lgkmcnt(0)
	v_mfma_f32_32x32x16_bf16 v[48:63], v[120:123], v[84:87], v[48:63]
	s_waitcnt vmcnt(9)
	v_mfma_f32_32x32x16_bf16 v[32:47], v[124:127], v[84:87], v[32:47]
	s_waitcnt vmcnt(8)
	v_mfma_f32_32x32x16_bf16 v[16:31], v[128:131], v[84:87], v[16:31]
	s_waitcnt vmcnt(7)
	v_mfma_f32_32x32x16_bf16 v[0:15], v[132:135], v[84:87], v[0:15]
	v_readlane_b32 s8, v245, 58
	v_readlane_b32 s9, v245, 59
	v_readlane_b32 s26, v245, 56
	v_readlane_b32 s27, v245, 57
	v_lshl_add_u64 v[96:97], s[8:9], 0, v[100:101]
	global_load_dwordx4 v[84:87], v[96:97], off
	global_load_dwordx4 v[88:91], v[96:97], off offset:512
	global_load_dwordx4 v[92:95], v[96:97], off offset:1024
	global_load_dwordx4 v[116:119], v[96:97], off offset:1536
	v_lshl_add_u64 v[96:97], s[76:77], 0, v[64:65]
	global_load_dwordx4 v[120:123], v[96:97], off
	v_lshl_add_u64 v[96:97], s[26:27], 0, v[98:99]
	global_load_dwordx4 v[124:127], v[96:97], off offset:16
	global_load_dwordx4 v[128:131], v[96:97], off
	s_waitcnt vmcnt(9)
; #define P3_STEP2(st) do { P3_SLOAD(A1, (st) + 1); P3_SCOMP(A0, (st)); P3_SLOAD(A0, (st) + 2); P3_SCOMP(A1, (st) + 1); } while (0)
; template <int DK> __device__ __forceinline__ void scan_out_wave(const ScanBufs<DK>& S, int g, int h, const bf16* P, int gcol, const float* gain, bf16* Y, LAS unsigned char* W, int lane) {
;     ...
;         P3_SLOAD(A0, 0);
;         P3_STEP2(0); P3_STEP2(2); P3_STEP2(4); P3_STEP2(6); P3_STEP2(8); P3_STEP2(10);
	v_lshlrev_b32_e32 v96, 16, v136
	v_and_b32_e32 v97, 0xffff0000, v136
	s_waitcnt vmcnt(7)
	v_pk_mul_f32 v[96:97], v[144:145], v[96:97]
	s_nop 0
	v_cvt_pk_bf16_f32 v132, v96, v97
	v_lshlrev_b32_e32 v96, 16, v137
	v_and_b32_e32 v97, 0xffff0000, v137
	v_pk_mul_f32 v[96:97], v[146:147], v[96:97]
	s_nop 0
	v_cvt_pk_bf16_f32 v133, v96, v97
	v_lshlrev_b32_e32 v96, 16, v138
	v_and_b32_e32 v97, 0xffff0000, v138
	v_pk_mul_f32 v[96:97], v[140:141], v[96:97]
	s_nop 0
	v_cvt_pk_bf16_f32 v134, v96, v97
	v_lshlrev_b32_e32 v96, 16, v139
	v_and_b32_e32 v97, 0xffff0000, v139
	v_pk_mul_f32 v[96:97], v[142:143], v[96:97]
	s_nop 0
	v_cvt_pk_bf16_f32 v135, v96, v97
	s_nop 1
	v_mfma_f32_32x32x16_bf16 v[48:63], v[68:71], v[132:135], v[48:63]
	v_mfma_f32_32x32x16_bf16 v[32:47], v[72:75], v[132:135], v[32:47]
	v_mfma_f32_32x32x16_bf16 v[16:31], v[76:79], v[132:135], v[16:31]
	v_mfma_f32_32x32x16_bf16 v[0:15], v[80:83], v[132:135], v[0:15]
	v_readlane_b32 s8, v244, 1
	v_readlane_b32 s9, v244, 2
	v_readlane_b32 s26, v244, 3
	v_readlane_b32 s27, v244, 4
	v_lshl_add_u64 v[80:81], s[8:9], 0, v[100:101]
	global_load_dwordx4 v[68:71], v[80:81], off
	global_load_dwordx4 v[72:75], v[80:81], off offset:512
	global_load_dwordx4 v[76:79], v[80:81], off offset:1024
	s_nop 0
	global_load_dwordx4 v[80:83], v[80:81], off offset:1536
	v_lshl_add_u64 v[96:97], s[70:71], 0, v[64:65]
	global_load_dwordx4 v[132:135], v[96:97], off
	v_lshl_add_u64 v[96:97], s[26:27], 0, v[98:99]
	global_load_dwordx4 v[136:139], v[96:97], off offset:16
	global_load_dwordx4 v[140:143], v[96:97], off
	s_waitcnt vmcnt(9)
	v_lshlrev_b32_e32 v96, 16, v120
	v_and_b32_e32 v97, 0xffff0000, v120
	s_waitcnt vmcnt(7)
	v_pk_mul_f32 v[96:97], v[128:129], v[96:97]
	s_nop 0
	v_cvt_pk_bf16_f32 v120, v96, v97
	v_lshlrev_b32_e32 v96, 16, v121
	v_and_b32_e32 v97, 0xffff0000, v121
	v_pk_mul_f32 v[96:97], v[130:131], v[96:97]
	s_nop 0
	v_cvt_pk_bf16_f32 v121, v96, v97
	v_lshlrev_b32_e32 v96, 16, v122
	v_and_b32_e32 v97, 0xffff0000, v122
	v_pk_mul_f32 v[96:97], v[124:125], v[96:97]
	s_nop 0
	v_cvt_pk_bf16_f32 v122, v96, v97
	v_lshlrev_b32_e32 v96, 16, v123
	v_and_b32_e32 v97, 0xffff0000, v123
	v_pk_mul_f32 v[96:97], v[126:127], v[96:97]
	s_nop 0
	v_cvt_pk_bf16_f32 v123, v96, v97
	s_nop 1
	v_mfma_f32_32x32x16_bf16 v[48:63], v[84:87], v[120:123], v[48:63]
	v_mfma_f32_32x32x16_bf16 v[32:47], v[88:91], v[120:123], v[32:47]
	v_mfma_f32_32x32x16_bf16 v[16:31], v[92:95], v[120:123], v[16:31]
	v_mfma_f32_32x32x16_bf16 v[0:15], v[116:119], v[120:123], v[0:15]
	v_readlane_b32 s8, v244, 5
	v_readlane_b32 s9, v244, 6
	v_readlane_b32 s26, v244, 7
	v_readlane_b32 s27, v244, 8
	v_lshl_add_u64 v[96:97], s[8:9], 0, v[100:101]
	global_load_dwordx4 v[84:87], v[96:97], off
	global_load_dwordx4 v[88:91], v[96:97], off offset:512
	global_load_dwordx4 v[92:95], v[96:97], off offset:1024
	global_load_dwordx4 v[116:119], v[96:97], off offset:1536
	v_lshl_add_u64 v[96:97], s[68:69], 0, v[64:65]
	global_load_dwordx4 v[120:123], v[96:97], off
	v_lshl_add_u64 v[96:97], s[26:27], 0, v[98:99]
	global_load_dwordx4 v[124:127], v[96:97], off offset:16
	global_load_dwordx4 v[128:131], v[96:97], off
	s_waitcnt vmcnt(9)
	v_lshlrev_b32_e32 v96, 16, v132
	v_and_b32_e32 v97, 0xffff0000, v132
	s_waitcnt vmcnt(7)
	v_pk_mul_f32 v[96:97], v[140:141], v[96:97]
	s_nop 0
	v_cvt_pk_bf16_f32 v132, v96, v97
	v_lshlrev_b32_e32 v96, 16, v133
	v_and_b32_e32 v97, 0xffff0000, v133
	v_pk_mul_f32 v[96:97], v[142:143], v[96:97]
	s_nop 0
	v_cvt_pk_bf16_f32 v133, v96, v97
	v_lshlrev_b32_e32 v96, 16, v134
	v_and_b32_e32 v97, 0xffff0000, v134
	v_pk_mul_f32 v[96:97], v[136:137], v[96:97]
	s_nop 0
	v_cvt_pk_bf16_f32 v134, v96, v97
	v_lshlrev_b32_e32 v96, 16, v135
	v_and_b32_e32 v97, 0xffff0000, v135
	v_pk_mul_f32 v[96:97], v[138:139], v[96:97]
	s_nop 0
	v_cvt_pk_bf16_f32 v135, v96, v97
	s_nop 1
	v_mfma_f32_32x32x16_bf16 v[48:63], v[68:71], v[132:135], v[48:63]
	v_mfma_f32_32x32x16_bf16 v[32:47], v[72:75], v[132:135], v[32:47]
	v_mfma_f32_32x32x16_bf16 v[16:31], v[76:79], v[132:135], v[16:31]
	v_mfma_f32_32x32x16_bf16 v[0:15], v[80:83], v[132:135], v[0:15]
	v_readlane_b32 s8, v244, 9
	v_readlane_b32 s9, v244, 10
	v_readlane_b32 s26, v244, 11
	v_readlane_b32 s27, v244, 12
	v_lshl_add_u64 v[80:81], s[8:9], 0, v[100:101]
	global_load_dwordx4 v[68:71], v[80:81], off
	global_load_dwordx4 v[72:75], v[80:81], off offset:512
	global_load_dwordx4 v[76:79], v[80:81], off offset:1024
	s_nop 0
	global_load_dwordx4 v[80:83], v[80:81], off offset:1536
	v_lshl_add_u64 v[96:97], s[66:67], 0, v[64:65]
	global_load_dwordx4 v[132:135], v[96:97], off
	v_lshl_add_u64 v[96:97], s[26:27], 0, v[98:99]
	global_load_dwordx4 v[136:139], v[96:97], off offset:16
	global_load_dwordx4 v[140:143], v[96:97], off
	s_waitcnt vmcnt(9)
	v_lshlrev_b32_e32 v96, 16, v120
	v_and_b32_e32 v97, 0xffff0000, v120
	s_waitcnt vmcnt(7)
	v_pk_mul_f32 v[96:97], v[128:129], v[96:97]
	s_nop 0
	v_cvt_pk_bf16_f32 v120, v96, v97
	v_lshlrev_b32_e32 v96, 16, v121
	v_and_b32_e32 v97, 0xffff0000, v121
	v_pk_mul_f32 v[96:97], v[130:131], v[96:97]
	s_nop 0
	v_cvt_pk_bf16_f32 v121, v96, v97
	v_lshlrev_b32_e32 v96, 16, v122
	v_and_b32_e32 v97, 0xffff0000, v122
	v_pk_mul_f32 v[96:97], v[124:125], v[96:97]
	s_nop 0
	v_cvt_pk_bf16_f32 v122, v96, v97
	v_lshlrev_b32_e32 v96, 16, v123
	v_and_b32_e32 v97, 0xffff0000, v123
	v_pk_mul_f32 v[96:97], v[126:127], v[96:97]
	s_nop 0
	v_cvt_pk_bf16_f32 v123, v96, v97
	s_nop 1
	v_mfma_f32_32x32x16_bf16 v[48:63], v[84:87], v[120:123], v[48:63]
	v_mfma_f32_32x32x16_bf16 v[32:47], v[88:91], v[120:123], v[32:47]
	v_mfma_f32_32x32x16_bf16 v[16:31], v[92:95], v[120:123], v[16:31]
	v_mfma_f32_32x32x16_bf16 v[0:15], v[116:119], v[120:123], v[0:15]
	v_readlane_b32 s8, v244, 13
	v_readlane_b32 s9, v244, 14
	v_readlane_b32 s26, v244, 15
	v_readlane_b32 s27, v244, 16
	v_lshl_add_u64 v[96:97], s[8:9], 0, v[100:101]
	global_load_dwordx4 v[84:87], v[96:97], off
	global_load_dwordx4 v[88:91], v[96:97], off offset:512
	global_load_dwordx4 v[92:95], v[96:97], off offset:1024
	global_load_dwordx4 v[116:119], v[96:97], off offset:1536
	v_lshl_add_u64 v[96:97], s[64:65], 0, v[64:65]
	global_load_dwordx4 v[120:123], v[96:97], off
	v_lshl_add_u64 v[96:97], s[26:27], 0, v[98:99]
	global_load_dwordx4 v[124:127], v[96:97], off offset:16
	global_load_dwordx4 v[128:131], v[96:97], off
	s_waitcnt vmcnt(9)
; #define P3_STEP2(st) do { P3_SLOAD(A1, (st) + 1); P3_SCOMP(A0, (st)); P3_SLOAD(A0, (st) + 2); P3_SCOMP(A1, (st) + 1); } while (0)
; template <int DK> __device__ __forceinline__ void scan_out_wave(const ScanBufs<DK>& S, int g, int h, const bf16* P, int gcol, const float* gain, bf16* Y, LAS unsigned char* W, int lane) {
;     ...
;         P3_SLOAD(A0, 0);
;         P3_STEP2(0); P3_STEP2(2); P3_STEP2(4); P3_STEP2(6); P3_STEP2(8); P3_STEP2(10);
	v_lshlrev_b32_e32 v96, 16, v132
	v_and_b32_e32 v97, 0xffff0000, v132
	s_waitcnt vmcnt(7)
	v_pk_mul_f32 v[96:97], v[140:141], v[96:97]
	s_nop 0
	v_cvt_pk_bf16_f32 v132, v96, v97
	v_lshlrev_b32_e32 v96, 16, v133
	v_and_b32_e32 v97, 0xffff0000, v133
	v_pk_mul_f32 v[96:97], v[142:143], v[96:97]
	s_nop 0
	v_cvt_pk_bf16_f32 v133, v96, v97
	v_lshlrev_b32_e32 v96, 16, v134
	v_and_b32_e32 v97, 0xffff0000, v134
	v_pk_mul_f32 v[96:97], v[136:137], v[96:97]
	s_nop 0
	v_cvt_pk_bf16_f32 v134, v96, v97
	v_lshlrev_b32_e32 v96, 16, v135
	v_and_b32_e32 v97, 0xffff0000, v135
	v_pk_mul_f32 v[96:97], v[138:139], v[96:97]
	s_nop 0
	v_cvt_pk_bf16_f32 v135, v96, v97
	s_nop 1
	v_mfma_f32_32x32x16_bf16 v[48:63], v[68:71], v[132:135], v[48:63]
	v_mfma_f32_32x32x16_bf16 v[32:47], v[72:75], v[132:135], v[32:47]
	v_mfma_f32_32x32x16_bf16 v[16:31], v[76:79], v[132:135], v[16:31]
	v_mfma_f32_32x32x16_bf16 v[0:15], v[80:83], v[132:135], v[0:15]
	v_readlane_b32 s8, v244, 17
	v_readlane_b32 s9, v244, 18
	v_readlane_b32 s26, v244, 19
	v_readlane_b32 s27, v244, 20
	v_lshl_add_u64 v[80:81], s[8:9], 0, v[100:101]
	global_load_dwordx4 v[68:71], v[80:81], off
	global_load_dwordx4 v[72:75], v[80:81], off offset:512
	global_load_dwordx4 v[76:79], v[80:81], off offset:1024
	s_nop 0
	global_load_dwordx4 v[80:83], v[80:81], off offset:1536
	v_lshl_add_u64 v[96:97], s[62:63], 0, v[64:65]
	global_load_dwordx4 v[132:135], v[96:97], off
	v_lshl_add_u64 v[96:97], s[26:27], 0, v[98:99]
	global_load_dwordx4 v[136:139], v[96:97], off offset:16
	global_load_dwordx4 v[140:143], v[96:97], off
	s_waitcnt vmcnt(9)
	v_lshlrev_b32_e32 v96, 16, v120
	v_and_b32_e32 v97, 0xffff0000, v120
	s_waitcnt vmcnt(7)
	v_pk_mul_f32 v[96:97], v[128:129], v[96:97]
	s_nop 0
	v_cvt_pk_bf16_f32 v120, v96, v97
	v_lshlrev_b32_e32 v96, 16, v121
	v_and_b32_e32 v97, 0xffff0000, v121
	v_pk_mul_f32 v[96:97], v[130:131], v[96:97]
	s_nop 0
	v_cvt_pk_bf16_f32 v121, v96, v97
	v_lshlrev_b32_e32 v96, 16, v122
	v_and_b32_e32 v97, 0xffff0000, v122
	v_pk_mul_f32 v[96:97], v[124:125], v[96:97]
	s_nop 0
	v_cvt_pk_bf16_f32 v122, v96, v97
	v_lshlrev_b32_e32 v96, 16, v123
	v_and_b32_e32 v97, 0xffff0000, v123
	v_pk_mul_f32 v[96:97], v[126:127], v[96:97]
	s_nop 0
	v_cvt_pk_bf16_f32 v123, v96, v97
	s_nop 1
	v_mfma_f32_32x32x16_bf16 v[48:63], v[84:87], v[120:123], v[48:63]
	v_mfma_f32_32x32x16_bf16 v[32:47], v[88:91], v[120:123], v[32:47]
	v_mfma_f32_32x32x16_bf16 v[16:31], v[92:95], v[120:123], v[16:31]
	v_mfma_f32_32x32x16_bf16 v[0:15], v[116:119], v[120:123], v[0:15]
	v_readlane_b32 s8, v244, 21
	v_readlane_b32 s9, v244, 22
	v_readlane_b32 s26, v244, 23
	v_readlane_b32 s27, v244, 24
	v_lshl_add_u64 v[96:97], s[8:9], 0, v[100:101]
	global_load_dwordx4 v[84:87], v[96:97], off
	global_load_dwordx4 v[88:91], v[96:97], off offset:512
	global_load_dwordx4 v[92:95], v[96:97], off offset:1024
	global_load_dwordx4 v[116:119], v[96:97], off offset:1536
	v_lshl_add_u64 v[96:97], s[54:55], 0, v[64:65]
	global_load_dwordx4 v[120:123], v[96:97], off
	v_lshl_add_u64 v[96:97], s[26:27], 0, v[98:99]
	global_load_dwordx4 v[124:127], v[96:97], off offset:16
	global_load_dwordx4 v[128:131], v[96:97], off
	s_waitcnt vmcnt(9)
	v_lshlrev_b32_e32 v96, 16, v132
	v_and_b32_e32 v97, 0xffff0000, v132
	s_waitcnt vmcnt(7)
	v_pk_mul_f32 v[96:97], v[140:141], v[96:97]
	s_nop 0
	v_cvt_pk_bf16_f32 v132, v96, v97
	v_lshlrev_b32_e32 v96, 16, v133
	v_and_b32_e32 v97, 0xffff0000, v133
	v_pk_mul_f32 v[96:97], v[142:143], v[96:97]
	s_nop 0
	v_cvt_pk_bf16_f32 v133, v96, v97
	v_lshlrev_b32_e32 v96, 16, v134
	v_and_b32_e32 v97, 0xffff0000, v134
	v_pk_mul_f32 v[96:97], v[136:137], v[96:97]
	s_nop 0
	v_cvt_pk_bf16_f32 v134, v96, v97
	v_lshlrev_b32_e32 v96, 16, v135
	v_and_b32_e32 v97, 0xffff0000, v135
	v_pk_mul_f32 v[96:97], v[138:139], v[96:97]
	s_nop 0
	v_cvt_pk_bf16_f32 v135, v96, v97
	s_nop 1
	v_mfma_f32_32x32x16_bf16 v[48:63], v[68:71], v[132:135], v[48:63]
	v_mfma_f32_32x32x16_bf16 v[32:47], v[72:75], v[132:135], v[32:47]
	v_mfma_f32_32x32x16_bf16 v[16:31], v[76:79], v[132:135], v[16:31]
	v_mfma_f32_32x32x16_bf16 v[0:15], v[80:83], v[132:135], v[0:15]
	s_mov_b64 s[8:9], s[4:5]
	s_nop 0
	v_lshl_add_u64 v[80:81], s[8:9], 0, v[100:101]
	s_mov_b64 s[8:9], s[6:7]
	global_load_dwordx4 v[68:71], v[80:81], off
	global_load_dwordx4 v[72:75], v[80:81], off offset:512
	global_load_dwordx4 v[76:79], v[80:81], off offset:1024
	s_nop 0
	global_load_dwordx4 v[80:83], v[80:81], off offset:1536
	s_nop 0
	v_lshl_add_u64 v[96:97], s[8:9], 0, v[100:101]
	global_load_dwordx4 v[132:135], v[96:97], off
	global_load_dwordx4 v[136:139], v[96:97], off offset:512
	global_load_dwordx4 v[140:143], v[96:97], off offset:1024
	global_load_dwordx4 v[144:147], v[96:97], off offset:1536
	s_waitcnt vmcnt(10)
	v_lshlrev_b32_e32 v96, 16, v120
	v_and_b32_e32 v97, 0xffff0000, v120
	s_waitcnt vmcnt(8)
	v_pk_mul_f32 v[96:97], v[128:129], v[96:97]
	s_nop 0
	v_cvt_pk_bf16_f32 v120, v96, v97
	v_lshlrev_b32_e32 v96, 16, v121
	v_and_b32_e32 v97, 0xffff0000, v121
	v_pk_mul_f32 v[96:97], v[130:131], v[96:97]
	s_nop 0
	v_cvt_pk_bf16_f32 v121, v96, v97
	v_lshlrev_b32_e32 v96, 16, v122
	v_and_b32_e32 v97, 0xffff0000, v122
	v_pk_mul_f32 v[96:97], v[124:125], v[96:97]
	s_nop 0
	v_cvt_pk_bf16_f32 v122, v96, v97
	v_lshlrev_b32_e32 v96, 16, v123
	v_and_b32_e32 v97, 0xffff0000, v123
	v_pk_mul_f32 v[96:97], v[126:127], v[96:97]
	s_nop 0
	v_cvt_pk_bf16_f32 v123, v96, v97
	s_nop 1
	v_mfma_f32_32x32x16_bf16 v[48:63], v[84:87], v[120:123], v[48:63]
	v_mfma_f32_32x32x16_bf16 v[32:47], v[88:91], v[120:123], v[32:47]
	v_mfma_f32_32x32x16_bf16 v[16:31], v[92:95], v[120:123], v[16:31]
	v_mfma_f32_32x32x16_bf16 v[0:15], v[116:119], v[120:123], v[0:15]
	s_mov_b64 s[8:9], s[80:81]
	s_nop 0
	v_lshl_add_u64 v[96:97], s[8:9], 0, v[100:101]
	s_mov_b64 s[8:9], s[10:11]
	global_load_dwordx4 v[84:87], v[96:97], off
	global_load_dwordx4 v[88:91], v[96:97], off offset:512
	global_load_dwordx4 v[92:95], v[96:97], off offset:1024
	global_load_dwordx4 v[116:119], v[96:97], off offset:1536
	s_nop 0
	v_lshl_add_u64 v[96:97], s[8:9], 0, v[100:101]
	global_load_dwordx4 v[120:123], v[96:97], off
	global_load_dwordx4 v[124:127], v[96:97], off offset:512
	global_load_dwordx4 v[128:131], v[96:97], off offset:1024
	global_load_dwordx4 v[148:151], v[96:97], off offset:1536
	ds_read_b128 v[152:155], v66 offset:4608
	s_waitcnt vmcnt(15) lgkmcnt(0)
; #define P3_STEP2(st) do { P3_SLOAD(A1, (st) + 1); P3_SCOMP(A0, (st)); P3_SLOAD(A0, (st) + 2); P3_SCOMP(A1, (st) + 1); } while (0)
; template <int DK> __device__ __forceinline__ void scan_out_wave(const ScanBufs<DK>& S, int g, int h, const bf16* P, int gcol, const float* gain, bf16* Y, LAS unsigned char* W, int lane) {
;     ...
;         P3_SLOAD(A0, 0);
;         P3_STEP2(0); P3_STEP2(2); P3_STEP2(4); P3_STEP2(6); P3_STEP2(8); P3_STEP2(10);
	v_mfma_f32_32x32x16_bf16 v[48:63], v[68:71], v[152:155], v[48:63]
	ds_read_b128 v[68:71], v66 offset:4640
	s_waitcnt vmcnt(14)
	v_mfma_f32_32x32x16_bf16 v[32:47], v[72:75], v[152:155], v[32:47]
	s_waitcnt vmcnt(13)
	v_mfma_f32_32x32x16_bf16 v[16:31], v[76:79], v[152:155], v[16:31]
	s_waitcnt vmcnt(12)
	v_mfma_f32_32x32x16_bf16 v[0:15], v[80:83], v[152:155], v[0:15]
	s_waitcnt vmcnt(11) lgkmcnt(0)
	v_mfma_f32_32x32x16_bf16 v[48:63], v[132:135], v[68:71], v[48:63]
	s_waitcnt vmcnt(10)
	v_mfma_f32_32x32x16_bf16 v[32:47], v[136:139], v[68:71], v[32:47]
	s_waitcnt vmcnt(9)
	v_mfma_f32_32x32x16_bf16 v[16:31], v[140:143], v[68:71], v[16:31]
	s_waitcnt vmcnt(8)
	v_mfma_f32_32x32x16_bf16 v[0:15], v[144:147], v[68:71], v[0:15]
	s_mov_b64 s[8:9], s[72:73]
	s_mov_b64 s[26:27], s[74:75]
	v_lshl_add_u64 v[80:81], s[8:9], 0, v[100:101]
	global_load_dwordx4 v[68:71], v[80:81], off
	global_load_dwordx4 v[72:75], v[80:81], off offset:512
	global_load_dwordx4 v[76:79], v[80:81], off offset:1024
	s_nop 0
	global_load_dwordx4 v[80:83], v[80:81], off offset:1536
	v_lshl_add_u64 v[96:97], s[52:53], 0, v[64:65]
	global_load_dwordx4 v[132:135], v[96:97], off
	v_lshl_add_u64 v[96:97], s[26:27], 0, v[98:99]
	global_load_dwordx4 v[136:139], v[96:97], off offset:16
	global_load_dwordx4 v[140:143], v[96:97], off
	ds_read_b128 v[144:147], v66 offset:4672
	s_waitcnt vmcnt(14) lgkmcnt(0)
	v_mfma_f32_32x32x16_bf16 v[48:63], v[84:87], v[144:147], v[48:63]
	ds_read_b128 v[84:87], v66 offset:4704
	s_waitcnt vmcnt(13)
	v_mfma_f32_32x32x16_bf16 v[32:47], v[88:91], v[144:147], v[32:47]
	s_waitcnt vmcnt(12)
	v_mfma_f32_32x32x16_bf16 v[16:31], v[92:95], v[144:147], v[16:31]
	s_waitcnt vmcnt(11)
	v_mfma_f32_32x32x16_bf16 v[0:15], v[116:119], v[144:147], v[0:15]
	s_waitcnt vmcnt(10) lgkmcnt(0)
	v_mfma_f32_32x32x16_bf16 v[48:63], v[120:123], v[84:87], v[48:63]
	s_waitcnt vmcnt(9)
	v_mfma_f32_32x32x16_bf16 v[32:47], v[124:127], v[84:87], v[32:47]
	s_waitcnt vmcnt(8)
	v_mfma_f32_32x32x16_bf16 v[16:31], v[128:131], v[84:87], v[16:31]
	s_waitcnt vmcnt(7)
	v_mfma_f32_32x32x16_bf16 v[0:15], v[148:151], v[84:87], v[0:15]
	v_readlane_b32 s8, v244, 25
	v_readlane_b32 s9, v244, 26
	v_readlane_b32 s26, v244, 27
	v_readlane_b32 s27, v244, 28
	v_lshl_add_u64 v[66:67], s[8:9], 0, v[100:101]
	global_load_dwordx4 v[84:87], v[66:67], off
	global_load_dwordx4 v[88:91], v[66:67], off offset:512
	global_load_dwordx4 v[92:95], v[66:67], off offset:1024
	global_load_dwordx4 v[116:119], v[66:67], off offset:1536
	v_lshl_add_u64 v[66:67], s[50:51], 0, v[64:65]
	global_load_dwordx4 v[120:123], v[66:67], off
	v_lshl_add_u64 v[66:67], s[26:27], 0, v[98:99]
	global_load_dwordx4 v[124:127], v[66:67], off offset:16
	global_load_dwordx4 v[128:131], v[66:67], off
	s_waitcnt vmcnt(9)
	v_lshlrev_b32_e32 v66, 16, v132
	v_and_b32_e32 v67, 0xffff0000, v132
	s_waitcnt vmcnt(7)
	v_pk_mul_f32 v[66:67], v[140:141], v[66:67]
	s_nop 0
	v_cvt_pk_bf16_f32 v132, v66, v67
	v_lshlrev_b32_e32 v66, 16, v133
	v_and_b32_e32 v67, 0xffff0000, v133
	v_pk_mul_f32 v[66:67], v[142:143], v[66:67]
	s_nop 0
	v_cvt_pk_bf16_f32 v133, v66, v67
	v_lshlrev_b32_e32 v66, 16, v134
	v_and_b32_e32 v67, 0xffff0000, v134
	v_pk_mul_f32 v[66:67], v[136:137], v[66:67]
	s_nop 0
	v_cvt_pk_bf16_f32 v134, v66, v67
	v_lshlrev_b32_e32 v66, 16, v135
	v_and_b32_e32 v67, 0xffff0000, v135
	v_pk_mul_f32 v[66:67], v[138:139], v[66:67]
	s_nop 0
	v_cvt_pk_bf16_f32 v135, v66, v67
	s_nop 1
	v_mfma_f32_32x32x16_bf16 v[48:63], v[68:71], v[132:135], v[48:63]
	v_mfma_f32_32x32x16_bf16 v[32:47], v[72:75], v[132:135], v[32:47]
	v_mfma_f32_32x32x16_bf16 v[16:31], v[76:79], v[132:135], v[16:31]
	v_mfma_f32_32x32x16_bf16 v[0:15], v[80:83], v[132:135], v[0:15]
	v_readlane_b32 s8, v244, 29
	v_readlane_b32 s9, v244, 30
	v_readlane_b32 s26, v244, 31
	v_readlane_b32 s27, v244, 32
	v_lshl_add_u64 v[78:79], s[8:9], 0, v[100:101]
	global_load_dwordx4 v[66:69], v[78:79], off
	global_load_dwordx4 v[70:73], v[78:79], off offset:512
	global_load_dwordx4 v[74:77], v[78:79], off offset:1024
	s_nop 0
	global_load_dwordx4 v[78:81], v[78:79], off offset:1536
	v_lshl_add_u64 v[82:83], s[48:49], 0, v[64:65]
	global_load_dwordx4 v[132:135], v[82:83], off
	v_lshl_add_u64 v[82:83], s[26:27], 0, v[98:99]
	global_load_dwordx4 v[136:139], v[82:83], off offset:16
	global_load_dwordx4 v[140:143], v[82:83], off
	s_waitcnt vmcnt(9)
	v_lshlrev_b32_e32 v82, 16, v120
	v_and_b32_e32 v83, 0xffff0000, v120
	s_waitcnt vmcnt(7)
	v_pk_mul_f32 v[82:83], v[128:129], v[82:83]
	s_nop 0
	v_cvt_pk_bf16_f32 v120, v82, v83
	v_lshlrev_b32_e32 v82, 16, v121
	v_and_b32_e32 v83, 0xffff0000, v121
	v_pk_mul_f32 v[82:83], v[130:131], v[82:83]
	s_nop 0
	v_cvt_pk_bf16_f32 v121, v82, v83
	v_lshlrev_b32_e32 v82, 16, v122
	v_and_b32_e32 v83, 0xffff0000, v122
	v_pk_mul_f32 v[82:83], v[124:125], v[82:83]
	s_nop 0
	v_cvt_pk_bf16_f32 v122, v82, v83
	v_lshlrev_b32_e32 v82, 16, v123
	v_and_b32_e32 v83, 0xffff0000, v123
	v_pk_mul_f32 v[82:83], v[126:127], v[82:83]
	s_nop 0
	v_cvt_pk_bf16_f32 v123, v82, v83
	s_nop 1
	v_mfma_f32_32x32x16_bf16 v[48:63], v[84:87], v[120:123], v[48:63]
	v_mfma_f32_32x32x16_bf16 v[32:47], v[88:91], v[120:123], v[32:47]
	v_mfma_f32_32x32x16_bf16 v[16:31], v[92:95], v[120:123], v[16:31]
	v_mfma_f32_32x32x16_bf16 v[0:15], v[116:119], v[120:123], v[0:15]
	v_readlane_b32 s8, v244, 33
	v_readlane_b32 s9, v244, 34
	s_mov_b64 s[26:27], s[86:87]
	s_nop 0
	v_lshl_add_u64 v[94:95], s[8:9], 0, v[100:101]
	global_load_dwordx4 v[82:85], v[94:95], off
	global_load_dwordx4 v[86:89], v[94:95], off offset:512
	global_load_dwordx4 v[90:93], v[94:95], off offset:1024
	s_nop 0
	global_load_dwordx4 v[94:97], v[94:95], off offset:1536
	v_lshl_add_u64 v[116:117], s[46:47], 0, v[64:65]
	v_lshl_add_u64 v[124:125], s[26:27], 0, v[98:99]
	global_load_dwordx4 v[116:119], v[116:117], off
	s_nop 0
	global_load_dwordx4 v[120:123], v[124:125], off offset:16
	s_nop 0
	global_load_dwordx4 v[124:127], v[124:125], off
	s_waitcnt vmcnt(9)
; #define P3_STEP2(st) do { P3_SLOAD(A1, (st) + 1); P3_SCOMP(A0, (st)); P3_SLOAD(A0, (st) + 2); P3_SCOMP(A1, (st) + 1); } while (0)
; template <int DK> __device__ __forceinline__ void scan_out_wave(const ScanBufs<DK>& S, int g, int h, const bf16* P, int gcol, const float* gain, bf16* Y, LAS unsigned char* W, int lane) {
;     ...
;         P3_SLOAD(A0, 0);
;         P3_STEP2(0); P3_STEP2(2); P3_STEP2(4); P3_STEP2(6); P3_STEP2(8); P3_STEP2(10);
	v_lshlrev_b32_e32 v128, 16, v132
	v_and_b32_e32 v129, 0xffff0000, v132
	v_lshlrev_b32_e32 v130, 16, v133
	v_and_b32_e32 v131, 0xffff0000, v133
	s_waitcnt vmcnt(7)
	v_pk_mul_f32 v[128:129], v[140:141], v[128:129]
	v_pk_mul_f32 v[130:131], v[142:143], v[130:131]
	v_cvt_pk_bf16_f32 v128, v128, v129
	v_cvt_pk_bf16_f32 v129, v130, v131
	v_lshlrev_b32_e32 v130, 16, v134
	v_and_b32_e32 v131, 0xffff0000, v134
	v_lshlrev_b32_e32 v132, 16, v135
	v_and_b32_e32 v133, 0xffff0000, v135
	v_pk_mul_f32 v[130:131], v[136:137], v[130:131]
	v_pk_mul_f32 v[132:133], v[138:139], v[132:133]
	v_cvt_pk_bf16_f32 v130, v130, v131
	v_cvt_pk_bf16_f32 v131, v132, v133
	s_nop 1
	v_mfma_f32_32x32x16_bf16 v[48:63], v[66:69], v[128:131], v[48:63]
	v_mfma_f32_32x32x16_bf16 v[32:47], v[70:73], v[128:131], v[32:47]
	v_mfma_f32_32x32x16_bf16 v[16:31], v[74:77], v[128:131], v[16:31]
	v_mfma_f32_32x32x16_bf16 v[0:15], v[78:81], v[128:131], v[0:15]
	s_mov_b64 s[8:9], s[88:89]
	s_mov_b64 s[26:27], s[90:91]
	v_lshl_add_u64 v[78:79], s[8:9], 0, v[100:101]
	global_load_dwordx4 v[66:69], v[78:79], off
	global_load_dwordx4 v[70:73], v[78:79], off offset:512
	global_load_dwordx4 v[74:77], v[78:79], off offset:1024
	s_nop 0
	global_load_dwordx4 v[78:81], v[78:79], off offset:1536
	v_lshl_add_u64 v[128:129], s[44:45], 0, v[64:65]
	v_lshl_add_u64 v[136:137], s[26:27], 0, v[98:99]
	global_load_dwordx4 v[128:131], v[128:129], off
	s_nop 0
	global_load_dwordx4 v[132:135], v[136:137], off offset:16
	s_nop 0
	global_load_dwordx4 v[136:139], v[136:137], off
	s_waitcnt vmcnt(9)
	v_lshlrev_b32_e32 v140, 16, v116
	v_and_b32_e32 v141, 0xffff0000, v116
	s_waitcnt vmcnt(7)
	v_pk_mul_f32 v[124:125], v[124:125], v[140:141]
	s_nop 0
	v_cvt_pk_bf16_f32 v116, v124, v125
	v_lshlrev_b32_e32 v124, 16, v117
	v_and_b32_e32 v125, 0xffff0000, v117
	v_pk_mul_f32 v[124:125], v[126:127], v[124:125]
	s_nop 0
	v_cvt_pk_bf16_f32 v117, v124, v125
	v_lshlrev_b32_e32 v124, 16, v118
	v_and_b32_e32 v125, 0xffff0000, v118
	v_pk_mul_f32 v[120:121], v[120:121], v[124:125]
	s_nop 0
	v_cvt_pk_bf16_f32 v118, v120, v121
	v_lshlrev_b32_e32 v120, 16, v119
	v_and_b32_e32 v121, 0xffff0000, v119
	v_pk_mul_f32 v[120:121], v[122:123], v[120:121]
	s_nop 0
	v_cvt_pk_bf16_f32 v119, v120, v121
	s_nop 1
	v_mfma_f32_32x32x16_bf16 v[48:63], v[82:85], v[116:119], v[48:63]
	v_mfma_f32_32x32x16_bf16 v[32:47], v[86:89], v[116:119], v[32:47]
	v_mfma_f32_32x32x16_bf16 v[16:31], v[90:93], v[116:119], v[16:31]
	v_mfma_f32_32x32x16_bf16 v[0:15], v[94:97], v[116:119], v[0:15]
	s_mov_b64 s[8:9], s[92:93]
	s_mov_b64 s[26:27], s[94:95]
	v_lshl_add_u64 v[94:95], s[8:9], 0, v[100:101]
	global_load_dwordx4 v[82:85], v[94:95], off
	global_load_dwordx4 v[86:89], v[94:95], off offset:512
	global_load_dwordx4 v[90:93], v[94:95], off offset:1024
	s_nop 0
	global_load_dwordx4 v[94:97], v[94:95], off offset:1536
	v_lshl_add_u64 v[116:117], s[42:43], 0, v[64:65]
	v_lshl_add_u64 v[124:125], s[26:27], 0, v[98:99]
	global_load_dwordx4 v[116:119], v[116:117], off
	s_nop 0
	global_load_dwordx4 v[120:123], v[124:125], off offset:16
	s_nop 0
	global_load_dwordx4 v[124:127], v[124:125], off
	s_waitcnt vmcnt(9)
	v_lshlrev_b32_e32 v140, 16, v128
	v_and_b32_e32 v141, 0xffff0000, v128
	s_waitcnt vmcnt(7)
	v_pk_mul_f32 v[136:137], v[136:137], v[140:141]
	s_nop 0
	v_cvt_pk_bf16_f32 v128, v136, v137
	v_lshlrev_b32_e32 v136, 16, v129
	v_and_b32_e32 v137, 0xffff0000, v129
	v_pk_mul_f32 v[136:137], v[138:139], v[136:137]
	s_nop 0
	v_cvt_pk_bf16_f32 v129, v136, v137
	v_lshlrev_b32_e32 v136, 16, v130
	v_and_b32_e32 v137, 0xffff0000, v130
	v_pk_mul_f32 v[132:133], v[132:133], v[136:137]
	s_nop 0
	v_cvt_pk_bf16_f32 v130, v132, v133
	v_lshlrev_b32_e32 v132, 16, v131
	v_and_b32_e32 v133, 0xffff0000, v131
	v_pk_mul_f32 v[132:133], v[134:135], v[132:133]
	s_nop 0
	v_cvt_pk_bf16_f32 v131, v132, v133
	s_nop 1
	v_mfma_f32_32x32x16_bf16 v[48:63], v[66:69], v[128:131], v[48:63]
	v_mfma_f32_32x32x16_bf16 v[32:47], v[70:73], v[128:131], v[32:47]
	v_mfma_f32_32x32x16_bf16 v[16:31], v[74:77], v[128:131], v[16:31]
	v_mfma_f32_32x32x16_bf16 v[0:15], v[78:81], v[128:131], v[0:15]
	s_mov_b64 s[8:9], s[96:97]
	s_mov_b64 s[26:27], s[56:57]
	v_lshl_add_u64 v[78:79], s[8:9], 0, v[100:101]
	global_load_dwordx4 v[66:69], v[78:79], off
	global_load_dwordx4 v[70:73], v[78:79], off offset:512
	global_load_dwordx4 v[74:77], v[78:79], off offset:1024
	s_nop 0
	global_load_dwordx4 v[78:81], v[78:79], off offset:1536
	v_lshl_add_u64 v[128:129], s[40:41], 0, v[64:65]
	v_lshl_add_u64 v[136:137], s[26:27], 0, v[98:99]
	global_load_dwordx4 v[128:131], v[128:129], off
	s_nop 0
	global_load_dwordx4 v[132:135], v[136:137], off offset:16
	s_nop 0
	global_load_dwordx4 v[136:139], v[136:137], off
	s_waitcnt vmcnt(9)
	v_lshlrev_b32_e32 v140, 16, v116
	v_and_b32_e32 v141, 0xffff0000, v116
	s_waitcnt vmcnt(7)
	v_pk_mul_f32 v[124:125], v[124:125], v[140:141]
	s_nop 0
	v_cvt_pk_bf16_f32 v116, v124, v125
	v_lshlrev_b32_e32 v124, 16, v117
	v_and_b32_e32 v125, 0xffff0000, v117
	v_pk_mul_f32 v[124:125], v[126:127], v[124:125]
	s_nop 0
	v_cvt_pk_bf16_f32 v117, v124, v125
	v_lshlrev_b32_e32 v124, 16, v118
	v_and_b32_e32 v125, 0xffff0000, v118
	v_pk_mul_f32 v[120:121], v[120:121], v[124:125]
	s_nop 0
	v_cvt_pk_bf16_f32 v118, v120, v121
	v_lshlrev_b32_e32 v120, 16, v119
	v_and_b32_e32 v121, 0xffff0000, v119
	v_pk_mul_f32 v[120:121], v[122:123], v[120:121]
	s_nop 0
	v_cvt_pk_bf16_f32 v119, v120, v121
	s_nop 1
	v_mfma_f32_32x32x16_bf16 v[48:63], v[82:85], v[116:119], v[48:63]
	v_mfma_f32_32x32x16_bf16 v[32:47], v[86:89], v[116:119], v[32:47]
	v_mfma_f32_32x32x16_bf16 v[16:31], v[90:93], v[116:119], v[16:31]
	v_mfma_f32_32x32x16_bf16 v[0:15], v[94:97], v[116:119], v[0:15]
	s_mov_b64 s[8:9], s[28:29]
	s_mov_b64 s[26:27], s[30:31]
	v_lshl_add_u64 v[82:83], s[8:9], 0, v[100:101]
	global_load_dwordx4 v[116:119], v[82:83], off
	global_load_dwordx4 v[120:123], v[82:83], off offset:512
	global_load_dwordx4 v[124:127], v[82:83], off offset:1024
	global_load_dwordx4 v[140:143], v[82:83], off offset:1536
	v_lshl_add_u64 v[82:83], s[38:39], 0, v[64:65]
	global_load_dwordx4 v[144:147], v[82:83], off
	v_lshl_add_u64 v[82:83], s[26:27], 0, v[98:99]
	global_load_dwordx4 v[148:151], v[82:83], off offset:16
	global_load_dwordx4 v[152:155], v[82:83], off
	v_readlane_b32 s27, v249, 40
	v_readlane_b32 s26, v249, 39
	s_waitcnt vmcnt(9)
; #define P3_STEP2(st) do { P3_SLOAD(A1, (st) + 1); P3_SCOMP(A0, (st)); P3_SLOAD(A0, (st) + 2); P3_SCOMP(A1, (st) + 1); } while (0)
; template <int DK> __device__ __forceinline__ void scan_out_wave(const ScanBufs<DK>& S, int g, int h, const bf16* P, int gcol, const float* gain, bf16* Y, LAS unsigned char* W, int lane) {
;     ...
;         P3_SLOAD(A0, 0);
;         P3_STEP2(0); P3_STEP2(2); P3_STEP2(4); P3_STEP2(6); P3_STEP2(8); P3_STEP2(10);
;         if (NK == 8) { P3_STEP2(12); P3_STEP2(14); P3_STEP2(16); P3_STEP2(18); }
;     ...
;         float ss = 0.f;
; #pragma unroll
;         for (int dvt = 0; dvt < 4; ++dvt)
; #pragma unroll
;             for (int e = 0; e < 16; ++e) ss += acc[dvt][e] * acc[dvt][e];
;         ss += __shfl_xor(ss, 32);
	v_lshlrev_b32_e32 v82, 16, v128
	v_and_b32_e32 v83, 0xffff0000, v128
	v_lshlrev_b32_e32 v84, 16, v129
	v_and_b32_e32 v85, 0xffff0000, v129
	s_waitcnt vmcnt(7)
	v_pk_mul_f32 v[82:83], v[136:137], v[82:83]
	v_pk_mul_f32 v[84:85], v[138:139], v[84:85]
	v_cvt_pk_bf16_f32 v82, v82, v83
	v_cvt_pk_bf16_f32 v83, v84, v85
	v_lshlrev_b32_e32 v84, 16, v130
	v_and_b32_e32 v85, 0xffff0000, v130
	v_lshlrev_b32_e32 v86, 16, v131
	v_and_b32_e32 v87, 0xffff0000, v131
	v_pk_mul_f32 v[84:85], v[132:133], v[84:85]
	v_pk_mul_f32 v[86:87], v[134:135], v[86:87]
	v_cvt_pk_bf16_f32 v84, v84, v85
	v_cvt_pk_bf16_f32 v85, v86, v87
	s_nop 1
	v_mfma_f32_32x32x16_bf16 v[48:63], v[66:69], v[82:85], v[48:63]
	v_mfma_f32_32x32x16_bf16 v[32:47], v[70:73], v[82:85], v[32:47]
	v_mfma_f32_32x32x16_bf16 v[16:31], v[74:77], v[82:85], v[16:31]
	v_mfma_f32_32x32x16_bf16 v[0:15], v[78:81], v[82:85], v[0:15]
	s_mov_b32 s8, 0xf800000
	v_lshl_add_u64 v[66:67], s[36:37], 0, v[102:103]
	global_load_dwordx4 v[94:97], v[66:67], off
	s_nop 0
	v_lshl_add_u64 v[66:67], s[18:19], 0, v[102:103]
	global_load_dwordx4 v[90:93], v[66:67], off
	s_nop 0
	v_lshl_add_u64 v[66:67], s[24:25], 0, v[102:103]
	global_load_dwordx4 v[86:89], v[66:67], off
	s_nop 0
	v_lshl_add_u64 v[66:67], s[0:1], 0, v[102:103]
	global_load_dwordx4 v[82:85], v[66:67], off
	s_nop 0
	v_lshl_add_u64 v[66:67], s[22:23], 0, v[102:103]
	global_load_dwordx4 v[78:81], v[66:67], off
	s_nop 0
	v_lshl_add_u64 v[66:67], s[20:21], 0, v[102:103]
	global_load_dwordx4 v[74:77], v[66:67], off
	s_nop 0
	v_lshl_add_u64 v[66:67], s[16:17], 0, v[102:103]
	global_load_dwordx4 v[70:73], v[66:67], off
	s_nop 0
	v_lshl_add_u64 v[66:67], s[2:3], 0, v[102:103]
	global_load_dwordx4 v[66:69], v[66:67], off
	s_waitcnt vmcnt(10)
	v_lshlrev_b32_e32 v128, 16, v144
	v_and_b32_e32 v129, 0xffff0000, v144
	v_lshlrev_b32_e32 v130, 16, v145
	v_and_b32_e32 v131, 0xffff0000, v145
	s_waitcnt vmcnt(8)
	v_pk_mul_f32 v[128:129], v[152:153], v[128:129]
	v_pk_mul_f32 v[130:131], v[154:155], v[130:131]
	v_cvt_pk_bf16_f32 v128, v128, v129
	v_cvt_pk_bf16_f32 v129, v130, v131
	v_lshlrev_b32_e32 v130, 16, v146
	v_and_b32_e32 v131, 0xffff0000, v146
	v_lshlrev_b32_e32 v132, 16, v147
	v_and_b32_e32 v133, 0xffff0000, v147
	v_pk_mul_f32 v[130:131], v[148:149], v[130:131]
	v_pk_mul_f32 v[132:133], v[150:151], v[132:133]
	v_cvt_pk_bf16_f32 v130, v130, v131
	v_cvt_pk_bf16_f32 v131, v132, v133
	s_nop 1
	v_mfma_f32_32x32x16_bf16 v[48:63], v[116:119], v[128:131], v[48:63]
	v_mfma_f32_32x32x16_bf16 v[32:47], v[120:123], v[128:131], v[32:47]
	v_mfma_f32_32x32x16_bf16 v[16:31], v[124:127], v[128:131], v[16:31]
	v_mfma_f32_32x32x16_bf16 v[0:15], v[140:143], v[128:131], v[0:15]
	s_nop 8
	v_mul_f32_e32 v113, v49, v49
	v_fmac_f32_e32 v113, v48, v48
	v_fmac_f32_e32 v113, v50, v50
	v_fmac_f32_e32 v113, v51, v51
	v_fmac_f32_e32 v113, v52, v52
	v_fmac_f32_e32 v113, v53, v53
	v_fmac_f32_e32 v113, v54, v54
	v_fmac_f32_e32 v113, v55, v55
	v_fmac_f32_e32 v113, v56, v56
	v_fmac_f32_e32 v113, v57, v57
	v_fmac_f32_e32 v113, v58, v58
	v_fmac_f32_e32 v113, v59, v59
	v_fmac_f32_e32 v113, v60, v60
	v_fmac_f32_e32 v113, v61, v61
	v_fmac_f32_e32 v113, v62, v62
	v_fmac_f32_e32 v113, v63, v63
	v_fmac_f32_e32 v113, v32, v32
	v_fmac_f32_e32 v113, v33, v33
	v_fmac_f32_e32 v113, v34, v34
	v_fmac_f32_e32 v113, v35, v35
	v_fmac_f32_e32 v113, v36, v36
	v_fmac_f32_e32 v113, v37, v37
	v_fmac_f32_e32 v113, v38, v38
	v_fmac_f32_e32 v113, v39, v39
	v_fmac_f32_e32 v113, v40, v40
	v_fmac_f32_e32 v113, v41, v41
	v_fmac_f32_e32 v113, v42, v42
	v_fmac_f32_e32 v113, v43, v43
	v_fmac_f32_e32 v113, v44, v44
	v_fmac_f32_e32 v113, v45, v45
	v_fmac_f32_e32 v113, v46, v46
	v_fmac_f32_e32 v113, v47, v47
	v_fmac_f32_e32 v113, v16, v16
	v_fmac_f32_e32 v113, v17, v17
	v_fmac_f32_e32 v113, v18, v18
	v_fmac_f32_e32 v113, v19, v19
	v_fmac_f32_e32 v113, v20, v20
	v_fmac_f32_e32 v113, v21, v21
	v_fmac_f32_e32 v113, v22, v22
	v_fmac_f32_e32 v113, v23, v23
	v_fmac_f32_e32 v113, v24, v24
	v_fmac_f32_e32 v113, v25, v25
	v_fmac_f32_e32 v113, v26, v26
	v_fmac_f32_e32 v113, v27, v27
	v_fmac_f32_e32 v113, v28, v28
	v_fmac_f32_e32 v113, v29, v29
	v_fmac_f32_e32 v113, v30, v30
	v_fmac_f32_e32 v113, v31, v31
	v_fmac_f32_e32 v113, v0, v0
	v_fmac_f32_e32 v113, v1, v1
	v_fmac_f32_e32 v113, v2, v2
	v_fmac_f32_e32 v113, v3, v3
	v_fmac_f32_e32 v113, v4, v4
	v_fmac_f32_e32 v113, v5, v5
	v_fmac_f32_e32 v113, v6, v6
	v_fmac_f32_e32 v113, v7, v7
	v_fmac_f32_e32 v113, v8, v8
	v_fmac_f32_e32 v113, v9, v9
	v_pk_mul_f32 v[120:121], v[10:11], v[10:11]
	v_pk_mul_f32 v[118:119], v[12:13], v[12:13]
	v_add_f32_e32 v113, v120, v113
	v_add_f32_e32 v113, v121, v113
	v_add_f32_e32 v113, v118, v113
	v_pk_mul_f32 v[116:117], v[14:15], v[14:15]
	v_add_f32_e32 v113, v119, v113
	v_add_f32_e32 v113, v116, v113
	v_and_b32_e32 v116, 64, v201
	v_xor_b32_e32 v115, 32, v201
	v_add_u32_e32 v116, 64, v116
	v_cmp_lt_i32_e32 vcc, v115, v116
	v_add_f32_e32 v113, v117, v113
	s_nop 0
	v_cndmask_b32_e32 v115, v201, v115, vcc
	v_lshlrev_b32_e32 v115, 2, v115
	ds_bpermute_b32 v115, v115, v113
	s_waitcnt lgkmcnt(0)
; #define GAS __attribute__((address_space(1)))
; #define LAS __attribute__((address_space(3)))
; #define LDS_WAIT() asm volatile("s_waitcnt lgkmcnt(0)" ::: "memory")
; __device__ __forceinline__ unsigned pk2(float lo, float hi) { const f32x2_t v = {lo, hi}; const bf16x2_t b = __builtin_convertvector(v, bf16x2_t); return __builtin_bit_cast(unsigned, b); }
; __device__ __forceinline__ float bflo(unsigned w) { return __uint_as_float(w << 16); }
; __device__ __forceinline__ float bfhi(unsigned w) { return __uint_as_float(w & 0xffff0000u); }
; __device__ __forceinline__ float sigmoidf_(float x) { return __builtin_amdgcn_rcpf(1.f + __expf(-x)); }
; template <int DK> __device__ __forceinline__ void scan_out_wave(const ScanBufs<DK>& S, int g, int h, const bf16* P, int gcol, const float* gain, bf16* Y, LAS unsigned char* W, int lane) {
;     ...
;         const float rstd = 1.0f / sqrtf(ss * (1.f / 128.f) + RMS_EPS);
;         LAS unsigned char* st = W + (size_t)tt * 2 * 32 * P3_ALP;
; #pragma unroll
;         for (int dvt = 0; dvt < 4; ++dvt)
; #pragma unroll
;             for (int q = 0; q < 4; ++q) { v2u o; o.x = pk2(acc[dvt][4 * q] * rstd, acc[dvt][4 * q + 1] * rstd); o.y = pk2(acc[dvt][4 * q + 2] * rstd, acc[dvt][4 * q + 3] * rstd); *(LAS v2u*)(st + r * P3_STP + (32 * dvt + 8 * q + 4 * hi) * 2) = o; }
;         LDS_WAIT();
;         { char* Yu = (char*)(Y + rowt * 1024 + h * 128); const unsigned oy = (unsigned)((tl * 1024 + seg * 8) * 2);
; #pragma unroll
;           for (int j = 0; j < 8; ++j) { const int rr = 8 * (j >> 1), hf = j & 1; const v4u ow = *(const LAS v4u*)(st + (tl + rr) * P3_STP + hf * 128 + seg * 16); const v4u gw = A0.x[j];
;               const float* gn = gain + hf * 64 + seg * 8; const f32x4 n0 = *(const GAS f32x4*)gn, n1 = *(const GAS f32x4*)(gn + 4); v4u y;
; #pragma unroll
;               for (int c = 0; c < 4; ++c) { const float z0 = bflo(gw[c]), z1 = bfhi(gw[c]); const float na = c < 2 ? n0[2 * c] : n1[2 * c - 4], nb = c < 2 ? n0[2 * c + 1] : n1[2 * c - 3];
;                   y[c] = pk2(bflo(ow[c]) * na * z0 * sigmoidf_(z0), bfhi(ow[c]) * nb * z1 * sigmoidf_(z1)); }
;               *(GAS v4u*)(Yu + oy + ((size_t)rr * 1024 + hf * 64) * 2) = y; } }
	v_add_f32_e32 v113, v113, v115
	v_fmamk_f32 v113, v113, 0x3c000000, v202
	v_mul_f32_e32 v115, 0x4f800000, v113
	v_cmp_gt_f32_e32 vcc, s8, v113
	s_nop 1
	v_cndmask_b32_e32 v113, v113, v115, vcc
	v_sqrt_f32_e32 v115, v113
	s_nop 0
	v_add_u32_e32 v116, -1, v115
	v_fma_f32 v117, -v116, v115, v113
	v_cmp_ge_f32_e64 s[2:3], 0, v117
	v_add_u32_e32 v117, 1, v115
	s_nop 0
	v_cndmask_b32_e64 v116, v115, v116, s[2:3]
	v_fma_f32 v115, -v117, v115, v113
	v_cmp_lt_f32_e64 s[2:3], 0, v115
	s_nop 1
	v_cndmask_b32_e64 v115, v116, v117, s[2:3]
	v_mul_f32_e32 v116, 0x37800000, v115
	v_cndmask_b32_e32 v115, v115, v116, vcc
	v_cmp_class_f32_e32 vcc, v113, v203
	s_mov_b32 s2, 0xc000
	s_nop 0
	v_cndmask_b32_e32 v113, v115, v113, vcc
	v_div_scale_f32 v115, s[0:1], v113, v113, 1.0
	v_rcp_f32_e32 v116, v115
	s_movk_i32 s1, 0x4000
	s_mov_b32 s0, 0x8000
	v_fma_f32 v117, -v115, v116, 1.0
	v_fmac_f32_e32 v116, v117, v116
	v_div_scale_f32 v117, vcc, 1.0, v113, 1.0
	v_mul_f32_e32 v118, v117, v116
	v_fma_f32 v119, -v115, v118, v117
	v_fmac_f32_e32 v118, v119, v116
	v_fma_f32 v115, -v115, v118, v117
	v_div_fmas_f32 v115, v115, v116, v118
	v_div_fixup_f32 v116, v115, v113, 1.0
	v_pk_mul_f32 v[48:49], v[48:49], v[116:117] op_sel_hi:[1,0]
	v_pk_mul_f32 v[50:51], v[50:51], v[116:117] op_sel_hi:[1,0]
	v_pk_mul_f32 v[32:33], v[32:33], v[116:117] op_sel_hi:[1,0]
	v_pk_mul_f32 v[34:35], v[34:35], v[116:117] op_sel_hi:[1,0]
	v_pk_mul_f32 v[16:17], v[16:17], v[116:117] op_sel_hi:[1,0]
	v_pk_mul_f32 v[18:19], v[18:19], v[116:117] op_sel_hi:[1,0]
	v_pk_mul_f32 v[0:1], v[0:1], v[116:117] op_sel_hi:[1,0]
	v_pk_mul_f32 v[2:3], v[2:3], v[116:117] op_sel_hi:[1,0]
	v_cvt_pk_bf16_f32 v48, v48, v49
	v_cvt_pk_bf16_f32 v49, v50, v51
	v_pk_mul_f32 v[50:51], v[52:53], v[116:117] op_sel_hi:[1,0]
	v_pk_mul_f32 v[52:53], v[54:55], v[116:117] op_sel_hi:[1,0]
	v_cvt_pk_bf16_f32 v32, v32, v33
	v_cvt_pk_bf16_f32 v33, v34, v35
	v_pk_mul_f32 v[34:35], v[36:37], v[116:117] op_sel_hi:[1,0]
	v_pk_mul_f32 v[36:37], v[38:39], v[116:117] op_sel_hi:[1,0]
	v_cvt_pk_bf16_f32 v16, v16, v17
	v_cvt_pk_bf16_f32 v17, v18, v19
	v_pk_mul_f32 v[18:19], v[20:21], v[116:117] op_sel_hi:[1,0]
	v_pk_mul_f32 v[20:21], v[22:23], v[116:117] op_sel_hi:[1,0]
	v_cvt_pk_bf16_f32 v0, v0, v1
	v_cvt_pk_bf16_f32 v1, v2, v3
	v_pk_mul_f32 v[2:3], v[4:5], v[116:117] op_sel_hi:[1,0]
	v_pk_mul_f32 v[4:5], v[6:7], v[116:117] op_sel_hi:[1,0]
	v_add3_u32 v113, s33, v111, v109
	v_cvt_pk_bf16_f32 v50, v50, v51
	v_cvt_pk_bf16_f32 v51, v52, v53
	v_cvt_pk_bf16_f32 v34, v34, v35
	v_cvt_pk_bf16_f32 v35, v36, v37
	v_cvt_pk_bf16_f32 v18, v18, v19
	v_cvt_pk_bf16_f32 v19, v20, v21
	v_cvt_pk_bf16_f32 v2, v2, v3
	v_cvt_pk_bf16_f32 v3, v4, v5
	ds_write2_b64 v113, v[48:49], v[50:51] offset1:2
	v_pk_mul_f32 v[48:49], v[56:57], v[116:117] op_sel_hi:[1,0]
	v_pk_mul_f32 v[50:51], v[58:59], v[116:117] op_sel_hi:[1,0]
	ds_write2_b64 v113, v[32:33], v[34:35] offset0:8 offset1:10
	v_pk_mul_f32 v[32:33], v[40:41], v[116:117] op_sel_hi:[1,0]
	v_pk_mul_f32 v[34:35], v[42:43], v[116:117] op_sel_hi:[1,0]
	ds_write2_b64 v113, v[16:17], v[18:19] offset0:16 offset1:18
	v_pk_mul_f32 v[16:17], v[24:25], v[116:117] op_sel_hi:[1,0]
	v_pk_mul_f32 v[18:19], v[26:27], v[116:117] op_sel_hi:[1,0]
	ds_write2_b64 v113, v[0:1], v[2:3] offset0:24 offset1:26
	v_pk_mul_f32 v[0:1], v[8:9], v[116:117] op_sel_hi:[1,0]
	v_pk_mul_f32 v[2:3], v[10:11], v[116:117] op_sel_hi:[1,0]
	v_cvt_pk_bf16_f32 v48, v48, v49
	v_cvt_pk_bf16_f32 v49, v50, v51
	v_pk_mul_f32 v[50:51], v[60:61], v[116:117] op_sel_hi:[1,0]
	v_pk_mul_f32 v[52:53], v[62:63], v[116:117] op_sel_hi:[1,0]
	v_cvt_pk_bf16_f32 v32, v32, v33
	v_cvt_pk_bf16_f32 v33, v34, v35
	v_pk_mul_f32 v[34:35], v[44:45], v[116:117] op_sel_hi:[1,0]
	v_pk_mul_f32 v[36:37], v[46:47], v[116:117] op_sel_hi:[1,0]
	v_cvt_pk_bf16_f32 v16, v16, v17
	v_cvt_pk_bf16_f32 v17, v18, v19
	v_pk_mul_f32 v[18:19], v[28:29], v[116:117] op_sel_hi:[1,0]
	v_pk_mul_f32 v[20:21], v[30:31], v[116:117] op_sel_hi:[1,0]
	v_cvt_pk_bf16_f32 v0, v0, v1
	v_cvt_pk_bf16_f32 v1, v2, v3
	v_pk_mul_f32 v[2:3], v[12:13], v[116:117] op_sel_hi:[1,0]
	v_pk_mul_f32 v[4:5], v[14:15], v[116:117] op_sel_hi:[1,0]
	v_cvt_pk_bf16_f32 v50, v50, v51
	v_cvt_pk_bf16_f32 v51, v52, v53
	v_cvt_pk_bf16_f32 v34, v34, v35
	v_cvt_pk_bf16_f32 v35, v36, v37
	v_cvt_pk_bf16_f32 v18, v18, v19
	v_cvt_pk_bf16_f32 v19, v20, v21
	v_cvt_pk_bf16_f32 v2, v2, v3
	v_cvt_pk_bf16_f32 v3, v4, v5
	ds_write2_b64 v113, v[48:49], v[50:51] offset0:4 offset1:6
	ds_write2_b64 v113, v[32:33], v[34:35] offset0:12 offset1:14
	ds_write2_b64 v113, v[16:17], v[18:19] offset0:20 offset1:22
	ds_write2_b64 v113, v[0:1], v[2:3] offset0:28 offset1:30
	s_waitcnt lgkmcnt(0)
	global_load_dwordx4 v[48:51], v[104:105], off
	global_load_dwordx4 v[52:55], v[104:105], off offset:16
	global_load_dwordx4 v[56:59], v[104:105], off offset:256
	global_load_dwordx4 v[60:63], v[104:105], off offset:272
	s_waitcnt vmcnt(0)
	v_lshlrev_b32_e32 v20, 16, v94
	v_and_b32_e32 v21, 0xffff0000, v94
	v_mul_f32_e32 v0, 0xbfb8aa3b, v20
	v_mul_f32_e32 v1, 0xbfb8aa3b, v21
	v_exp_f32_e32 v0, v0
	v_add3_u32 v6, s33, v112, v114
	v_exp_f32_e32 v7, v1
	ds_read_b128 v[16:19], v6
	v_add_f32_e32 v0, 1.0, v0
	v_rcp_f32_e32 v22, v0
	v_add_f32_e32 v7, 1.0, v7
	v_rcp_f32_e32 v23, v7
	ds_read_b128 v[0:3], v6 offset:128
	s_waitcnt lgkmcnt(1)
; #define GAS __attribute__((address_space(1)))
; #define LAS __attribute__((address_space(3)))
; __device__ __forceinline__ unsigned pk2(float lo, float hi) { const f32x2_t v = {lo, hi}; const bf16x2_t b = __builtin_convertvector(v, bf16x2_t); return __builtin_bit_cast(unsigned, b); }
; __device__ __forceinline__ float bflo(unsigned w) { return __uint_as_float(w << 16); }
; __device__ __forceinline__ float bfhi(unsigned w) { return __uint_as_float(w & 0xffff0000u); }
; __device__ __forceinline__ float sigmoidf_(float x) { return __builtin_amdgcn_rcpf(1.f + __expf(-x)); }
; template <int DK> __device__ __forceinline__ void scan_out_wave(const ScanBufs<DK>& S, int g, int h, const bf16* P, int gcol, const float* gain, bf16* Y, LAS unsigned char* W, int lane) {
;     ...
;         { char* Yu = (char*)(Y + rowt * 1024 + h * 128); const unsigned oy = (unsigned)((tl * 1024 + seg * 8) * 2);
; #pragma unroll
;           for (int j = 0; j < 8; ++j) { const int rr = 8 * (j >> 1), hf = j & 1; const v4u ow = *(const LAS v4u*)(st + (tl + rr) * P3_STP + hf * 128 + seg * 16); const v4u gw = A0.x[j];
;               const float* gn = gain + hf * 64 + seg * 8; const f32x4 n0 = *(const GAS f32x4*)gn, n1 = *(const GAS f32x4*)(gn + 4); v4u y;
; #pragma unroll
;               for (int c = 0; c < 4; ++c) { const float z0 = bflo(gw[c]), z1 = bfhi(gw[c]); const float na = c < 2 ? n0[2 * c] : n1[2 * c - 4], nb = c < 2 ? n0[2 * c + 1] : n1[2 * c - 3];
;                   y[c] = pk2(bflo(ow[c]) * na * z0 * sigmoidf_(z0), bfhi(ow[c]) * nb * z1 * sigmoidf_(z1)); }
;               *(GAS v4u*)(Yu + oy + ((size_t)rr * 1024 + hf * 64) * 2) = y; } }
	v_lshlrev_b32_e32 v24, 16, v16
	v_and_b32_e32 v25, 0xffff0000, v16
	v_lshlrev_b32_e32 v16, 16, v17
	v_and_b32_e32 v17, 0xffff0000, v17
	v_lshl_add_u64 v[4:5], v[106:107], 0, s[34:35]
	v_pk_mul_f32 v[8:9], v[48:49], v[24:25]
	s_nop 0
	v_pk_mul_f32 v[8:9], v[8:9], v[20:21]
	v_lshlrev_b32_e32 v20, 16, v95
	v_pk_mul_f32 v[8:9], v[22:23], v[8:9]
	v_mul_f32_e32 v7, 0xbfb8aa3b, v20
	v_and_b32_e32 v21, 0xffff0000, v95
	v_cvt_pk_bf16_f32 v8, v8, v9
	v_exp_f32_e32 v7, v7
	v_mul_f32_e32 v9, 0xbfb8aa3b, v21
	v_exp_f32_e32 v9, v9
	v_pk_mul_f32 v[10:11], v[50:51], v[16:17]
	v_add_f32_e32 v7, 1.0, v7
	v_rcp_f32_e32 v22, v7
	v_add_f32_e32 v7, 1.0, v9
	v_rcp_f32_e32 v23, v7
	v_pk_mul_f32 v[10:11], v[10:11], v[20:21]
	v_lshlrev_b32_e32 v20, 16, v18
	v_and_b32_e32 v21, 0xffff0000, v18
	v_pk_mul_f32 v[10:11], v[22:23], v[10:11]
	v_pk_mul_f32 v[12:13], v[52:53], v[20:21]
	v_cvt_pk_bf16_f32 v9, v10, v11
	v_lshlrev_b32_e32 v10, 16, v96
	v_mul_f32_e32 v7, 0xbfb8aa3b, v10
	v_and_b32_e32 v11, 0xffff0000, v96
	v_exp_f32_e32 v7, v7
	v_mul_f32_e32 v16, 0xbfb8aa3b, v11
	v_exp_f32_e32 v17, v16
	v_pk_mul_f32 v[10:11], v[12:13], v[10:11]
	v_add_f32_e32 v7, 1.0, v7
	v_rcp_f32_e32 v16, v7
	v_add_f32_e32 v7, 1.0, v17
	v_rcp_f32_e32 v17, v7
	v_lshlrev_b32_e32 v12, 16, v97
	v_mul_f32_e32 v7, 0xbfb8aa3b, v12
	v_and_b32_e32 v13, 0xffff0000, v97
	v_pk_mul_f32 v[10:11], v[16:17], v[10:11]
	v_exp_f32_e32 v7, v7
	v_cvt_pk_bf16_f32 v10, v10, v11
	v_mul_f32_e32 v11, 0xbfb8aa3b, v13
	v_exp_f32_e32 v11, v11
	v_add_f32_e32 v7, 1.0, v7
	v_rcp_f32_e32 v16, v7
	v_lshlrev_b32_e32 v18, 16, v19
	v_add_f32_e32 v7, 1.0, v11
	v_rcp_f32_e32 v17, v7
	v_and_b32_e32 v19, 0xffff0000, v19
	v_pk_mul_f32 v[14:15], v[54:55], v[18:19]
	s_waitcnt lgkmcnt(0)
	v_lshlrev_b32_e32 v22, 16, v0
	v_pk_mul_f32 v[12:13], v[14:15], v[12:13]
	v_and_b32_e32 v23, 0xffff0000, v0
	v_pk_mul_f32 v[12:13], v[16:17], v[12:13]
	v_lshlrev_b32_e32 v16, 16, v90
	v_cvt_pk_bf16_f32 v11, v12, v13
	global_store_dwordx4 v[4:5], v[8:11], off
	s_nop 1
	s_nop 0
	v_and_b32_e32 v17, 0xffff0000, v90
	v_mul_f32_e32 v7, 0xbfb8aa3b, v16
	v_mul_f32_e32 v18, 0xbfb8aa3b, v17
	v_exp_f32_e32 v7, v7
	v_exp_f32_e32 v19, v18
	v_lshlrev_b32_e32 v18, 16, v91
	v_lshlrev_b32_e32 v24, 16, v88
	v_add_f32_e32 v7, 1.0, v7
	v_add_f32_e32 v19, 1.0, v19
	v_rcp_f32_e32 v20, v7
	v_rcp_f32_e32 v21, v19
	v_mul_f32_e32 v7, 0xbfb8aa3b, v18
	v_and_b32_e32 v19, 0xffff0000, v91
	v_exp_f32_e32 v7, v7
	v_and_b32_e32 v25, 0xffff0000, v88
	v_add_f32_e32 v7, 1.0, v7
	v_pk_mul_f32 v[8:9], v[56:57], v[22:23]
	s_nop 0
	v_pk_mul_f32 v[8:9], v[8:9], v[16:17]
	v_lshlrev_b32_e32 v16, 16, v1
	v_pk_mul_f32 v[8:9], v[20:21], v[8:9]
	v_and_b32_e32 v17, 0xffff0000, v1
	v_cvt_pk_bf16_f32 v0, v8, v9
	v_mul_f32_e32 v8, 0xbfb8aa3b, v19
	v_exp_f32_e32 v9, v8
	v_rcp_f32_e32 v8, v7
	v_pk_mul_f32 v[10:11], v[58:59], v[16:17]
	v_lshlrev_b32_e32 v16, 16, v2
	v_add_f32_e32 v7, 1.0, v9
	v_rcp_f32_e32 v9, v7
	v_pk_mul_f32 v[10:11], v[10:11], v[18:19]
	v_and_b32_e32 v17, 0xffff0000, v2
	v_pk_mul_f32 v[12:13], v[60:61], v[16:17]
	v_pk_mul_f32 v[8:9], v[8:9], v[10:11]
	v_lshlrev_b32_e32 v20, 16, v86
	v_cvt_pk_bf16_f32 v1, v8, v9
	v_lshlrev_b32_e32 v8, 16, v92
	v_mul_f32_e32 v7, 0xbfb8aa3b, v8
	v_and_b32_e32 v9, 0xffff0000, v92
	v_exp_f32_e32 v7, v7
	v_mul_f32_e32 v10, 0xbfb8aa3b, v9
	v_exp_f32_e32 v11, v10
	v_pk_mul_f32 v[8:9], v[12:13], v[8:9]
	v_add_f32_e32 v7, 1.0, v7
	v_rcp_f32_e32 v10, v7
	v_add_f32_e32 v7, 1.0, v11
	v_rcp_f32_e32 v11, v7
	v_lshlrev_b32_e32 v12, 16, v3
	v_and_b32_e32 v13, 0xffff0000, v3
	v_pk_mul_f32 v[12:13], v[62:63], v[12:13]
	v_pk_mul_f32 v[8:9], v[10:11], v[8:9]
	v_and_b32_e32 v21, 0xffff0000, v86
	v_cvt_pk_bf16_f32 v2, v8, v9
	v_lshlrev_b32_e32 v8, 16, v93
	v_mul_f32_e32 v7, 0xbfb8aa3b, v8
	v_and_b32_e32 v9, 0xffff0000, v93
	v_exp_f32_e32 v7, v7
	v_mul_f32_e32 v10, 0xbfb8aa3b, v9
	v_exp_f32_e32 v11, v10
	v_pk_mul_f32 v[8:9], v[12:13], v[8:9]
	v_add_f32_e32 v7, 1.0, v7
	v_rcp_f32_e32 v10, v7
	v_add_f32_e32 v7, 1.0, v11
	v_rcp_f32_e32 v11, v7
	v_lshlrev_b32_e32 v22, 16, v87
	v_and_b32_e32 v23, 0xffff0000, v87
	v_mul_f32_e32 v7, 0xbfb8aa3b, v24
	v_pk_mul_f32 v[8:9], v[10:11], v[8:9]
	v_exp_f32_e32 v7, v7
	v_cvt_pk_bf16_f32 v3, v8, v9
	global_store_dwordx4 v[4:5], v[0:3], off offset:128
	s_nop 1
	v_mul_f32_e32 v0, 0xbfb8aa3b, v20
	v_mul_f32_e32 v1, 0xbfb8aa3b, v21
	v_mul_f32_e32 v2, 0xbfb8aa3b, v22
	v_mul_f32_e32 v3, 0xbfb8aa3b, v23
	v_exp_f32_e32 v0, v0
	v_exp_f32_e32 v1, v1
	v_exp_f32_e32 v2, v2
	v_exp_f32_e32 v3, v3
	ds_read_b128 v[16:19], v6 offset:2176
	v_add_f32_e32 v0, 1.0, v0
	v_add_f32_e32 v1, 1.0, v1
	v_add_f32_e32 v2, 1.0, v2
	v_add_f32_e32 v3, 1.0, v3
	v_rcp_f32_e32 v26, v0
	v_rcp_f32_e32 v27, v1
	v_rcp_f32_e32 v28, v2
	v_rcp_f32_e32 v29, v3
	ds_read_b128 v[0:3], v6 offset:2304
	s_waitcnt lgkmcnt(1)
; #define GAS __attribute__((address_space(1)))
; #define LAS __attribute__((address_space(3)))
; __device__ __forceinline__ unsigned pk2(float lo, float hi) { const f32x2_t v = {lo, hi}; const bf16x2_t b = __builtin_convertvector(v, bf16x2_t); return __builtin_bit_cast(unsigned, b); }
; __device__ __forceinline__ float bflo(unsigned w) { return __uint_as_float(w << 16); }
; __device__ __forceinline__ float bfhi(unsigned w) { return __uint_as_float(w & 0xffff0000u); }
; __device__ __forceinline__ float sigmoidf_(float x) { return __builtin_amdgcn_rcpf(1.f + __expf(-x)); }
; template <int DK> __device__ __forceinline__ void scan_out_wave(const ScanBufs<DK>& S, int g, int h, const bf16* P, int gcol, const float* gain, bf16* Y, LAS unsigned char* W, int lane) {
;     ...
;         { char* Yu = (char*)(Y + rowt * 1024 + h * 128); const unsigned oy = (unsigned)((tl * 1024 + seg * 8) * 2);
; #pragma unroll
;           for (int j = 0; j < 8; ++j) { const int rr = 8 * (j >> 1), hf = j & 1; const v4u ow = *(const LAS v4u*)(st + (tl + rr) * P3_STP + hf * 128 + seg * 16); const v4u gw = A0.x[j];
;               const float* gn = gain + hf * 64 + seg * 8; const f32x4 n0 = *(const GAS f32x4*)gn, n1 = *(const GAS f32x4*)(gn + 4); v4u y;
; #pragma unroll
;               for (int c = 0; c < 4; ++c) { const float z0 = bflo(gw[c]), z1 = bfhi(gw[c]); const float na = c < 2 ? n0[2 * c] : n1[2 * c - 4], nb = c < 2 ? n0[2 * c + 1] : n1[2 * c - 3];
;                   y[c] = pk2(bflo(ow[c]) * na * z0 * sigmoidf_(z0), bfhi(ow[c]) * nb * z1 * sigmoidf_(z1)); }
;               *(GAS v4u*)(Yu + oy + ((size_t)rr * 1024 + hf * 64) * 2) = y; } }
	v_lshlrev_b32_e32 v30, 16, v16
	v_and_b32_e32 v31, 0xffff0000, v16
	v_lshlrev_b32_e32 v16, 16, v17
	v_and_b32_e32 v17, 0xffff0000, v17
	v_add_f32_e32 v7, 1.0, v7
	v_pk_mul_f32 v[8:9], v[48:49], v[30:31]
	v_pk_mul_f32 v[10:11], v[50:51], v[16:17]
	v_pk_mul_f32 v[8:9], v[8:9], v[20:21]
	v_pk_mul_f32 v[10:11], v[10:11], v[22:23]
	v_pk_mul_f32 v[8:9], v[26:27], v[8:9]
	v_pk_mul_f32 v[10:11], v[28:29], v[10:11]
	v_cvt_pk_bf16_f32 v8, v8, v9
	v_cvt_pk_bf16_f32 v9, v10, v11
	v_mul_f32_e32 v10, 0xbfb8aa3b, v25
	v_exp_f32_e32 v11, v10
	v_rcp_f32_e32 v10, v7
	v_lshlrev_b32_e32 v16, 16, v18
	v_and_b32_e32 v17, 0xffff0000, v18
	v_add_f32_e32 v7, 1.0, v11
	v_rcp_f32_e32 v11, v7
	v_pk_mul_f32 v[12:13], v[52:53], v[16:17]
	v_lshlrev_b32_e32 v18, 16, v19
	v_pk_mul_f32 v[12:13], v[12:13], v[24:25]
	v_and_b32_e32 v19, 0xffff0000, v19
	v_pk_mul_f32 v[10:11], v[10:11], v[12:13]
	v_lshlrev_b32_e32 v12, 16, v89
	v_mul_f32_e32 v7, 0xbfb8aa3b, v12
	v_and_b32_e32 v13, 0xffff0000, v89
	v_cvt_pk_bf16_f32 v10, v10, v11
	v_exp_f32_e32 v7, v7
	v_mul_f32_e32 v11, 0xbfb8aa3b, v13
	v_exp_f32_e32 v11, v11
	v_pk_mul_f32 v[14:15], v[54:55], v[18:19]
	v_add_f32_e32 v7, 1.0, v7
	v_rcp_f32_e32 v16, v7
	v_add_f32_e32 v7, 1.0, v11
	v_rcp_f32_e32 v17, v7
	v_pk_mul_f32 v[12:13], v[14:15], v[12:13]
	v_lshlrev_b32_e32 v18, 16, v82
	v_and_b32_e32 v19, 0xffff0000, v82
	v_pk_mul_f32 v[12:13], v[16:17], v[12:13]
	v_add_co_u32_e32 v16, vcc, s1, v4
	v_cvt_pk_bf16_f32 v11, v12, v13
	s_nop 0
	v_addc_co_u32_e32 v17, vcc, 0, v5, vcc
	global_store_dwordx4 v[16:17], v[8:11], off
	s_nop 1
	s_nop 0
	v_lshlrev_b32_e32 v20, 16, v83
	v_and_b32_e32 v21, 0xffff0000, v83
	v_mul_f32_e32 v7, 0xbfb8aa3b, v18
	v_mul_f32_e32 v24, 0xbfb8aa3b, v19
	v_lshlrev_b32_e32 v22, 16, v84
	v_and_b32_e32 v23, 0xffff0000, v84
	v_mul_f32_e32 v25, 0xbfb8aa3b, v20
	v_mul_f32_e32 v26, 0xbfb8aa3b, v21
	v_exp_f32_e32 v7, v7
	v_exp_f32_e32 v24, v24
	v_mul_f32_e32 v27, 0xbfb8aa3b, v22
	v_mul_f32_e32 v28, 0xbfb8aa3b, v23
	v_exp_f32_e32 v25, v25
	v_exp_f32_e32 v26, v26
	v_exp_f32_e32 v27, v27
	v_exp_f32_e32 v28, v28
	v_add_f32_e32 v7, 1.0, v7
	v_add_f32_e32 v29, 1.0, v24
	v_add_f32_e32 v30, 1.0, v25
	v_add_f32_e32 v31, 1.0, v26
	v_rcp_f32_e32 v24, v7
	v_rcp_f32_e32 v25, v29
	v_add_f32_e32 v32, 1.0, v27
	v_add_f32_e32 v33, 1.0, v28
	v_rcp_f32_e32 v26, v30
	v_rcp_f32_e32 v27, v31
	s_waitcnt lgkmcnt(0)
	v_lshlrev_b32_e32 v30, 16, v0
	v_and_b32_e32 v31, 0xffff0000, v0
	v_rcp_f32_e32 v28, v32
	v_rcp_f32_e32 v29, v33
	v_lshlrev_b32_e32 v0, 16, v1
	v_and_b32_e32 v1, 0xffff0000, v1
	v_lshlrev_b32_e32 v32, 16, v2
	v_and_b32_e32 v33, 0xffff0000, v2
	v_pk_mul_f32 v[8:9], v[56:57], v[30:31]
	v_pk_mul_f32 v[0:1], v[58:59], v[0:1]
	v_pk_mul_f32 v[8:9], v[8:9], v[18:19]
	v_pk_mul_f32 v[10:11], v[60:61], v[32:33]
	v_pk_mul_f32 v[0:1], v[0:1], v[20:21]
	v_pk_mul_f32 v[8:9], v[24:25], v[8:9]
	v_pk_mul_f32 v[10:11], v[10:11], v[22:23]
	v_pk_mul_f32 v[12:13], v[26:27], v[0:1]
	v_cvt_pk_bf16_f32 v0, v8, v9
	v_lshlrev_b32_e32 v8, 16, v85
	v_pk_mul_f32 v[10:11], v[28:29], v[10:11]
	v_mul_f32_e32 v7, 0xbfb8aa3b, v8
	v_and_b32_e32 v9, 0xffff0000, v85
	v_cvt_pk_bf16_f32 v2, v10, v11
	v_exp_f32_e32 v7, v7
	v_mul_f32_e32 v10, 0xbfb8aa3b, v9
	v_exp_f32_e32 v11, v10
	v_cvt_pk_bf16_f32 v1, v12, v13
	v_add_f32_e32 v7, 1.0, v7
	v_rcp_f32_e32 v10, v7
	v_add_f32_e32 v7, 1.0, v11
	v_rcp_f32_e32 v11, v7
	v_lshlrev_b32_e32 v12, 16, v3
	v_and_b32_e32 v13, 0xffff0000, v3
	v_pk_mul_f32 v[12:13], v[62:63], v[12:13]
	v_and_b32_e32 v21, 0xffff0000, v78
	v_pk_mul_f32 v[8:9], v[12:13], v[8:9]
	v_lshlrev_b32_e32 v22, 16, v79
	v_pk_mul_f32 v[8:9], v[10:11], v[8:9]
	v_and_b32_e32 v23, 0xffff0000, v79
	v_cvt_pk_bf16_f32 v3, v8, v9
	global_store_dwordx4 v[16:17], v[0:3], off offset:128
	s_nop 1
	s_nop 0
	v_lshlrev_b32_e32 v24, 16, v80
	v_mul_f32_e32 v12, 0xbfb8aa3b, v21
	v_mul_f32_e32 v13, 0xbfb8aa3b, v22
	v_mul_f32_e32 v14, 0xbfb8aa3b, v23
	v_mul_f32_e32 v15, 0xbfb8aa3b, v24
	v_exp_f32_e32 v12, v12
	v_exp_f32_e32 v13, v13
	v_exp_f32_e32 v14, v14
	v_exp_f32_e32 v15, v15
	v_lshlrev_b32_e32 v20, 16, v78
	v_and_b32_e32 v25, 0xffff0000, v80
	v_lshlrev_b32_e32 v26, 16, v81
	v_and_b32_e32 v27, 0xffff0000, v81
	v_mul_f32_e32 v7, 0xbfb8aa3b, v20
	v_mul_f32_e32 v16, 0xbfb8aa3b, v25
	v_mul_f32_e32 v17, 0xbfb8aa3b, v26
	v_mul_f32_e32 v18, 0xbfb8aa3b, v27
	v_exp_f32_e32 v7, v7
	v_exp_f32_e32 v16, v16
	v_exp_f32_e32 v17, v17
	v_exp_f32_e32 v18, v18
	v_add_f32_e32 v12, 1.0, v12
	v_add_f32_e32 v13, 1.0, v13
	v_add_f32_e32 v14, 1.0, v14
	v_add_f32_e32 v15, 1.0, v15
	v_rcp_f32_e32 v29, v12
	v_rcp_f32_e32 v30, v13
	v_rcp_f32_e32 v31, v14
	v_rcp_f32_e32 v32, v15
	ds_read_b128 v[12:15], v6 offset:4352
	v_add_f32_e32 v7, 1.0, v7
	v_add_f32_e32 v16, 1.0, v16
	v_add_f32_e32 v17, 1.0, v17
	v_add_f32_e32 v18, 1.0, v18
	v_rcp_f32_e32 v28, v7
	v_rcp_f32_e32 v33, v16
	v_rcp_f32_e32 v34, v17
	v_rcp_f32_e32 v35, v18
	ds_read_b128 v[16:19], v6 offset:4480
	s_waitcnt lgkmcnt(1)
; #define GAS __attribute__((address_space(1)))
; #define LAS __attribute__((address_space(3)))
; __device__ __forceinline__ unsigned pk2(float lo, float hi) { const f32x2_t v = {lo, hi}; const bf16x2_t b = __builtin_convertvector(v, bf16x2_t); return __builtin_bit_cast(unsigned, b); }
; __device__ __forceinline__ float bflo(unsigned w) { return __uint_as_float(w << 16); }
; __device__ __forceinline__ float bfhi(unsigned w) { return __uint_as_float(w & 0xffff0000u); }
; __device__ __forceinline__ float sigmoidf_(float x) { return __builtin_amdgcn_rcpf(1.f + __expf(-x)); }
; template <int DK> __device__ __forceinline__ void scan_out_wave(const ScanBufs<DK>& S, int g, int h, const bf16* P, int gcol, const float* gain, bf16* Y, LAS unsigned char* W, int lane) {
;     ...
;         { char* Yu = (char*)(Y + rowt * 1024 + h * 128); const unsigned oy = (unsigned)((tl * 1024 + seg * 8) * 2);
; #pragma unroll
;           for (int j = 0; j < 8; ++j) { const int rr = 8 * (j >> 1), hf = j & 1; const v4u ow = *(const LAS v4u*)(st + (tl + rr) * P3_STP + hf * 128 + seg * 16); const v4u gw = A0.x[j];
;               const float* gn = gain + hf * 64 + seg * 8; const f32x4 n0 = *(const GAS f32x4*)gn, n1 = *(const GAS f32x4*)(gn + 4); v4u y;
; #pragma unroll
;               for (int c = 0; c < 4; ++c) { const float z0 = bflo(gw[c]), z1 = bfhi(gw[c]); const float na = c < 2 ? n0[2 * c] : n1[2 * c - 4], nb = c < 2 ? n0[2 * c + 1] : n1[2 * c - 3];
;                   y[c] = pk2(bflo(ow[c]) * na * z0 * sigmoidf_(z0), bfhi(ow[c]) * nb * z1 * sigmoidf_(z1)); }
;               *(GAS v4u*)(Yu + oy + ((size_t)rr * 1024 + hf * 64) * 2) = y; } }
	v_lshlrev_b32_e32 v36, 16, v12
	v_and_b32_e32 v37, 0xffff0000, v12
	v_lshlrev_b32_e32 v12, 16, v13
	v_and_b32_e32 v13, 0xffff0000, v13
	v_lshlrev_b32_e32 v38, 16, v14
	v_and_b32_e32 v39, 0xffff0000, v14
	v_lshlrev_b32_e32 v14, 16, v15
	v_and_b32_e32 v15, 0xffff0000, v15
	v_pk_mul_f32 v[0:1], v[48:49], v[36:37]
	v_pk_mul_f32 v[2:3], v[50:51], v[12:13]
	v_pk_mul_f32 v[8:9], v[52:53], v[38:39]
	v_pk_mul_f32 v[10:11], v[54:55], v[14:15]
	v_pk_mul_f32 v[0:1], v[0:1], v[20:21]
	v_pk_mul_f32 v[2:3], v[2:3], v[22:23]
	v_pk_mul_f32 v[8:9], v[8:9], v[24:25]
	v_pk_mul_f32 v[10:11], v[10:11], v[26:27]
	v_pk_mul_f32 v[0:1], v[28:29], v[0:1]
	v_pk_mul_f32 v[2:3], v[30:31], v[2:3]
	v_pk_mul_f32 v[8:9], v[32:33], v[8:9]
	v_pk_mul_f32 v[10:11], v[34:35], v[10:11]
	v_add_co_u32_e32 v12, vcc, s0, v4
	v_cvt_pk_bf16_f32 v0, v0, v1
	v_cvt_pk_bf16_f32 v1, v2, v3
	v_cvt_pk_bf16_f32 v2, v8, v9
	v_cvt_pk_bf16_f32 v3, v10, v11
	v_addc_co_u32_e32 v13, vcc, 0, v5, vcc
	global_store_dwordx4 v[12:13], v[0:3], off
	s_nop 1
	s_nop 0
	v_lshlrev_b32_e32 v14, 16, v74
	v_and_b32_e32 v15, 0xffff0000, v74
	v_lshlrev_b32_e32 v20, 16, v75
	v_and_b32_e32 v21, 0xffff0000, v75
	v_lshlrev_b32_e32 v22, 16, v76
	v_and_b32_e32 v23, 0xffff0000, v76
	v_lshlrev_b32_e32 v24, 16, v77
	v_and_b32_e32 v25, 0xffff0000, v77
	v_mul_f32_e32 v7, 0xbfb8aa3b, v14
	v_mul_f32_e32 v26, 0xbfb8aa3b, v15
	v_mul_f32_e32 v27, 0xbfb8aa3b, v20
	v_mul_f32_e32 v28, 0xbfb8aa3b, v21
	v_mul_f32_e32 v29, 0xbfb8aa3b, v22
	v_mul_f32_e32 v30, 0xbfb8aa3b, v23
	v_mul_f32_e32 v31, 0xbfb8aa3b, v24
	v_mul_f32_e32 v32, 0xbfb8aa3b, v25
	v_exp_f32_e32 v7, v7
	v_exp_f32_e32 v26, v26
	v_exp_f32_e32 v27, v27
	v_exp_f32_e32 v28, v28
	v_exp_f32_e32 v29, v29
	v_exp_f32_e32 v30, v30
	v_exp_f32_e32 v31, v31
	v_exp_f32_e32 v32, v32
	v_add_f32_e32 v7, 1.0, v7
	v_add_f32_e32 v33, 1.0, v26
	v_add_f32_e32 v34, 1.0, v27
	v_add_f32_e32 v35, 1.0, v28
	v_add_f32_e32 v36, 1.0, v29
	v_add_f32_e32 v37, 1.0, v30
	v_add_f32_e32 v38, 1.0, v31
	v_add_f32_e32 v39, 1.0, v32
	v_rcp_f32_e32 v26, v7
	v_rcp_f32_e32 v27, v33
	v_rcp_f32_e32 v28, v34
	v_rcp_f32_e32 v29, v35
	v_rcp_f32_e32 v30, v36
	v_rcp_f32_e32 v31, v37
	v_rcp_f32_e32 v32, v38
	v_rcp_f32_e32 v33, v39
	s_waitcnt lgkmcnt(0)
	v_lshlrev_b32_e32 v34, 16, v16
	v_and_b32_e32 v35, 0xffff0000, v16
	v_lshlrev_b32_e32 v16, 16, v17
	v_and_b32_e32 v17, 0xffff0000, v17
	v_lshlrev_b32_e32 v36, 16, v18
	v_and_b32_e32 v37, 0xffff0000, v18
	v_lshlrev_b32_e32 v18, 16, v19
	v_and_b32_e32 v19, 0xffff0000, v19
	v_pk_mul_f32 v[0:1], v[56:57], v[34:35]
	v_pk_mul_f32 v[2:3], v[58:59], v[16:17]
	v_pk_mul_f32 v[8:9], v[60:61], v[36:37]
	v_pk_mul_f32 v[10:11], v[62:63], v[18:19]
	v_pk_mul_f32 v[0:1], v[0:1], v[14:15]
	v_pk_mul_f32 v[2:3], v[2:3], v[20:21]
	v_pk_mul_f32 v[8:9], v[8:9], v[22:23]
	v_pk_mul_f32 v[10:11], v[10:11], v[24:25]
	v_pk_mul_f32 v[0:1], v[26:27], v[0:1]
	v_pk_mul_f32 v[2:3], v[28:29], v[2:3]
	v_pk_mul_f32 v[8:9], v[30:31], v[8:9]
	v_pk_mul_f32 v[10:11], v[32:33], v[10:11]
	v_cvt_pk_bf16_f32 v0, v0, v1
	v_cvt_pk_bf16_f32 v1, v2, v3
	v_cvt_pk_bf16_f32 v2, v8, v9
	v_cvt_pk_bf16_f32 v3, v10, v11
	global_store_dwordx4 v[12:13], v[0:3], off offset:128
	s_nop 1
	s_nop 0
	v_lshlrev_b32_e32 v16, 16, v70
	v_and_b32_e32 v17, 0xffff0000, v70
	v_lshlrev_b32_e32 v18, 16, v71
	v_and_b32_e32 v19, 0xffff0000, v71
	v_lshlrev_b32_e32 v20, 16, v72
	v_and_b32_e32 v21, 0xffff0000, v72
	v_lshlrev_b32_e32 v22, 16, v73
	v_mul_f32_e32 v7, 0xbfb8aa3b, v16
	v_mul_f32_e32 v12, 0xbfb8aa3b, v17
	v_mul_f32_e32 v13, 0xbfb8aa3b, v18
	v_mul_f32_e32 v14, 0xbfb8aa3b, v19
	v_mul_f32_e32 v15, 0xbfb8aa3b, v20
	v_add_co_u32_e32 v24, vcc, s2, v4
	v_mul_f32_e32 v26, 0xbfb8aa3b, v21
	v_mul_f32_e32 v27, 0xbfb8aa3b, v22
	v_addc_co_u32_e32 v25, vcc, 0, v5, vcc
	v_exp_f32_e32 v4, v7
	v_exp_f32_e32 v5, v12
	v_exp_f32_e32 v7, v13
	v_exp_f32_e32 v12, v14
	v_exp_f32_e32 v13, v15
	v_exp_f32_e32 v14, v26
	v_exp_f32_e32 v15, v27
	v_and_b32_e32 v23, 0xffff0000, v73
	v_mul_f32_e32 v28, 0xbfb8aa3b, v23
	v_exp_f32_e32 v26, v28
	v_add_f32_e32 v12, 1.0, v12
	v_add_f32_e32 v13, 1.0, v13
	v_add_f32_e32 v31, 1.0, v14
	v_add_f32_e32 v32, 1.0, v15
	v_rcp_f32_e32 v29, v12
	v_rcp_f32_e32 v30, v13
	ds_read_b128 v[12:15], v6 offset:6528
	v_add_f32_e32 v4, 1.0, v4
	v_add_f32_e32 v5, 1.0, v5
	v_add_f32_e32 v7, 1.0, v7
	v_add_f32_e32 v33, 1.0, v26
	v_rcp_f32_e32 v26, v4
	v_rcp_f32_e32 v27, v5
	v_rcp_f32_e32 v28, v7
	v_rcp_f32_e32 v31, v31
	v_rcp_f32_e32 v32, v32
	v_rcp_f32_e32 v33, v33
	s_waitcnt lgkmcnt(0)
; #define GAS __attribute__((address_space(1)))
; #define LAS __attribute__((address_space(3)))
; #define LDS_WAIT() asm volatile("s_waitcnt lgkmcnt(0)" ::: "memory")
; __device__ __forceinline__ unsigned pk2(float lo, float hi) { const f32x2_t v = {lo, hi}; const bf16x2_t b = __builtin_convertvector(v, bf16x2_t); return __builtin_bit_cast(unsigned, b); }
; __device__ __forceinline__ float bflo(unsigned w) { return __uint_as_float(w << 16); }
; __device__ __forceinline__ float bfhi(unsigned w) { return __uint_as_float(w & 0xffff0000u); }
; __device__ __forceinline__ float sigmoidf_(float x) { return __builtin_amdgcn_rcpf(1.f + __expf(-x)); }
; template <int DK> __device__ __forceinline__ void scan_out_wave(const ScanBufs<DK>& S, int g, int h, const bf16* P, int gcol, const float* gain, bf16* Y, LAS unsigned char* W, int lane) {
;     ...
;         { char* Yu = (char*)(Y + rowt * 1024 + h * 128); const unsigned oy = (unsigned)((tl * 1024 + seg * 8) * 2);
; #pragma unroll
;           for (int j = 0; j < 8; ++j) { const int rr = 8 * (j >> 1), hf = j & 1; const v4u ow = *(const LAS v4u*)(st + (tl + rr) * P3_STP + hf * 128 + seg * 16); const v4u gw = A0.x[j];
;               const float* gn = gain + hf * 64 + seg * 8; const f32x4 n0 = *(const GAS f32x4*)gn, n1 = *(const GAS f32x4*)(gn + 4); v4u y;
; #pragma unroll
;               for (int c = 0; c < 4; ++c) { const float z0 = bflo(gw[c]), z1 = bfhi(gw[c]); const float na = c < 2 ? n0[2 * c] : n1[2 * c - 4], nb = c < 2 ? n0[2 * c + 1] : n1[2 * c - 3];
;                   y[c] = pk2(bflo(ow[c]) * na * z0 * sigmoidf_(z0), bfhi(ow[c]) * nb * z1 * sigmoidf_(z1)); }
;               *(GAS v4u*)(Yu + oy + ((size_t)rr * 1024 + hf * 64) * 2) = y; } }
;         LDS_WAIT();
;     }
	v_lshlrev_b32_e32 v34, 16, v12
	v_and_b32_e32 v35, 0xffff0000, v12
	v_lshlrev_b32_e32 v12, 16, v13
	v_and_b32_e32 v13, 0xffff0000, v13
	v_lshlrev_b32_e32 v36, 16, v14
	v_and_b32_e32 v37, 0xffff0000, v14
	v_lshlrev_b32_e32 v14, 16, v15
	v_and_b32_e32 v15, 0xffff0000, v15
	ds_read_b128 v[4:7], v6 offset:6656
	s_andn2_b64 vcc, exec, s[14:15]
	s_mov_b64 s[14:15], 0
	v_pk_mul_f32 v[0:1], v[48:49], v[34:35]
	v_pk_mul_f32 v[2:3], v[50:51], v[12:13]
	v_pk_mul_f32 v[8:9], v[52:53], v[36:37]
	v_pk_mul_f32 v[10:11], v[54:55], v[14:15]
	v_pk_mul_f32 v[0:1], v[0:1], v[16:17]
	v_pk_mul_f32 v[2:3], v[2:3], v[18:19]
	v_pk_mul_f32 v[8:9], v[8:9], v[20:21]
	v_pk_mul_f32 v[10:11], v[10:11], v[22:23]
	v_pk_mul_f32 v[0:1], v[26:27], v[0:1]
	v_pk_mul_f32 v[2:3], v[28:29], v[2:3]
	v_pk_mul_f32 v[8:9], v[30:31], v[8:9]
	v_pk_mul_f32 v[10:11], v[32:33], v[10:11]
	v_cvt_pk_bf16_f32 v0, v0, v1
	v_cvt_pk_bf16_f32 v1, v2, v3
	v_cvt_pk_bf16_f32 v2, v8, v9
	v_cvt_pk_bf16_f32 v3, v10, v11
	global_store_dwordx4 v[24:25], v[0:3], off
	s_nop 1
	s_nop 0
	v_lshlrev_b32_e32 v12, 16, v66
	v_and_b32_e32 v13, 0xffff0000, v66
	v_lshlrev_b32_e32 v14, 16, v67
	v_and_b32_e32 v15, 0xffff0000, v67
	v_lshlrev_b32_e32 v16, 16, v68
	v_and_b32_e32 v17, 0xffff0000, v68
	v_lshlrev_b32_e32 v18, 16, v69
	v_and_b32_e32 v19, 0xffff0000, v69
	v_mul_f32_e32 v20, 0xbfb8aa3b, v12
	v_mul_f32_e32 v21, 0xbfb8aa3b, v13
	v_mul_f32_e32 v22, 0xbfb8aa3b, v14
	v_mul_f32_e32 v23, 0xbfb8aa3b, v15
	v_mul_f32_e32 v26, 0xbfb8aa3b, v16
	v_mul_f32_e32 v27, 0xbfb8aa3b, v17
	v_mul_f32_e32 v28, 0xbfb8aa3b, v18
	v_mul_f32_e32 v29, 0xbfb8aa3b, v19
	v_exp_f32_e32 v20, v20
	v_exp_f32_e32 v21, v21
	v_exp_f32_e32 v22, v22
	v_exp_f32_e32 v23, v23
	v_exp_f32_e32 v26, v26
	v_exp_f32_e32 v27, v27
	v_exp_f32_e32 v28, v28
	v_exp_f32_e32 v29, v29
	v_add_f32_e32 v20, 1.0, v20
	v_add_f32_e32 v21, 1.0, v21
	v_add_f32_e32 v22, 1.0, v22
	v_add_f32_e32 v23, 1.0, v23
	v_add_f32_e32 v26, 1.0, v26
	v_add_f32_e32 v27, 1.0, v27
	v_add_f32_e32 v28, 1.0, v28
	v_add_f32_e32 v29, 1.0, v29
	v_rcp_f32_e32 v20, v20
	v_rcp_f32_e32 v21, v21
	v_rcp_f32_e32 v22, v22
	v_rcp_f32_e32 v23, v23
	v_rcp_f32_e32 v26, v26
	v_rcp_f32_e32 v27, v27
	v_rcp_f32_e32 v28, v28
	v_rcp_f32_e32 v29, v29
	s_waitcnt lgkmcnt(0)
	v_lshlrev_b32_e32 v30, 16, v4
	v_and_b32_e32 v31, 0xffff0000, v4
	v_lshlrev_b32_e32 v4, 16, v5
	v_and_b32_e32 v5, 0xffff0000, v5
	v_lshlrev_b32_e32 v32, 16, v6
	v_and_b32_e32 v33, 0xffff0000, v6
	v_lshlrev_b32_e32 v6, 16, v7
	v_and_b32_e32 v7, 0xffff0000, v7
	v_pk_mul_f32 v[0:1], v[56:57], v[30:31]
	v_pk_mul_f32 v[2:3], v[58:59], v[4:5]
	v_pk_mul_f32 v[4:5], v[60:61], v[32:33]
	v_pk_mul_f32 v[6:7], v[62:63], v[6:7]
	v_pk_mul_f32 v[0:1], v[0:1], v[12:13]
	v_pk_mul_f32 v[2:3], v[2:3], v[14:15]
	v_pk_mul_f32 v[4:5], v[4:5], v[16:17]
	v_pk_mul_f32 v[6:7], v[6:7], v[18:19]
	v_pk_mul_f32 v[0:1], v[20:21], v[0:1]
	v_pk_mul_f32 v[2:3], v[22:23], v[2:3]
	v_pk_mul_f32 v[4:5], v[26:27], v[4:5]
	v_pk_mul_f32 v[6:7], v[28:29], v[6:7]
	v_cvt_pk_bf16_f32 v0, v0, v1
	v_cvt_pk_bf16_f32 v1, v2, v3
	v_cvt_pk_bf16_f32 v2, v4, v5
	v_cvt_pk_bf16_f32 v3, v6, v7
	global_store_dwordx4 v[24:25], v[0:3], off offset:128
	s_nop 1
	s_waitcnt lgkmcnt(0)
	s_cbranch_vccz .LBB0_1098
	s_branch .LBB0_1084
